# code placement: 47 branch-target labels in the attention phases that are never reached by fall-through aligned to 64 bytes
# baseline (speedup 1.0000x reference)
.LBB0_228:
	s_or_b64 exec, exec, s[6:7]
	v_readlane_b32 s0, v254, 24
	s_mov_b64 s[6:7], s[40:41]
	v_mov_b32_e32 v122, v146
	v_readlane_b32 s1, v254, 25
	s_waitcnt lgkmcnt(0)
	s_barrier
	s_andn2_b64 vcc, exec, s[0:1]
	v_readfirstlane_b32 s0, v122
	s_cbranch_vccnz .LBB0_295
	s_load_dwordx2 s[12:13], s[6:7], 0x98
	v_readlane_b32 s4, v255, 16
	s_lshl_b32 s16, s4, 4
	s_ashr_i32 s0, s0, 6
	v_ashrrev_i32_e32 v2, 5, v122
	s_waitcnt lgkmcnt(0)
	s_add_u32 s1, s12, 0x5f00000
	s_addc_u32 s2, s13, 0
	s_add_u32 s20, s12, 0x5d40000
	s_addc_u32 s21, s13, 0
	s_add_u32 s8, s12, 0xff00000
	s_addc_u32 s9, s13, 0
	v_add_u32_e32 v211, 16, v2
	v_bfe_u32 v2, v122, 3, 3
	s_lshl_b32 s33, s0, 3
	v_bitop3_b32 v5, v2, v122, 7 bitop3:0x78
	v_or_b32_e32 v2, s33, v2
	v_bfe_u32 v0, v122, 4, 2
	v_ashrrev_i32_e32 v3, 31, v2
	v_and_b32_e32 v4, 7, v122
	v_lshlrev_b64 v[126:127], 12, v[2:3]
	v_bitop3_b32 v2, v0, v122, 7 bitop3:0x78
	v_lshlrev_b32_e32 v213, 4, v2
	v_bitop3_b32 v2, v0, v4, 4 bitop3:0x36
	v_lshlrev_b32_e32 v214, 4, v2
	v_lshlrev_b32_e32 v216, 2, v0
	v_bfe_u32 v2, v122, 2, 2
	v_or_b32_e32 v2, v216, v2
	v_bfe_u32 v3, v122, 1, 1
	v_bitop3_b32 v4, v2, v3, 7 bitop3:0x6c
	s_movk_i32 s4, 0x100
	v_lshlrev_b32_e32 v220, 4, v4
	v_or_b32_e32 v4, 2, v3
	v_cmp_gt_i32_e64 s[38:39], s4, v122
	s_lshl_b32 s4, s0, 9
	v_bitop3_b32 v4, v2, v4, 7 bitop3:0x6c
	s_add_i32 s15, s4, 0
	v_lshlrev_b32_e32 v221, 4, v4
	v_or_b32_e32 v4, 4, v3
	v_or_b32_e32 v3, 6, v3
	s_mul_i32 s4, s0, 0xf00
	v_lshlrev_b32_e32 v217, 7, v2
	v_bitop3_b32 v4, v2, v4, 7 bitop3:0x6c
	v_bitop3_b32 v2, v2, v3, 7 bitop3:0x6c
	s_add_i32 s4, s15, s4
	v_and_b32_e32 v210, 15, v122
	v_lshlrev_b32_e32 v223, 4, v2
	v_mov_b32_e32 v2, s4
	s_movk_i32 s4, 0x110
	v_mad_u32_u24 v225, v210, s4, v2
	s_and_b32 s4, s0, 3
	s_lshl_b32 s37, s4, 6
	s_lshl_b32 s4, s4, 12
	s_lshl_b32 s14, s0, 10
	s_andn2_b32 s33, s33, 31
	s_add_i32 s78, s4, 0
	v_lshl_or_b32 v2, s0, 5, v210
	s_movk_i32 s4, 0x880
	v_ashrrev_i32_e32 v3, 31, v2
	s_cmp_lt_i32 s0, 4
	v_readlane_b32 s5, v255, 17
	v_lshl_or_b32 v126, v5, 3, v126
	v_lshlrev_b32_e32 v222, 4, v4
	v_cmp_gt_i32_e64 s[40:41], s4, v122
	v_lshlrev_b64 v[4:5], 12, v[2:3]
	s_cselect_b64 s[10:11], -1, 0
	s_lshl_b32 s4, s0, 4
	v_and_b32_e32 v128, 48, v122
	v_lshl_add_u64 v[4:5], s[12:13], 0, v[4:5]
	v_mov_b32_e32 v129, v1
	s_ashr_i32 s5, s4, 31
	v_lshl_add_u64 v[130:131], v[4:5], 0, v[128:129]
	v_or_b32_e32 v4, s4, v210
	s_lshl_b64 s[4:5], s[4:5], 1
	v_lshlrev_b32_e32 v124, 3, v0
	v_lshlrev_b32_e32 v226, 6, v0
	v_mul_u32_u24_e32 v8, 0x840, v0
	v_mul_u32_u24_e32 v0, 0x210, v210
	v_ashrrev_i32_e32 v5, 31, v4
	s_add_u32 s4, s12, s4
	v_add3_u32 v229, 0, v0, v128
	v_lshlrev_b64 v[4:5], 9, v[4:5]
	s_addc_u32 s5, s13, s5
	v_lshlrev_b32_e32 v0, 1, v210
	v_lshl_add_u64 v[4:5], s[12:13], 0, v[4:5]
	v_lshl_add_u64 v[134:135], s[4:5], 0, v[0:1]
	v_lshlrev_b32_e32 v0, 1, v128
	v_lshlrev_b32_e32 v6, 4, v122
	v_lshl_add_u64 v[132:133], v[4:5], 0, v[128:129]
	v_lshl_add_u64 v[4:5], s[12:13], 0, v[0:1]
	s_mov_b64 s[4:5], 0x11f00000
	v_lshlrev_b32_e32 v218, 3, v122
	v_ashrrev_i32_e32 v123, 31, v122
	v_lshl_add_u32 v7, v2, 1, 0
	v_lshl_add_u64 v[136:137], v[4:5], 0, s[4:5]
	v_and_b32_e32 v0, 0x1f0, v6
	v_lshl_add_u64 v[2:3], v[2:3], 2, s[12:13]
	s_mov_b64 s[4:5], 0x5d30000
	v_add_u32_e32 v212, 0, v6
	v_lshlrev_b32_e32 v215, 7, v210
	v_and_b32_e32 v219, 8, v218
	v_add_u32_e32 v224, s15, v128
	v_add_u32_e32 v227, s78, v128
	v_lshlrev_b32_e32 v228, 4, v210
	s_add_i32 s79, s14, 0
	v_or_b32_e32 v129, 64, v128
	v_lshl_add_u64 v[138:139], s[20:21], 0, v[0:1]
	v_lshl_add_u64 v[140:141], v[122:123], 4, s[20:21]
	v_lshl_add_u64 v[142:143], v[2:3], 0, s[4:5]
	v_lshl_add_u32 v230, v210, 11, 0
	s_lshl_b64 s[12:13], s[16:17], 2
	v_add_u32_e32 v231, v7, v8
	v_readlane_b32 s80, v253, 6
	s_branch .LBB0_233
	.p2alignl 6, 3212836864

.LBB0_253:
	s_mov_b32 s44, 0
	s_mov_b64 s[76:77], -1
	s_branch .LBB0_255
	.p2alignl 6, 3212836864

.LBB0_255:
	s_or_b32 s16, s44, s23
	s_cmp_gt_i32 s16, s18
	s_cbranch_scc1 .LBB0_254
	s_lshl_b32 s16, s16, 14
	s_and_b32 s16, s16, 0xc000
	s_add_i32 s16, s16, 0
	s_waitcnt lgkmcnt(0)
	v_add_u32_e32 v50, s16, v215
	v_and_b32_e32 v51, 64, v147
	v_add_u32_e32 v232, v50, v213
	v_add_u32_e32 v82, 64, v51
	v_add_u32_e32 v165, v50, v214
	ds_read_b128 v[70:73], v232 offset:32768
	ds_read_b128 v[74:77], v232 offset:34816
	ds_read_b128 v[78:81], v165 offset:32768
	ds_read_b128 v[66:69], v165 offset:34816
	ds_read_b128 v[62:65], v232 offset:36864
	ds_read_b128 v[54:57], v232 offset:38912
	ds_read_b128 v[58:61], v165 offset:36864
	ds_read_b128 v[50:53], v165 offset:38912
	s_add_i32 s42, s44, s71
	s_lshl_b32 s82, s42, 6
	s_or_b32 s42, s82, 63
	s_cmp_le_u32 s42, s5
	v_xor_b32_e32 v0, 16, v147
	s_cselect_b64 s[42:43], -1, 0
	s_cmp_gt_i32 s82, s19
	v_cmp_lt_i32_e32 vcc, v0, v82
	v_xor_b32_e32 v83, 32, v147
	s_cselect_b64 s[44:45], -1, 0
	v_cndmask_b32_e32 v0, v147, v0, vcc
	v_cmp_lt_i32_e32 vcc, v83, v82
	s_and_b64 s[42:43], s[42:43], s[44:45]
	v_lshlrev_b32_e32 v0, 2, v0
	v_cndmask_b32_e32 v82, v147, v83, vcc
	v_lshlrev_b32_e32 v149, 2, v82
	s_andn2_b64 vcc, exec, s[42:43]
	s_mov_b64 s[42:43], -1
	s_cbranch_vccz .Lsw_p1
	v_lshl_add_u32 v114, s82, 2, v145
	ds_read2_b32 v[82:83], v114 offset0:127 offset1:128
	ds_read2_b32 v[84:85], v114 offset0:129 offset1:130
	ds_read2_b32 v[86:87], v114 offset0:143 offset1:144
	ds_read2_b32 v[88:89], v114 offset0:145 offset1:146
	s_waitcnt lgkmcnt(4)
	v_mfma_f32_16x16x32_bf16 v[70:73], v[70:73], v[2:5], 0
	v_mfma_f32_16x16x32_bf16 v[74:77], v[74:77], v[2:5], 0
	v_mfma_f32_16x16x32_bf16 v[62:65], v[62:65], v[2:5], 0
	v_mfma_f32_16x16x32_bf16 v[54:57], v[54:57], v[2:5], 0
	ds_read2_b32 v[90:91], v114 offset0:159 offset1:160
	ds_read2_b32 v[92:93], v114 offset0:161 offset1:162
	ds_read2_b32 v[94:95], v114 offset0:175 offset1:176
	ds_read2_b32 v[96:97], v114 offset0:177 offset1:178
	v_mfma_f32_16x16x32_bf16 v[70:73], v[78:81], v[6:9], v[70:73]
	v_mfma_f32_16x16x32_bf16 v[74:77], v[66:69], v[6:9], v[74:77]
	v_mfma_f32_16x16x32_bf16 v[62:65], v[58:61], v[6:9], v[62:65]
	v_mfma_f32_16x16x32_bf16 v[54:57], v[50:53], v[6:9], v[54:57]
	s_waitcnt lgkmcnt(0)
	ds_read_b128 v[98:101], v232 offset:32768
	ds_read_b128 v[78:81], v165 offset:32768
	ds_read_b128 v[102:105], v232 offset:34816
	ds_read_b128 v[66:69], v165 offset:34816
	ds_read_b128 v[106:109], v232 offset:36864
	ds_read_b128 v[58:61], v165 offset:36864
	ds_read_b128 v[110:113], v232 offset:38912
	ds_read_b128 v[50:53], v165 offset:38912
	v_pk_fma_f32 v[70:71], v[70:71], s[36:37], v[82:83] op_sel_hi:[1,0,1]
	v_pk_fma_f32 v[72:73], v[72:73], s[36:37], v[84:85] op_sel_hi:[1,0,1]
	v_pk_fma_f32 v[74:75], v[74:75], s[36:37], v[86:87] op_sel_hi:[1,0,1]
	v_pk_fma_f32 v[76:77], v[76:77], s[36:37], v[88:89] op_sel_hi:[1,0,1]
	v_pk_fma_f32 v[62:63], v[62:63], s[36:37], v[90:91] op_sel_hi:[1,0,1]
	v_pk_fma_f32 v[64:65], v[64:65], s[36:37], v[92:93] op_sel_hi:[1,0,1]
	v_pk_fma_f32 v[54:55], v[54:55], s[36:37], v[94:95] op_sel_hi:[1,0,1]
	v_pk_fma_f32 v[56:57], v[56:57], s[36:37], v[96:97] op_sel_hi:[1,0,1]
	v_or_b32_e32 v117, s82, v216
	v_sub_u32_e32 v115, v144, v117
	v_subrev_u32_e32 v117, 0, v115
	v_cmp_gt_u32_e64 s[48:49], s26, v117
	v_subrev_u32_e32 v117, 1, v115
	v_cmp_gt_u32_e64 s[50:51], s26, v117
	v_subrev_u32_e32 v117, 2, v115
	v_cmp_gt_u32_e64 s[52:53], s26, v117
	v_subrev_u32_e32 v117, 3, v115
	v_cmp_gt_u32_e64 s[54:55], s26, v117
	v_subrev_u32_e32 v117, 16, v115
	v_cmp_gt_u32_e64 s[56:57], s26, v117
	v_subrev_u32_e32 v117, 17, v115
	v_cmp_gt_u32_e64 s[58:59], s26, v117
	v_subrev_u32_e32 v117, 18, v115
	v_cmp_gt_u32_e64 s[60:61], s26, v117
	v_subrev_u32_e32 v117, 19, v115
	v_cmp_gt_u32_e64 s[62:63], s26, v117
	v_cndmask_b32_e64 v70, v148, v70, s[48:49]
	v_cndmask_b32_e64 v71, v148, v71, s[50:51]
	v_cndmask_b32_e64 v72, v148, v72, s[52:53]
	v_cndmask_b32_e64 v73, v148, v73, s[54:55]
	v_cndmask_b32_e64 v74, v148, v74, s[56:57]
	v_cndmask_b32_e64 v75, v148, v75, s[58:59]
	v_cndmask_b32_e64 v76, v148, v76, s[60:61]
	v_cndmask_b32_e64 v77, v148, v77, s[62:63]
	v_subrev_u32_e32 v117, 32, v115
	v_cmp_gt_u32_e64 s[48:49], s26, v117
	v_subrev_u32_e32 v117, 33, v115
	v_cmp_gt_u32_e64 s[50:51], s26, v117
	v_subrev_u32_e32 v117, 34, v115
	v_cmp_gt_u32_e64 s[52:53], s26, v117
	v_subrev_u32_e32 v117, 35, v115
	v_cmp_gt_u32_e64 s[54:55], s26, v117
	v_subrev_u32_e32 v117, 48, v115
	v_cmp_gt_u32_e64 s[56:57], s26, v117
	v_subrev_u32_e32 v117, 49, v115
	v_cmp_gt_u32_e64 s[58:59], s26, v117
	v_subrev_u32_e32 v117, 50, v115
	v_cmp_gt_u32_e64 s[60:61], s26, v117
	v_subrev_u32_e32 v117, 51, v115
	v_cmp_gt_u32_e64 s[62:63], s26, v117
	v_cndmask_b32_e64 v62, v148, v62, s[48:49]
	v_cndmask_b32_e64 v63, v148, v63, s[50:51]
	v_cndmask_b32_e64 v64, v148, v64, s[52:53]
	v_cndmask_b32_e64 v65, v148, v65, s[54:55]
	v_cndmask_b32_e64 v54, v148, v54, s[56:57]
	v_cndmask_b32_e64 v55, v148, v55, s[58:59]
	v_cndmask_b32_e64 v56, v148, v56, s[60:61]
	v_cndmask_b32_e64 v57, v148, v57, s[62:63]
	v_max3_f32 v116, v70, v71, v72
	v_max3_f32 v116, v116, v73, v74
	v_max3_f32 v116, v116, v75, v76
	v_max3_f32 v116, v116, v77, v62
	v_max3_f32 v116, v116, v63, v64
	v_max3_f32 v116, v116, v65, v54
	v_max3_f32 v116, v116, v55, v56
	v_max3_f32 v116, v116, v57, s29
	v_mov_b32_e32 v117, v116
	s_nop 1
	v_permlane16_swap_b32_e32 v116, v117
	v_max_f32_e32 v116, v116, v117
	v_mov_b32_e32 v117, v116
	s_nop 1
	v_permlane32_swap_b32_e32 v116, v117
	v_max_f32_e32 v116, v116, v117
	v_max_f32_e32 v121, v166, v116
	v_sub_f32_e32 v118, v166, v121
	v_cmp_lt_f32_e32 vcc, s30, v121
	v_exp_f32_e32 v118, v118
	v_mov_b32_e32 v166, v121
	v_cndmask_b32_e32 v120, 0, v121, vcc
	v_pk_mul_f32 v[46:47], v[46:47], v[118:119] op_sel_hi:[1,0]
	v_pk_mul_f32 v[48:49], v[48:49], v[118:119] op_sel_hi:[1,0]
	v_pk_mul_f32 v[42:43], v[42:43], v[118:119] op_sel_hi:[1,0]
	v_pk_mul_f32 v[44:45], v[44:45], v[118:119] op_sel_hi:[1,0]
	v_pk_mul_f32 v[38:39], v[38:39], v[118:119] op_sel_hi:[1,0]
	v_pk_mul_f32 v[40:41], v[40:41], v[118:119] op_sel_hi:[1,0]
	v_pk_mul_f32 v[34:35], v[34:35], v[118:119] op_sel_hi:[1,0]
	v_pk_mul_f32 v[36:37], v[36:37], v[118:119] op_sel_hi:[1,0]
	v_pk_add_f32 v[70:71], v[70:71], v[120:121] op_sel_hi:[1,0] neg_lo:[0,1] neg_hi:[0,1]
	v_pk_add_f32 v[72:73], v[72:73], v[120:121] op_sel_hi:[1,0] neg_lo:[0,1] neg_hi:[0,1]
	v_pk_add_f32 v[74:75], v[74:75], v[120:121] op_sel_hi:[1,0] neg_lo:[0,1] neg_hi:[0,1]
	v_pk_add_f32 v[76:77], v[76:77], v[120:121] op_sel_hi:[1,0] neg_lo:[0,1] neg_hi:[0,1]
	v_pk_add_f32 v[62:63], v[62:63], v[120:121] op_sel_hi:[1,0] neg_lo:[0,1] neg_hi:[0,1]
	v_pk_add_f32 v[64:65], v[64:65], v[120:121] op_sel_hi:[1,0] neg_lo:[0,1] neg_hi:[0,1]
	v_pk_add_f32 v[54:55], v[54:55], v[120:121] op_sel_hi:[1,0] neg_lo:[0,1] neg_hi:[0,1]
	v_pk_add_f32 v[56:57], v[56:57], v[120:121] op_sel_hi:[1,0] neg_lo:[0,1] neg_hi:[0,1]
	v_exp_f32_e32 v70, v70
	v_exp_f32_e32 v71, v71
	v_exp_f32_e32 v72, v72
	v_exp_f32_e32 v73, v73
	v_exp_f32_e32 v74, v74
	v_exp_f32_e32 v75, v75
	v_exp_f32_e32 v76, v76
	v_exp_f32_e32 v77, v77
	v_exp_f32_e32 v62, v62
	v_exp_f32_e32 v63, v63
	v_exp_f32_e32 v64, v64
	v_exp_f32_e32 v65, v65
	v_exp_f32_e32 v54, v54
	v_exp_f32_e32 v55, v55
	v_exp_f32_e32 v56, v56
	v_exp_f32_e32 v57, v57
	s_nop 0
	v_pk_add_f32 v[82:83], v[70:71], v[72:73]
	v_pk_add_f32 v[84:85], v[74:75], v[76:77]
	v_pk_add_f32 v[86:87], v[62:63], v[64:65]
	v_pk_add_f32 v[88:89], v[54:55], v[56:57]
	v_pk_add_f32 v[82:83], v[82:83], v[84:85]
	v_pk_add_f32 v[86:87], v[86:87], v[88:89]
	s_nop 0
	v_pk_add_f32 v[82:83], v[82:83], v[86:87]
	s_nop 0
	v_add_f32_e32 v82, v82, v83
	v_fma_f32 v158, v158, v118, v82
	v_cvt_pk_bf16_f32 v77, v76, v77
	v_cvt_pk_bf16_f32 v76, v74, v75
	v_cvt_pk_bf16_f32 v75, v72, v73
	v_cvt_pk_bf16_f32 v74, v70, v71
	v_cvt_pk_bf16_f32 v62, v62, v63
	v_cvt_pk_bf16_f32 v63, v64, v65
	v_cvt_pk_bf16_f32 v64, v54, v55
	v_cvt_pk_bf16_f32 v65, v56, v57
	s_waitcnt lgkmcnt(0)
	ds_read2_b32 v[82:83], v114 offset0:111 offset1:112
	ds_read2_b32 v[84:85], v114 offset0:113 offset1:114
	ds_read2_b32 v[86:87], v114 offset0:127 offset1:128
	ds_read2_b32 v[88:89], v114 offset0:129 offset1:130
	ds_read2_b32 v[90:91], v114 offset0:143 offset1:144
	ds_read2_b32 v[92:93], v114 offset0:145 offset1:146
	ds_read2_b32 v[94:95], v114 offset0:159 offset1:160
	ds_read2_b32 v[96:97], v114 offset0:161 offset1:162
	v_mfma_f32_16x16x32_bf16 v[98:101], v[98:101], v[10:13], 0
	v_mfma_f32_16x16x32_bf16 v[102:105], v[102:105], v[10:13], 0
	v_mfma_f32_16x16x32_bf16 v[106:109], v[106:109], v[10:13], 0
	v_mfma_f32_16x16x32_bf16 v[110:113], v[110:113], v[10:13], 0
	v_mfma_f32_16x16x32_bf16 v[98:101], v[78:81], v[14:17], v[98:101]
	v_mfma_f32_16x16x32_bf16 v[102:105], v[66:69], v[14:17], v[102:105]
	v_mfma_f32_16x16x32_bf16 v[106:109], v[58:61], v[14:17], v[106:109]
	v_mfma_f32_16x16x32_bf16 v[110:113], v[50:53], v[14:17], v[110:113]
	s_waitcnt lgkmcnt(0)
	s_nop 6
	v_pk_fma_f32 v[98:99], v[98:99], s[36:37], v[82:83] op_sel_hi:[1,0,1]
	v_pk_fma_f32 v[100:101], v[100:101], s[36:37], v[84:85] op_sel_hi:[1,0,1]
	v_pk_fma_f32 v[102:103], v[102:103], s[36:37], v[86:87] op_sel_hi:[1,0,1]
	v_pk_fma_f32 v[104:105], v[104:105], s[36:37], v[88:89] op_sel_hi:[1,0,1]
	v_pk_fma_f32 v[106:107], v[106:107], s[36:37], v[90:91] op_sel_hi:[1,0,1]
	v_pk_fma_f32 v[108:109], v[108:109], s[36:37], v[92:93] op_sel_hi:[1,0,1]
	v_pk_fma_f32 v[110:111], v[110:111], s[36:37], v[94:95] op_sel_hi:[1,0,1]
	v_pk_fma_f32 v[112:113], v[112:113], s[36:37], v[96:97] op_sel_hi:[1,0,1]
	v_or_b32_e32 v117, s82, v216
	v_sub_u32_e32 v115, v144, v117
	v_add_u32_e32 v115, 16, v115
	v_subrev_u32_e32 v117, 0, v115
	v_cmp_gt_u32_e64 s[48:49], s26, v117
	v_subrev_u32_e32 v117, 1, v115
	v_cmp_gt_u32_e64 s[50:51], s26, v117
	v_subrev_u32_e32 v117, 2, v115
	v_cmp_gt_u32_e64 s[52:53], s26, v117
	v_subrev_u32_e32 v117, 3, v115
	v_cmp_gt_u32_e64 s[54:55], s26, v117
	v_subrev_u32_e32 v117, 16, v115
	v_cmp_gt_u32_e64 s[56:57], s26, v117
	v_subrev_u32_e32 v117, 17, v115
	v_cmp_gt_u32_e64 s[58:59], s26, v117
	v_subrev_u32_e32 v117, 18, v115
	v_cmp_gt_u32_e64 s[60:61], s26, v117
	v_subrev_u32_e32 v117, 19, v115
	v_cmp_gt_u32_e64 s[62:63], s26, v117
	v_cndmask_b32_e64 v98, v148, v98, s[48:49]
	v_cndmask_b32_e64 v99, v148, v99, s[50:51]
	v_cndmask_b32_e64 v100, v148, v100, s[52:53]
	v_cndmask_b32_e64 v101, v148, v101, s[54:55]
	v_cndmask_b32_e64 v102, v148, v102, s[56:57]
	v_cndmask_b32_e64 v103, v148, v103, s[58:59]
	v_cndmask_b32_e64 v104, v148, v104, s[60:61]
	v_cndmask_b32_e64 v105, v148, v105, s[62:63]
	v_subrev_u32_e32 v117, 32, v115
	v_cmp_gt_u32_e64 s[48:49], s26, v117
	v_subrev_u32_e32 v117, 33, v115
	v_cmp_gt_u32_e64 s[50:51], s26, v117
	v_subrev_u32_e32 v117, 34, v115
	v_cmp_gt_u32_e64 s[52:53], s26, v117
	v_subrev_u32_e32 v117, 35, v115
	v_cmp_gt_u32_e64 s[54:55], s26, v117
	v_subrev_u32_e32 v117, 48, v115
	v_cmp_gt_u32_e64 s[56:57], s26, v117
	v_subrev_u32_e32 v117, 49, v115
	v_cmp_gt_u32_e64 s[58:59], s26, v117
	v_subrev_u32_e32 v117, 50, v115
	v_cmp_gt_u32_e64 s[60:61], s26, v117
	v_subrev_u32_e32 v117, 51, v115
	v_cmp_gt_u32_e64 s[62:63], s26, v117
	v_cndmask_b32_e64 v106, v148, v106, s[48:49]
	v_cndmask_b32_e64 v107, v148, v107, s[50:51]
	v_cndmask_b32_e64 v108, v148, v108, s[52:53]
	v_cndmask_b32_e64 v109, v148, v109, s[54:55]
	v_cndmask_b32_e64 v110, v148, v110, s[56:57]
	v_cndmask_b32_e64 v111, v148, v111, s[58:59]
	v_cndmask_b32_e64 v112, v148, v112, s[60:61]
	v_cndmask_b32_e64 v113, v148, v113, s[62:63]
	v_max3_f32 v116, v98, v99, v100
	v_max3_f32 v116, v116, v101, v102
	v_max3_f32 v116, v116, v103, v104
	v_max3_f32 v116, v116, v105, v106
	v_max3_f32 v116, v116, v107, v108
	v_max3_f32 v116, v116, v109, v110
	v_max3_f32 v116, v116, v111, v112
	v_max3_f32 v116, v116, v113, s29
	v_mov_b32_e32 v117, v116
	s_nop 1
	v_permlane16_swap_b32_e32 v116, v117
	v_max_f32_e32 v116, v116, v117
	v_mov_b32_e32 v117, v116
	s_nop 1
	v_permlane32_swap_b32_e32 v116, v117
	v_max_f32_e32 v116, v116, v117
	v_max_f32_e32 v121, v167, v116
	v_sub_f32_e32 v118, v167, v121
	v_cmp_lt_f32_e32 vcc, s30, v121
	v_exp_f32_e32 v118, v118
	v_mov_b32_e32 v167, v121
	v_cndmask_b32_e32 v120, 0, v121, vcc
	v_pk_mul_f32 v[30:31], v[30:31], v[118:119] op_sel_hi:[1,0]
	v_pk_mul_f32 v[32:33], v[32:33], v[118:119] op_sel_hi:[1,0]
	v_pk_mul_f32 v[26:27], v[26:27], v[118:119] op_sel_hi:[1,0]
	v_pk_mul_f32 v[28:29], v[28:29], v[118:119] op_sel_hi:[1,0]
	v_pk_mul_f32 v[22:23], v[22:23], v[118:119] op_sel_hi:[1,0]
	v_pk_mul_f32 v[24:25], v[24:25], v[118:119] op_sel_hi:[1,0]
	v_pk_mul_f32 v[18:19], v[18:19], v[118:119] op_sel_hi:[1,0]
	v_pk_mul_f32 v[20:21], v[20:21], v[118:119] op_sel_hi:[1,0]
	v_pk_add_f32 v[98:99], v[98:99], v[120:121] op_sel_hi:[1,0] neg_lo:[0,1] neg_hi:[0,1]
	v_pk_add_f32 v[100:101], v[100:101], v[120:121] op_sel_hi:[1,0] neg_lo:[0,1] neg_hi:[0,1]
	v_pk_add_f32 v[102:103], v[102:103], v[120:121] op_sel_hi:[1,0] neg_lo:[0,1] neg_hi:[0,1]
	v_pk_add_f32 v[104:105], v[104:105], v[120:121] op_sel_hi:[1,0] neg_lo:[0,1] neg_hi:[0,1]
	v_pk_add_f32 v[106:107], v[106:107], v[120:121] op_sel_hi:[1,0] neg_lo:[0,1] neg_hi:[0,1]
	v_pk_add_f32 v[108:109], v[108:109], v[120:121] op_sel_hi:[1,0] neg_lo:[0,1] neg_hi:[0,1]
	v_pk_add_f32 v[110:111], v[110:111], v[120:121] op_sel_hi:[1,0] neg_lo:[0,1] neg_hi:[0,1]
	v_pk_add_f32 v[112:113], v[112:113], v[120:121] op_sel_hi:[1,0] neg_lo:[0,1] neg_hi:[0,1]
	v_exp_f32_e32 v98, v98
	v_exp_f32_e32 v99, v99
	v_exp_f32_e32 v100, v100
	v_exp_f32_e32 v101, v101
	v_exp_f32_e32 v102, v102
	v_exp_f32_e32 v103, v103
	v_exp_f32_e32 v104, v104
	v_exp_f32_e32 v105, v105
	v_exp_f32_e32 v106, v106
	v_exp_f32_e32 v107, v107
	v_exp_f32_e32 v108, v108
	v_exp_f32_e32 v109, v109
	v_exp_f32_e32 v110, v110
	v_exp_f32_e32 v111, v111
	v_exp_f32_e32 v112, v112
	v_exp_f32_e32 v113, v113
	s_nop 0
	v_pk_add_f32 v[82:83], v[98:99], v[100:101]
	v_pk_add_f32 v[84:85], v[102:103], v[104:105]
	v_pk_add_f32 v[86:87], v[106:107], v[108:109]
	v_pk_add_f32 v[88:89], v[110:111], v[112:113]
	v_pk_add_f32 v[82:83], v[82:83], v[84:85]
	v_pk_add_f32 v[86:87], v[86:87], v[88:89]
	s_nop 0
	v_pk_add_f32 v[82:83], v[82:83], v[86:87]
	s_nop 0
	v_add_f32_e32 v82, v82, v83
	v_fma_f32 v159, v159, v118, v82
	v_cvt_pk_bf16_f32 v105, v104, v105
	v_cvt_pk_bf16_f32 v104, v102, v103
	v_cvt_pk_bf16_f32 v103, v100, v101
	v_cvt_pk_bf16_f32 v102, v98, v99
	v_cvt_pk_bf16_f32 v106, v106, v107
	v_cvt_pk_bf16_f32 v107, v108, v109
	v_cvt_pk_bf16_f32 v108, v110, v111
	v_cvt_pk_bf16_f32 v109, v112, v113
	s_branch .Lsw_pv
	.p2alignl 6, 3212836864

.LBB0_261:
	s_andn2_b64 vcc, exec, s[74:75]
	s_cbranch_vccz .LBB0_264
	s_mov_b32 s23, s25
	s_branch .LBB0_249
	.p2alignl 6, 3212836864

.LBB0_285:
	s_mov_b32 s25, 0
	s_mov_b64 s[72:73], -1
	s_branch .LBB0_287
	.p2alignl 6, 3212836864

.LBB0_287:
	s_or_b32 s16, s25, s19
	s_cmp_gt_i32 s16, s14
	s_cbranch_scc1 .LBB0_286
	s_lshl_b32 s16, s16, 14
	s_and_b32 s16, s16, 0xc000
	s_add_i32 s16, s16, 0
	s_waitcnt lgkmcnt(0)
	v_add_u32_e32 v50, s16, v215
	v_and_b32_e32 v51, 64, v147
	v_add_u32_e32 v232, v50, v213
	v_add_u32_e32 v82, 64, v51
	v_add_u32_e32 v159, v50, v214
	ds_read_b128 v[78:81], v232 offset:32768
	ds_read_b128 v[70:73], v232 offset:34816
	ds_read_b128 v[74:77], v159 offset:32768
	ds_read_b128 v[66:69], v159 offset:34816
	ds_read_b128 v[62:65], v232 offset:36864
	ds_read_b128 v[54:57], v232 offset:38912
	ds_read_b128 v[58:61], v159 offset:36864
	ds_read_b128 v[50:53], v159 offset:38912
	s_add_i32 s25, s25, s23
	s_lshl_b32 s25, s25, 6
	s_or_b32 s42, s25, 63
	s_cmp_le_i32 s42, s4
	s_cselect_b64 s[42:43], -1, 0
	s_sub_i32 s44, s18, s25
	v_xor_b32_e32 v0, 16, v147
	s_cmpk_lt_i32 s44, 0x200
	v_cmp_lt_i32_e32 vcc, v0, v82
	v_xor_b32_e32 v83, 32, v147
	s_cselect_b64 s[44:45], -1, 0
	v_cndmask_b32_e32 v0, v147, v0, vcc
	v_cmp_lt_i32_e32 vcc, v83, v82
	s_and_b64 s[42:43], s[42:43], s[44:45]
	v_lshlrev_b32_e32 v0, 2, v0
	v_cndmask_b32_e32 v82, v147, v83, vcc
	v_lshlrev_b32_e32 v149, 2, v82
	s_andn2_b64 vcc, exec, s[42:43]
	s_mov_b64 s[42:43], -1
	s_cbranch_vccz .Lnw_p1
	v_lshl_add_u32 v114, s25, 2, v145
	v_add_u32_e32 v115, 0xffc, v114
	ds_read2_b32 v[82:83], v115 offset1:1
	ds_read2_b32 v[84:85], v115 offset0:2 offset1:3
	ds_read2_b32 v[86:87], v115 offset0:16 offset1:17
	ds_read2_b32 v[88:89], v115 offset0:18 offset1:19
	s_waitcnt lgkmcnt(4)
	v_mfma_f32_16x16x32_bf16 v[78:81], v[78:81], v[2:5], 0
	v_mfma_f32_16x16x32_bf16 v[70:73], v[70:73], v[2:5], 0
	v_mfma_f32_16x16x32_bf16 v[62:65], v[62:65], v[2:5], 0
	v_mfma_f32_16x16x32_bf16 v[54:57], v[54:57], v[2:5], 0
	ds_read2_b32 v[90:91], v115 offset0:32 offset1:33
	ds_read2_b32 v[92:93], v115 offset0:34 offset1:35
	ds_read2_b32 v[94:95], v115 offset0:48 offset1:49
	ds_read2_b32 v[96:97], v115 offset0:50 offset1:51
	v_mfma_f32_16x16x32_bf16 v[78:81], v[74:77], v[6:9], v[78:81]
	v_mfma_f32_16x16x32_bf16 v[70:73], v[66:69], v[6:9], v[70:73]
	v_mfma_f32_16x16x32_bf16 v[62:65], v[58:61], v[6:9], v[62:65]
	v_mfma_f32_16x16x32_bf16 v[54:57], v[50:53], v[6:9], v[54:57]
	s_waitcnt lgkmcnt(0)
	ds_read_b128 v[98:101], v232 offset:32768
	ds_read_b128 v[74:77], v159 offset:32768
	ds_read_b128 v[102:105], v232 offset:34816
	ds_read_b128 v[66:69], v159 offset:34816
	ds_read_b128 v[106:109], v232 offset:36864
	ds_read_b128 v[58:61], v159 offset:36864
	ds_read_b128 v[110:113], v232 offset:38912
	ds_read_b128 v[50:53], v159 offset:38912
	v_pk_fma_f32 v[78:79], v[78:79], s[36:37], v[82:83] op_sel_hi:[1,0,1]
	v_pk_fma_f32 v[80:81], v[80:81], s[36:37], v[84:85] op_sel_hi:[1,0,1]
	v_pk_fma_f32 v[70:71], v[70:71], s[36:37], v[86:87] op_sel_hi:[1,0,1]
	v_pk_fma_f32 v[72:73], v[72:73], s[36:37], v[88:89] op_sel_hi:[1,0,1]
	v_pk_fma_f32 v[62:63], v[62:63], s[36:37], v[90:91] op_sel_hi:[1,0,1]
	v_pk_fma_f32 v[64:65], v[64:65], s[36:37], v[92:93] op_sel_hi:[1,0,1]
	v_pk_fma_f32 v[54:55], v[54:55], s[36:37], v[94:95] op_sel_hi:[1,0,1]
	v_pk_fma_f32 v[56:57], v[56:57], s[36:37], v[96:97] op_sel_hi:[1,0,1]
	v_or_b32_e32 v117, s25, v216
	v_sub_u32_e32 v115, v144, v117
	v_subrev_u32_e32 v117, 0, v115
	v_cmp_gt_u32_e64 s[48:49], s3, v117
	v_subrev_u32_e32 v117, 1, v115
	v_cmp_gt_u32_e64 s[50:51], s3, v117
	v_subrev_u32_e32 v117, 2, v115
	v_cmp_gt_u32_e64 s[52:53], s3, v117
	v_subrev_u32_e32 v117, 3, v115
	v_cmp_gt_u32_e64 s[54:55], s3, v117
	v_subrev_u32_e32 v117, 16, v115
	v_cmp_gt_u32_e64 s[56:57], s3, v117
	v_subrev_u32_e32 v117, 17, v115
	v_cmp_gt_u32_e64 s[58:59], s3, v117
	v_subrev_u32_e32 v117, 18, v115
	v_cmp_gt_u32_e64 s[60:61], s3, v117
	v_subrev_u32_e32 v117, 19, v115
	v_cmp_gt_u32_e64 s[62:63], s3, v117
	v_cndmask_b32_e64 v78, v148, v78, s[48:49]
	v_cndmask_b32_e64 v79, v148, v79, s[50:51]
	v_cndmask_b32_e64 v80, v148, v80, s[52:53]
	v_cndmask_b32_e64 v81, v148, v81, s[54:55]
	v_cndmask_b32_e64 v70, v148, v70, s[56:57]
	v_cndmask_b32_e64 v71, v148, v71, s[58:59]
	v_cndmask_b32_e64 v72, v148, v72, s[60:61]
	v_cndmask_b32_e64 v73, v148, v73, s[62:63]
	v_subrev_u32_e32 v117, 32, v115
	v_cmp_gt_u32_e64 s[48:49], s3, v117
	v_subrev_u32_e32 v117, 33, v115
	v_cmp_gt_u32_e64 s[50:51], s3, v117
	v_subrev_u32_e32 v117, 34, v115
	v_cmp_gt_u32_e64 s[52:53], s3, v117
	v_subrev_u32_e32 v117, 35, v115
	v_cmp_gt_u32_e64 s[54:55], s3, v117
	v_subrev_u32_e32 v117, 48, v115
	v_cmp_gt_u32_e64 s[56:57], s3, v117
	v_subrev_u32_e32 v117, 49, v115
	v_cmp_gt_u32_e64 s[58:59], s3, v117
	v_subrev_u32_e32 v117, 50, v115
	v_cmp_gt_u32_e64 s[60:61], s3, v117
	v_subrev_u32_e32 v117, 51, v115
	v_cmp_gt_u32_e64 s[62:63], s3, v117
	v_cndmask_b32_e64 v62, v148, v62, s[48:49]
	v_cndmask_b32_e64 v63, v148, v63, s[50:51]
	v_cndmask_b32_e64 v64, v148, v64, s[52:53]
	v_cndmask_b32_e64 v65, v148, v65, s[54:55]
	v_cndmask_b32_e64 v54, v148, v54, s[56:57]
	v_cndmask_b32_e64 v55, v148, v55, s[58:59]
	v_cndmask_b32_e64 v56, v148, v56, s[60:61]
	v_cndmask_b32_e64 v57, v148, v57, s[62:63]
	v_max3_f32 v116, v78, v79, v80
	v_max3_f32 v116, v116, v81, v70
	v_max3_f32 v116, v116, v71, v72
	v_max3_f32 v116, v116, v73, v62
	v_max3_f32 v116, v116, v63, v64
	v_max3_f32 v116, v116, v65, v54
	v_max3_f32 v116, v116, v55, v56
	v_max3_f32 v116, v116, v57, s29
	v_mov_b32_e32 v117, v116
	s_nop 1
	v_permlane16_swap_b32_e32 v116, v117
	v_max_f32_e32 v116, v116, v117
	v_mov_b32_e32 v117, v116
	s_nop 1
	v_permlane32_swap_b32_e32 v116, v117
	v_max_f32_e32 v116, v116, v117
	v_max_f32_e32 v121, v166, v116
	v_sub_f32_e32 v118, v166, v121
	v_cmp_lt_f32_e32 vcc, s30, v121
	v_exp_f32_e32 v118, v118
	v_mov_b32_e32 v166, v121
	v_cndmask_b32_e32 v120, 0, v121, vcc
	v_pk_mul_f32 v[46:47], v[46:47], v[118:119] op_sel_hi:[1,0]
	v_pk_mul_f32 v[48:49], v[48:49], v[118:119] op_sel_hi:[1,0]
	v_pk_mul_f32 v[42:43], v[42:43], v[118:119] op_sel_hi:[1,0]
	v_pk_mul_f32 v[44:45], v[44:45], v[118:119] op_sel_hi:[1,0]
	v_pk_mul_f32 v[38:39], v[38:39], v[118:119] op_sel_hi:[1,0]
	v_pk_mul_f32 v[40:41], v[40:41], v[118:119] op_sel_hi:[1,0]
	v_pk_mul_f32 v[34:35], v[34:35], v[118:119] op_sel_hi:[1,0]
	v_pk_mul_f32 v[36:37], v[36:37], v[118:119] op_sel_hi:[1,0]
	v_pk_add_f32 v[78:79], v[78:79], v[120:121] op_sel_hi:[1,0] neg_lo:[0,1] neg_hi:[0,1]
	v_pk_add_f32 v[80:81], v[80:81], v[120:121] op_sel_hi:[1,0] neg_lo:[0,1] neg_hi:[0,1]
	v_pk_add_f32 v[70:71], v[70:71], v[120:121] op_sel_hi:[1,0] neg_lo:[0,1] neg_hi:[0,1]
	v_pk_add_f32 v[72:73], v[72:73], v[120:121] op_sel_hi:[1,0] neg_lo:[0,1] neg_hi:[0,1]
	v_pk_add_f32 v[62:63], v[62:63], v[120:121] op_sel_hi:[1,0] neg_lo:[0,1] neg_hi:[0,1]
	v_pk_add_f32 v[64:65], v[64:65], v[120:121] op_sel_hi:[1,0] neg_lo:[0,1] neg_hi:[0,1]
	v_pk_add_f32 v[54:55], v[54:55], v[120:121] op_sel_hi:[1,0] neg_lo:[0,1] neg_hi:[0,1]
	v_pk_add_f32 v[56:57], v[56:57], v[120:121] op_sel_hi:[1,0] neg_lo:[0,1] neg_hi:[0,1]
	v_exp_f32_e32 v78, v78
	v_exp_f32_e32 v79, v79
	v_exp_f32_e32 v80, v80
	v_exp_f32_e32 v81, v81
	v_exp_f32_e32 v70, v70
	v_exp_f32_e32 v71, v71
	v_exp_f32_e32 v72, v72
	v_exp_f32_e32 v73, v73
	v_exp_f32_e32 v62, v62
	v_exp_f32_e32 v63, v63
	v_exp_f32_e32 v64, v64
	v_exp_f32_e32 v65, v65
	v_exp_f32_e32 v54, v54
	v_exp_f32_e32 v55, v55
	v_exp_f32_e32 v56, v56
	v_exp_f32_e32 v57, v57
	s_nop 0
	v_pk_add_f32 v[82:83], v[78:79], v[80:81]
	v_pk_add_f32 v[84:85], v[70:71], v[72:73]
	v_pk_add_f32 v[86:87], v[62:63], v[64:65]
	v_pk_add_f32 v[88:89], v[54:55], v[56:57]
	v_pk_add_f32 v[82:83], v[82:83], v[84:85]
	v_pk_add_f32 v[86:87], v[86:87], v[88:89]
	s_nop 0
	v_pk_add_f32 v[82:83], v[82:83], v[86:87]
	s_nop 0
	v_add_f32_e32 v82, v82, v83
	v_fma_f32 v160, v160, v118, v82
	v_cvt_pk_bf16_f32 v73, v72, v73
	v_cvt_pk_bf16_f32 v72, v70, v71
	v_cvt_pk_bf16_f32 v71, v80, v81
	v_cvt_pk_bf16_f32 v70, v78, v79
	v_cvt_pk_bf16_f32 v62, v62, v63
	v_cvt_pk_bf16_f32 v63, v64, v65
	v_cvt_pk_bf16_f32 v64, v54, v55
	v_cvt_pk_bf16_f32 v65, v56, v57
	v_add_u32_e32 v115, 0xfbc, v114
	s_waitcnt lgkmcnt(0)
	ds_read2_b32 v[82:83], v115 offset1:1
	ds_read2_b32 v[84:85], v115 offset0:2 offset1:3
	ds_read2_b32 v[86:87], v115 offset0:16 offset1:17
	ds_read2_b32 v[88:89], v115 offset0:18 offset1:19
	ds_read2_b32 v[90:91], v115 offset0:32 offset1:33
	ds_read2_b32 v[92:93], v115 offset0:34 offset1:35
	ds_read2_b32 v[94:95], v115 offset0:48 offset1:49
	ds_read2_b32 v[96:97], v115 offset0:50 offset1:51
	v_mfma_f32_16x16x32_bf16 v[98:101], v[98:101], v[10:13], 0
	v_mfma_f32_16x16x32_bf16 v[102:105], v[102:105], v[10:13], 0
	v_mfma_f32_16x16x32_bf16 v[106:109], v[106:109], v[10:13], 0
	v_mfma_f32_16x16x32_bf16 v[110:113], v[110:113], v[10:13], 0
	v_mfma_f32_16x16x32_bf16 v[98:101], v[74:77], v[14:17], v[98:101]
	v_mfma_f32_16x16x32_bf16 v[102:105], v[66:69], v[14:17], v[102:105]
	v_mfma_f32_16x16x32_bf16 v[106:109], v[58:61], v[14:17], v[106:109]
	v_mfma_f32_16x16x32_bf16 v[110:113], v[50:53], v[14:17], v[110:113]
	s_waitcnt lgkmcnt(0)
	s_nop 6
	v_pk_fma_f32 v[98:99], v[98:99], s[36:37], v[82:83] op_sel_hi:[1,0,1]
	v_pk_fma_f32 v[100:101], v[100:101], s[36:37], v[84:85] op_sel_hi:[1,0,1]
	v_pk_fma_f32 v[102:103], v[102:103], s[36:37], v[86:87] op_sel_hi:[1,0,1]
	v_pk_fma_f32 v[104:105], v[104:105], s[36:37], v[88:89] op_sel_hi:[1,0,1]
	v_pk_fma_f32 v[106:107], v[106:107], s[36:37], v[90:91] op_sel_hi:[1,0,1]
	v_pk_fma_f32 v[108:109], v[108:109], s[36:37], v[92:93] op_sel_hi:[1,0,1]
	v_pk_fma_f32 v[110:111], v[110:111], s[36:37], v[94:95] op_sel_hi:[1,0,1]
	v_pk_fma_f32 v[112:113], v[112:113], s[36:37], v[96:97] op_sel_hi:[1,0,1]
	v_or_b32_e32 v117, s25, v216
	v_sub_u32_e32 v115, v144, v117
	v_add_u32_e32 v115, 16, v115
	v_subrev_u32_e32 v117, 0, v115
	v_cmp_gt_u32_e64 s[48:49], s3, v117
	v_subrev_u32_e32 v117, 1, v115
	v_cmp_gt_u32_e64 s[50:51], s3, v117
	v_subrev_u32_e32 v117, 2, v115
	v_cmp_gt_u32_e64 s[52:53], s3, v117
	v_subrev_u32_e32 v117, 3, v115
	v_cmp_gt_u32_e64 s[54:55], s3, v117
	v_subrev_u32_e32 v117, 16, v115
	v_cmp_gt_u32_e64 s[56:57], s3, v117
	v_subrev_u32_e32 v117, 17, v115
	v_cmp_gt_u32_e64 s[58:59], s3, v117
	v_subrev_u32_e32 v117, 18, v115
	v_cmp_gt_u32_e64 s[60:61], s3, v117
	v_subrev_u32_e32 v117, 19, v115
	v_cmp_gt_u32_e64 s[62:63], s3, v117
	v_cndmask_b32_e64 v98, v148, v98, s[48:49]
	v_cndmask_b32_e64 v99, v148, v99, s[50:51]
	v_cndmask_b32_e64 v100, v148, v100, s[52:53]
	v_cndmask_b32_e64 v101, v148, v101, s[54:55]
	v_cndmask_b32_e64 v102, v148, v102, s[56:57]
	v_cndmask_b32_e64 v103, v148, v103, s[58:59]
	v_cndmask_b32_e64 v104, v148, v104, s[60:61]
	v_cndmask_b32_e64 v105, v148, v105, s[62:63]
	v_subrev_u32_e32 v117, 32, v115
	v_cmp_gt_u32_e64 s[48:49], s3, v117
	v_subrev_u32_e32 v117, 33, v115
	v_cmp_gt_u32_e64 s[50:51], s3, v117
	v_subrev_u32_e32 v117, 34, v115
	v_cmp_gt_u32_e64 s[52:53], s3, v117
	v_subrev_u32_e32 v117, 35, v115
	v_cmp_gt_u32_e64 s[54:55], s3, v117
	v_subrev_u32_e32 v117, 48, v115
	v_cmp_gt_u32_e64 s[56:57], s3, v117
	v_subrev_u32_e32 v117, 49, v115
	v_cmp_gt_u32_e64 s[58:59], s3, v117
	v_subrev_u32_e32 v117, 50, v115
	v_cmp_gt_u32_e64 s[60:61], s3, v117
	v_subrev_u32_e32 v117, 51, v115
	v_cmp_gt_u32_e64 s[62:63], s3, v117
	v_cndmask_b32_e64 v106, v148, v106, s[48:49]
	v_cndmask_b32_e64 v107, v148, v107, s[50:51]
	v_cndmask_b32_e64 v108, v148, v108, s[52:53]
	v_cndmask_b32_e64 v109, v148, v109, s[54:55]
	v_cndmask_b32_e64 v110, v148, v110, s[56:57]
	v_cndmask_b32_e64 v111, v148, v111, s[58:59]
	v_cndmask_b32_e64 v112, v148, v112, s[60:61]
	v_cndmask_b32_e64 v113, v148, v113, s[62:63]
	v_max3_f32 v116, v98, v99, v100
	v_max3_f32 v116, v116, v101, v102
	v_max3_f32 v116, v116, v103, v104
	v_max3_f32 v116, v116, v105, v106
	v_max3_f32 v116, v116, v107, v108
	v_max3_f32 v116, v116, v109, v110
	v_max3_f32 v116, v116, v111, v112
	v_max3_f32 v116, v116, v113, s29
	v_mov_b32_e32 v117, v116
	s_nop 1
	v_permlane16_swap_b32_e32 v116, v117
	v_max_f32_e32 v116, v116, v117
	v_mov_b32_e32 v117, v116
	s_nop 1
	v_permlane32_swap_b32_e32 v116, v117
	v_max_f32_e32 v116, v116, v117
	v_max_f32_e32 v121, v167, v116
	v_sub_f32_e32 v118, v167, v121
	v_cmp_lt_f32_e32 vcc, s30, v121
	v_exp_f32_e32 v118, v118
	v_mov_b32_e32 v167, v121
	v_cndmask_b32_e32 v120, 0, v121, vcc
	v_pk_mul_f32 v[30:31], v[30:31], v[118:119] op_sel_hi:[1,0]
	v_pk_mul_f32 v[32:33], v[32:33], v[118:119] op_sel_hi:[1,0]
	v_pk_mul_f32 v[26:27], v[26:27], v[118:119] op_sel_hi:[1,0]
	v_pk_mul_f32 v[28:29], v[28:29], v[118:119] op_sel_hi:[1,0]
	v_pk_mul_f32 v[22:23], v[22:23], v[118:119] op_sel_hi:[1,0]
	v_pk_mul_f32 v[24:25], v[24:25], v[118:119] op_sel_hi:[1,0]
	v_pk_mul_f32 v[18:19], v[18:19], v[118:119] op_sel_hi:[1,0]
	v_pk_mul_f32 v[20:21], v[20:21], v[118:119] op_sel_hi:[1,0]
	v_pk_add_f32 v[98:99], v[98:99], v[120:121] op_sel_hi:[1,0] neg_lo:[0,1] neg_hi:[0,1]
	v_pk_add_f32 v[100:101], v[100:101], v[120:121] op_sel_hi:[1,0] neg_lo:[0,1] neg_hi:[0,1]
	v_pk_add_f32 v[102:103], v[102:103], v[120:121] op_sel_hi:[1,0] neg_lo:[0,1] neg_hi:[0,1]
	v_pk_add_f32 v[104:105], v[104:105], v[120:121] op_sel_hi:[1,0] neg_lo:[0,1] neg_hi:[0,1]
	v_pk_add_f32 v[106:107], v[106:107], v[120:121] op_sel_hi:[1,0] neg_lo:[0,1] neg_hi:[0,1]
	v_pk_add_f32 v[108:109], v[108:109], v[120:121] op_sel_hi:[1,0] neg_lo:[0,1] neg_hi:[0,1]
	v_pk_add_f32 v[110:111], v[110:111], v[120:121] op_sel_hi:[1,0] neg_lo:[0,1] neg_hi:[0,1]
	v_pk_add_f32 v[112:113], v[112:113], v[120:121] op_sel_hi:[1,0] neg_lo:[0,1] neg_hi:[0,1]
	v_exp_f32_e32 v98, v98
	v_exp_f32_e32 v99, v99
	v_exp_f32_e32 v100, v100
	v_exp_f32_e32 v101, v101
	v_exp_f32_e32 v102, v102
	v_exp_f32_e32 v103, v103
	v_exp_f32_e32 v104, v104
	v_exp_f32_e32 v105, v105
	v_exp_f32_e32 v106, v106
	v_exp_f32_e32 v107, v107
	v_exp_f32_e32 v108, v108
	v_exp_f32_e32 v109, v109
	v_exp_f32_e32 v110, v110
	v_exp_f32_e32 v111, v111
	v_exp_f32_e32 v112, v112
	v_exp_f32_e32 v113, v113
	s_nop 0
	v_pk_add_f32 v[82:83], v[98:99], v[100:101]
	v_pk_add_f32 v[84:85], v[102:103], v[104:105]
	v_pk_add_f32 v[86:87], v[106:107], v[108:109]
	v_pk_add_f32 v[88:89], v[110:111], v[112:113]
	v_pk_add_f32 v[82:83], v[82:83], v[84:85]
	v_pk_add_f32 v[86:87], v[86:87], v[88:89]
	s_nop 0
	v_pk_add_f32 v[82:83], v[82:83], v[86:87]
	s_nop 0
	v_add_f32_e32 v82, v82, v83
	v_fma_f32 v161, v161, v118, v82
	v_cvt_pk_bf16_f32 v105, v104, v105
	v_cvt_pk_bf16_f32 v104, v102, v103
	v_cvt_pk_bf16_f32 v103, v100, v101
	v_cvt_pk_bf16_f32 v102, v98, v99
	v_cvt_pk_bf16_f32 v106, v106, v107
	v_cvt_pk_bf16_f32 v107, v108, v109
	v_cvt_pk_bf16_f32 v108, v110, v111
	v_cvt_pk_bf16_f32 v109, v112, v113
	s_branch .Lnw_pv
	.p2alignl 6, 3212836864

.LBB0_293:
	s_andn2_b64 vcc, exec, s[70:71]
	s_cbranch_vccz .LBB0_231
	s_mov_b32 s19, s21
	s_branch .LBB0_281
	.p2alignl 6, 3212836864
.LBB0_295:
	s_waitcnt vmcnt(0)
	s_barrier
	s_mov_b64 s[6:7], exec
	v_readlane_b32 s0, v253, 8
	v_readlane_b32 s1, v253, 9
	s_and_b64 s[0:1], s[6:7], s[0:1]
	s_mov_b64 exec, s[0:1]
	s_cbranch_execz .LBB0_347
	v_readlane_b32 s0, v254, 58
	s_waitcnt vmcnt(0) expcnt(0) lgkmcnt(0)
	s_nop 0
	v_mov_b32_e32 v0, s0
	ds_read_b32 v3, v0
	v_readlane_b32 s0, v254, 59
	s_waitcnt lgkmcnt(0)
	v_cmp_ne_u32_e32 vcc, 0, v3
	v_mov_b32_e32 v0, s0
	ds_read_b32 v2, v0
	s_cbranch_vccnz .LBB0_311
	s_mov_b32 s0, 1
	s_branch .LBB0_299
	.p2alignl 6, 3212836864

.LBB0_304:
	s_add_i32 s0, s0, 1
	s_mov_b64 s[10:11], 0
	s_branch .LBB0_298
	.p2alignl 6, 3212836864
.LBB0_305:
	s_cmp_lt_u32 s0, 0x40001
	s_mov_b64 s[8:9], 0
	s_cselect_b64 s[12:13], -1, 0
	s_and_b64 vcc, exec, s[12:13]
	s_cbranch_vccz .LBB0_298
	s_branch .LBB0_304
	.p2alignl 6, 3212836864

.LBB0_313:
	s_or_b64 exec, exec, s[8:9]
	v_cvt_f32_u32_e32 v5, v3
	s_waitcnt vmcnt(0)
	v_readfirstlane_b32 s0, v4
	v_sub_u32_e32 v4, 0, v3
	v_rcp_iflag_f32_e32 v5, v5
	v_add_u32_e32 v6, s0, v0
	v_mul_f32_e32 v5, 0x4f7ffffe, v5
	v_cvt_u32_f32_e32 v5, v5
	v_mul_lo_u32 v0, v4, v5
	v_mul_hi_u32 v0, v5, v0
	v_add_u32_e32 v0, v5, v0
	v_mul_hi_u32 v0, v6, v0
	v_mul_lo_u32 v4, v0, v3
	v_sub_u32_e32 v4, v6, v4
	v_add_u32_e32 v5, 1, v0
	v_cmp_ge_u32_e32 vcc, v4, v3
	s_nop 1
	v_cndmask_b32_e32 v0, v0, v5, vcc
	v_sub_u32_e32 v5, v4, v3
	v_cndmask_b32_e32 v4, v4, v5, vcc
	v_add_u32_e32 v5, 1, v0
	v_cmp_ge_u32_e32 vcc, v4, v3
	v_add_u32_e32 v4, 1, v6
	s_nop 0
	v_cndmask_b32_e32 v0, v0, v5, vcc
	v_mul_lo_u32 v5, v3, v0
	v_add_u32_e32 v3, v5, v3
	v_cmp_ne_u32_e32 vcc, v4, v3
	s_and_saveexec_b64 s[0:1], vcc
	s_xor_b64 s[8:9], exec, s[0:1]
	s_cbranch_execz .LBB0_327
	v_readlane_b32 s0, v254, 18
	v_readlane_b32 s1, v254, 19
	s_waitcnt lgkmcnt(0)
	s_nop 3
	global_load_dword v2, v1, s[0:1] sc1
	s_waitcnt vmcnt(0)
	v_cmp_eq_u32_e32 vcc, v2, v0
	s_and_saveexec_b64 s[10:11], vcc
	s_cbranch_execz .LBB0_326
	s_mov_b32 s0, 1
	s_mov_b64 s[12:13], 0
	s_branch .LBB0_317
	.p2alignl 6, 3212836864

.LBB0_321:
	v_readlane_b32 s4, v254, 18
	v_readlane_b32 s5, v254, 19
	s_add_i32 s0, s0, 1
	s_mov_b64 s[38:39], -1
	s_nop 2
	global_load_dword v2, v1, s[4:5] sc1
	s_waitcnt vmcnt(0)
	v_cmp_ne_u32_e32 vcc, v2, v0
	s_orn2_b64 s[22:23], vcc, exec
	s_branch .LBB0_316
	.p2alignl 6, 3212836864
.LBB0_322:
	s_cmp_lt_u32 s0, 0x40001
	s_mov_b64 s[38:39], 0
	s_cselect_b64 s[40:41], -1, 0
	s_and_b64 vcc, exec, s[40:41]
	s_cbranch_vccz .LBB0_316
	s_branch .LBB0_321
	.p2alignl 6, 3212836864

.LBB0_330:
	s_or_b64 exec, exec, s[10:11]
	s_waitcnt vmcnt(0)
	v_readfirstlane_b32 s0, v3
	v_sub_u32_e32 v4, 0, v2
	s_mov_b64 s[10:11], -1
	v_add_u32_e32 v3, s0, v0
	v_cvt_f32_u32_e32 v0, v2
	v_readlane_b32 s0, v254, 22
	v_readlane_b32 s1, v254, 23
	v_rcp_iflag_f32_e32 v0, v0
	s_nop 0
	v_mul_f32_e32 v0, 0x4f7ffffe, v0
	v_cvt_u32_f32_e32 v0, v0
	v_mul_lo_u32 v4, v4, v0
	v_mul_hi_u32 v4, v0, v4
	v_add_u32_e32 v0, v0, v4
	v_mul_hi_u32 v0, v3, v0
	v_mul_lo_u32 v4, v0, v2
	v_sub_u32_e32 v4, v3, v4
	v_cmp_ge_u32_e32 vcc, v4, v2
	v_add_u32_e32 v5, 1, v0
	v_add_u32_e32 v3, 1, v3
	v_cndmask_b32_e32 v0, v0, v5, vcc
	v_sub_u32_e32 v5, v4, v2
	v_cndmask_b32_e32 v4, v4, v5, vcc
	v_cmp_ge_u32_e32 vcc, v4, v2
	v_add_u32_e32 v4, 1, v0
	s_nop 0
	v_cndmask_b32_e32 v0, v0, v4, vcc
	v_mul_lo_u32 v4, v2, v0
	v_add_u32_e32 v2, v4, v2
	v_cmp_ne_u32_e32 vcc, v3, v2
	v_mov_b64_e32 v[2:3], s[0:1]
	s_and_saveexec_b64 s[8:9], vcc
	s_cbranch_execz .LBB0_342
	v_readlane_b32 s0, v254, 22
	v_readlane_b32 s1, v254, 23
	s_mov_b64 s[12:13], 0
	s_nop 3
	global_load_dword v2, v1, s[0:1] sc1
	s_waitcnt vmcnt(0)
	v_cmp_eq_u32_e32 vcc, v2, v0
	s_and_saveexec_b64 s[10:11], vcc
	s_cbranch_execz .LBB0_341
	s_mov_b32 s0, 1
	s_branch .LBB0_334
	.p2alignl 6, 3212836864

.LBB0_338:
	v_readlane_b32 s4, v254, 22
	v_readlane_b32 s5, v254, 23
	s_add_i32 s0, s0, 1
	s_mov_b64 s[38:39], -1
	s_nop 2
	global_load_dword v2, v1, s[4:5] sc1
	s_waitcnt vmcnt(0)
	v_cmp_ne_u32_e32 vcc, v2, v0
	s_orn2_b64 s[22:23], vcc, exec
	s_branch .LBB0_333
	.p2alignl 6, 3212836864

.LBB0_347:
	s_or_b64 exec, exec, s[6:7]
	v_readlane_b32 s6, v253, 4
	v_readlane_b32 s4, v253, 10
	v_readlane_b32 s7, v253, 5
	s_waitcnt lgkmcnt(0)
	v_mov_b32_e32 v2, v146
	v_readlane_b32 s5, v253, 11
	s_barrier
	s_and_b64 vcc, exec, s[4:5]
	v_readfirstlane_b32 s0, v2
	s_cbranch_vccz .LBB0_451
	s_load_dwordx2 s[4:5], s[6:7], 0x98
	s_ashr_i32 s2, s0, 6
	v_bfe_u32 v0, v2, 3, 3
	v_bfe_u32 v12, v2, 4, 2
	v_and_b32_e32 v8, 7, v2
	s_waitcnt lgkmcnt(0)
	s_add_u32 s6, s4, 0x5f00000
	s_addc_u32 s7, s5, 0
	s_lshl_b32 s8, s2, 3
	v_bitop3_b32 v11, v0, v2, 7 bitop3:0x78
	v_or_b32_e32 v4, s8, v0
	v_bitop3_b32 v0, v12, v2, 7 bitop3:0x78
	v_lshlrev_b32_e32 v194, 4, v0
	v_bitop3_b32 v0, v12, v8, 4 bitop3:0x36
	v_lshlrev_b32_e32 v197, 2, v12
	v_bfe_u32 v122, v2, 2, 2
	v_lshlrev_b32_e32 v195, 4, v0
	v_or_b32_e32 v0, v197, v122
	v_bfe_u32 v8, v2, 1, 1
	v_bitop3_b32 v9, v0, v8, 7 bitop3:0x6c
	v_lshlrev_b32_e32 v200, 4, v9
	v_or_b32_e32 v9, 2, v8
	v_bitop3_b32 v9, v0, v9, 7 bitop3:0x6c
	v_and_b32_e32 v190, 63, v2
	v_lshlrev_b32_e32 v201, 4, v9
	v_or_b32_e32 v9, 4, v8
	v_or_b32_e32 v8, 6, v8
	s_lshl_b32 s1, s2, 10
	v_lshlrev_b32_e32 v198, 7, v0
	v_lshlrev_b32_e32 v13, 3, v190
	v_bitop3_b32 v9, v0, v9, 7 bitop3:0x6c
	v_bitop3_b32 v0, v0, v8, 7 bitop3:0x6c
	s_add_i32 s37, 0, 0x1c000
	s_andn2_b32 s0, s0, 63
	s_add_i32 s15, s1, 0
	v_lshlrev_b32_e32 v203, 4, v0
	v_lshlrev_b32_e32 v0, 4, v190
	v_add_u32_e32 v211, s37, v13
	s_add_i32 s37, s37, s0
	s_mul_i32 s0, s2, 0xd00
	v_lshlrev_b32_e32 v202, 4, v9
	v_lshl_add_u64 v[8:9], s[4:5], 0, v[0:1]
	v_add_u32_e32 v0, 48, v2
	s_add_i32 s0, s15, s0
	v_and_b32_e32 v7, 15, v2
	v_writelane_b32 v255, s6, 18
	v_and_b32_e32 v210, 63, v0
	v_and_b32_e32 v213, 48, v2
	v_mov_b32_e32 v0, s0
	s_movk_i32 s0, 0x110
	v_writelane_b32 v255, s7, 19
	s_mov_b64 s[6:7], 0x18700000
	v_mad_u32_u24 v214, v7, s0, v0
	v_lshlrev_b32_e32 v0, 1, v213
	v_and_b32_e32 v191, 3, v2
	v_ashrrev_i32_e32 v5, 31, v4
	v_lshl_add_u64 v[124:125], v[8:9], 0, s[6:7]
	v_lshl_add_u64 v[8:9], s[4:5], 0, v[0:1]
	s_mov_b64 s[0:1], 0x11f00000
	v_lshlrev_b32_e32 v10, 12, v191
	v_ashrrev_i32_e32 v3, 31, v2
	v_lshlrev_b64 v[126:127], 12, v[4:5]
	v_lshl_add_u64 v[128:129], v[8:9], 0, s[0:1]
	s_mov_b64 s[0:1], 0xff00000
	v_lshlrev_b64 v[4:5], 7, v[4:5]
	v_lshl_add_u64 v[130:131], v[8:9], 0, s[0:1]
	v_lshl_add_u64 v[8:9], v[2:3], 4, s[4:5]
	s_mov_b64 s[0:1], 0x5d40000
	v_lshl_or_b32 v4, v11, 4, v4
	v_lshl_or_b32 v0, v12, 8, v10
	v_lshl_add_u32 v192, v2, 4, 0
	v_lshl_add_u64 v[132:133], v[8:9], 0, s[0:1]
	v_lshl_add_u64 v[4:5], s[4:5], 0, v[4:5]
	s_mov_b64 s[0:1], 0x5e00000
	v_add_u32_e32 v217, 0x1068, v0
	v_and_b32_e32 v2, 12, v2
	v_lshl_add_u64 v[134:135], v[4:5], 0, s[0:1]
	v_sub_u32_e32 v2, v217, v2
	s_lshl_b32 s0, s2, 5
	v_subrev_u32_e32 v224, s0, v2
	v_add_u32_e32 v225, 0x1078, v0
	v_lshl_or_b32 v0, v191, 6, v122
	s_lshl_b32 s0, s2, 11
	v_lshlrev_b32_e32 v3, 7, v122
	v_add_u32_e32 v0, s8, v0
	s_add_i32 s0, s0, 0
	v_lshlrev_b32_e32 v196, 7, v7
	v_and_b32_e32 v199, 8, v13
	v_lshl_or_b32 v3, v12, 9, v3
	v_lshl_or_b32 v0, v0, 8, v197
	v_writelane_b32 v255, s8, 20
	s_add_i32 s0, s0, 0xc000
	v_lshlrev_b32_e32 v6, 3, v12
	v_add_u32_e32 v193, 0, v10
	v_lshlrev_b32_e32 v215, 6, v12
	v_or3_b32 v218, v3, v203, v199
	v_or3_b32 v219, v3, v202, v199
	v_or3_b32 v220, v3, v201, v199
	v_or3_b32 v221, v3, v200, v199
	v_or_b32_e32 v3, 0x4000, v196
	v_add_u32_e32 v226, 0xc000, v0
	v_or_b32_e32 v0, s8, v122
	v_writelane_b32 v255, s2, 21
	v_lshl_add_u32 v229, v190, 2, s0
	s_add_i32 s0, s15, 0x4000
	v_or_b32_e32 v123, 4, v122
	v_cmp_eq_u32_e64 s[38:39], 3, v12
	v_cmp_eq_u32_e64 s[40:41], 0, v190
	v_lshl_add_u32 v212, v122, 3, s37
	v_lshl_or_b32 v126, v11, 3, v126
	v_add_u32_e32 v216, v193, v213
	v_or_b32_e32 v222, v3, v195
	v_or_b32_e32 v223, v3, v194
	v_or_b32_e32 v227, 3, v197
	v_sub_u32_e32 v228, v0, v215
	v_writelane_b32 v255, s0, 22
	v_lshlrev_b32_e32 v136, 1, v6
	v_readlane_b32 s33, v253, 6
	s_branch .LBB0_351
	.p2alignl 6, 3212836864

.LBB0_362:
	s_add_i32 s4, s4, 1
	s_addk_i32 s19, 0x400
	s_addk_i32 s18, 0xfc00
	v_add_u32_e32 v149, 0x1000, v149
	v_add_u32_e32 v235, 0x2000, v235
	v_add_u32_e32 v234, 0x2000, v234
	v_add_u32_e32 v233, 0x2000, v233
	v_add_u32_e32 v232, 0x2000, v232
	v_add_u32_e32 v231, 0x2000, v231
	v_add_u32_e32 v230, 0x2000, v230
	s_cmp_eq_u32 s13, s19
	v_add_u32_e32 v159, 64, v159
	s_cbranch_scc1 .LBB0_364
	v_mov_b64_e32 v[18:19], v[94:95]
	v_mov_b64_e32 v[22:23], v[90:91]
	v_mov_b64_e32 v[26:27], v[86:87]
	v_mov_b64_e32 v[30:31], v[82:83]
	v_mov_b64_e32 v[34:35], v[110:111]
	v_mov_b64_e32 v[38:39], v[106:107]
	v_mov_b64_e32 v[42:43], v[102:103]
	v_mov_b64_e32 v[46:47], v[98:99]
	v_mov_b64_e32 v[20:21], v[96:97]
	v_mov_b64_e32 v[24:25], v[92:93]
	v_mov_b64_e32 v[28:29], v[88:89]
	v_mov_b64_e32 v[32:33], v[84:85]
	v_mov_b64_e32 v[36:37], v[112:113]
	v_mov_b64_e32 v[40:41], v[108:109]
	v_mov_b64_e32 v[44:45], v[104:105]
	v_mov_b64_e32 v[48:49], v[100:101]
	v_mov_b64_e32 v[162:163], v[188:189]
	v_mov_b32_e32 v238, v161
	v_mov_b32_e32 v0, v241
	s_branch .LBB0_354
	.p2alignl 6, 3212836864
.LBB0_364:
	v_and_b32_e32 v20, 64, v147
	s_lshl_b32 s4, s25, 3
	v_readlane_b32 s5, v255, 21
	v_xor_b32_e32 v0, 16, v147
	v_add_u32_e32 v38, 64, v20
	s_add_i32 s4, s4, s5
	v_cmp_lt_i32_e32 vcc, v0, v38
	s_ashr_i32 s5, s4, 31
	s_lshl_b64 s[4:5], s[4:5], 13
	v_cndmask_b32_e32 v0, v147, v0, vcc
	v_lshlrev_b32_e32 v119, 2, v0
	v_xor_b32_e32 v0, 32, v147
	v_lshl_add_u64 v[116:117], v[124:125], 0, s[4:5]
	v_cmp_lt_i32_e32 vcc, v0, v38
	s_add_i32 s5, s2, s22
	v_or_b32_e32 v114, s5, v122
	v_cndmask_b32_e32 v0, v147, v0, vcc
	v_mul_u32_u24_e32 v118, 3, v145
	v_readlane_b32 s6, v255, 18
	v_lshlrev_b32_e32 v137, 2, v0
	v_lshlrev_b32_e32 v0, 1, v118
	v_readlane_b32 s7, v255, 19
	v_ashrrev_i32_e32 v115, 31, v114
	v_lshlrev_b64 v[120:121], 13, v[114:115]
	v_lshl_add_u64 v[18:19], s[6:7], 0, v[0:1]
	v_lshl_add_u64 v[24:25], v[18:19], 0, v[120:121]
	s_movk_i32 s5, 0x1000
	v_add_co_u32_e32 v24, vcc, s5, v24
	ds_bpermute_b32 v22, v119, v188
	s_nop 0
	v_addc_co_u32_e32 v25, vcc, 0, v25, vcc
	global_load_ushort v0, v[24:25], off offset:3584
	s_mov_b64 s[98:99], 0x8000
	v_lshl_add_u64 v[56:57], v[24:25], 0, s[98:99]
	global_load_ushort v58, v[56:57], off offset:3584
	s_mov_b32 s4, 0
	s_movk_i32 s83, 0x1000
	v_sub_u32_e32 v40, v225, v143
	v_add_u32_e32 v41, s14, v228
	v_mov_b32_e32 v42, v227
	v_mov_b32_e32 v43, v223
	v_mov_b32_e32 v44, v222
	v_mov_b32_e32 v45, v226
	v_mov_b32_e32 v31, 0
	s_waitcnt vmcnt(0)
	v_lshlrev_b32_e32 v0, 16, v0
	v_mul_f32_e32 v0, 0xbfb8aa3b, v0
	v_exp_f32_e32 v0, v0
	s_nop 0
	v_add_f32_e32 v0, 1.0, v0
	v_div_scale_f32 v21, s[6:7], v0, v0, 1.0
	v_rcp_f32_e32 v23, v21
	s_nop 0
	v_fma_f32 v24, -v21, v23, 1.0
	v_fmac_f32_e32 v23, v24, v23
	v_div_scale_f32 v24, vcc, 1.0, v0, 1.0
	v_mul_f32_e32 v25, v24, v23
	v_fma_f32 v26, -v21, v25, v24
	v_fmac_f32_e32 v25, v26, v23
	v_fma_f32 v21, -v21, v25, v24
	v_div_fmas_f32 v21, v21, v23, v25
	ds_bpermute_b32 v23, v119, v189
	v_div_fixup_f32 v0, v21, v0, 1.0
	s_waitcnt lgkmcnt(0)
	v_pk_add_f32 v[22:23], v[188:189], v[22:23]
	ds_bpermute_b32 v24, v137, v22
	ds_bpermute_b32 v25, v137, v23
	s_waitcnt lgkmcnt(0)
	v_pk_add_f32 v[28:29], v[22:23], v[24:25]
	s_nop 0
	v_div_scale_f32 v21, s[6:7], v28, v28, 1.0
	v_rcp_f32_e32 v22, v21
	v_cmp_lt_f32_e64 s[42:43], 0, v29
	v_fma_f32 v23, -v21, v22, 1.0
	v_fmac_f32_e32 v22, v23, v22
	v_div_scale_f32 v23, vcc, 1.0, v28, 1.0
	v_mul_f32_e32 v24, v23, v22
	v_fma_f32 v25, -v21, v24, v23
	v_fmac_f32_e32 v24, v25, v22
	v_fma_f32 v21, -v21, v24, v23
	v_div_fmas_f32 v21, v21, v22, v24
	v_div_fixup_f32 v21, v21, v28, 1.0
	v_cmp_lt_f32_e32 vcc, 0, v28
	v_mov_b32_e32 v23, 0
	s_nop 0
	v_cndmask_b32_e32 v34, 0, v21, vcc
	v_mul_f32_e32 v0, v34, v0
	v_pk_mul_f32 v[26:27], v[100:101], v[0:1] op_sel_hi:[1,0]
	v_pk_mul_f32 v[24:25], v[98:99], v[0:1] op_sel_hi:[1,0]
	global_store_dwordx4 v[116:117], v[24:27], off
	v_mov_b32_e32 v35, v34
	s_nop 0
	v_pk_mul_f32 v[26:27], v[104:105], v[0:1] op_sel_hi:[1,0]
	v_pk_mul_f32 v[24:25], v[102:103], v[0:1] op_sel_hi:[1,0]
	global_store_dwordx4 v[116:117], v[24:27], off offset:1024
	v_or_b32_e32 v102, 4, v114
	v_ashrrev_i32_e32 v103, 31, v102
	v_pk_mul_f32 v[26:27], v[108:109], v[0:1] op_sel_hi:[1,0]
	v_pk_mul_f32 v[24:25], v[106:107], v[0:1] op_sel_hi:[1,0]
	global_store_dwordx4 v[116:117], v[24:27], off offset:2048
	s_nop 1
	v_pk_mul_f32 v[26:27], v[112:113], v[0:1] op_sel_hi:[1,0]
	v_pk_mul_f32 v[24:25], v[110:111], v[0:1] op_sel_hi:[1,0]
	v_div_scale_f32 v0, s[6:7], v29, v29, 1.0
	v_rcp_f32_e32 v21, v0
	global_store_dwordx4 v[116:117], v[24:27], off offset:3072
	v_lshlrev_b64 v[112:113], 13, v[102:103]
	v_lshl_add_u64 v[18:19], v[18:19], 0, v[112:113]
	v_fma_f32 v22, -v0, v21, 1.0
	v_fmac_f32_e32 v21, v22, v21
	v_div_scale_f32 v22, vcc, 1.0, v29, 1.0
	v_mul_f32_e32 v24, v22, v21
	v_fma_f32 v25, -v0, v24, v22
	v_fmac_f32_e32 v24, v25, v21
	v_fma_f32 v0, -v0, v24, v22
	v_div_fmas_f32 v0, v0, v21, v24
	v_add_co_u32_e32 v18, vcc, s5, v18
	v_div_fixup_f32 v0, v0, v29, 1.0
	s_nop 0
	v_addc_co_u32_e32 v19, vcc, 0, v19, vcc
	v_cndmask_b32_e64 v36, 0, v0, s[42:43]
	v_mov_b32_e32 v0, v58
	v_mov_b32_e32 v37, v36
	v_lshlrev_b32_e32 v0, 16, v0
	v_mul_f32_e32 v0, 0xbfb8aa3b, v0
	v_exp_f32_e32 v0, v0
	s_nop 0
	v_add_f32_e32 v0, 1.0, v0
	v_div_scale_f32 v18, s[6:7], v0, v0, 1.0
	v_rcp_f32_e32 v19, v18
	s_mov_b64 s[6:7], 0x1000
	v_lshl_add_u64 v[110:111], v[116:117], 0, s[6:7]
	s_mov_b64 s[6:7], 0x1400
	v_fma_f32 v21, -v18, v19, 1.0
	v_fmac_f32_e32 v19, v21, v19
	v_div_scale_f32 v21, vcc, 1.0, v0, 1.0
	v_mul_f32_e32 v22, v21, v19
	v_fma_f32 v24, -v18, v22, v21
	v_fmac_f32_e32 v22, v24, v19
	v_fma_f32 v18, -v18, v22, v21
	v_div_fmas_f32 v18, v18, v19, v22
	v_div_fixup_f32 v0, v18, v0, 1.0
	v_mul_f32_e32 v0, v36, v0
	v_add_co_u32_e32 v18, vcc, s5, v116
	v_pk_mul_f32 v[26:27], v[84:85], v[0:1] op_sel_hi:[1,0]
	v_pk_mul_f32 v[24:25], v[82:83], v[0:1] op_sel_hi:[1,0]
	v_addc_co_u32_e32 v19, vcc, 0, v117, vcc
	global_store_dwordx4 v[18:19], v[24:27], off
	v_lshl_add_u64 v[106:107], v[116:117], 0, s[6:7]
	s_mov_b64 s[6:7], 0x1800
	v_pk_mul_f32 v[26:27], v[88:89], v[0:1] op_sel_hi:[1,0]
	v_pk_mul_f32 v[24:25], v[86:87], v[0:1] op_sel_hi:[1,0]
	global_store_dwordx4 v[18:19], v[24:27], off offset:1024
	v_lshl_add_u64 v[108:109], v[116:117], 0, s[6:7]
	s_mov_b64 s[6:7], 0x1c00
	v_pk_mul_f32 v[26:27], v[92:93], v[0:1] op_sel_hi:[1,0]
	v_pk_mul_f32 v[24:25], v[90:91], v[0:1] op_sel_hi:[1,0]
	global_store_dwordx4 v[18:19], v[24:27], off offset:2048
	v_lshl_add_u64 v[104:105], v[116:117], 0, s[6:7]
	s_lshl_b32 s6, s0, 8
	v_pk_mul_f32 v[26:27], v[96:97], v[0:1] op_sel_hi:[1,0]
	v_pk_mul_f32 v[24:25], v[94:95], v[0:1] op_sel_hi:[1,0]
	v_or_b32_e32 v0, v20, v210
	v_lshlrev_b32_e32 v0, 2, v0
	s_add_i32 s5, s2, 0xfffffbe8
	v_subrev_u32_e32 v39, s6, v224
	global_store_dwordx4 v[18:19], v[24:27], off offset:3072
	s_barrier
	v_and_b32_e32 v141, 15, v146
	v_lshlrev_b32_e32 v141, 4, v141
	s_branch .LBB0_366
	.p2alignl 6, 3212836864

.LBB0_366:
	s_lshl_b32 s12, s4, 10
	s_sub_i32 s10, s23, s12
	s_cmp_lg_u32 s4, 3
	s_cselect_b64 s[6:7], -1, 0
	s_cmpk_gt_i32 s10, 0x315
	s_cselect_b64 s[8:9], -1, 0
	s_and_b64 s[8:9], s[6:7], s[8:9]
	s_cmp_gt_i32 s10, -1
	s_cselect_b64 s[10:11], -1, 0
	s_cmp_gt_i32 s12, s5
	s_cselect_b64 s[12:13], -1, 0
	s_and_b64 s[10:11], s[10:11], s[12:13]
	s_and_b64 s[6:7], s[10:11], s[6:7]
	v_cndmask_b32_e64 v18, 0, 1, s[6:7]
	s_and_b64 s[6:7], s[8:9], exec
	v_readfirstlane_b32 s6, v18
	s_cselect_b32 s10, 2, s6
	s_cmp_le_u32 s4, s16
	s_cselect_b64 s[8:9], -1, 0
	v_mov_b32_e32 v46, v42
	v_mov_b32_e32 v47, v43
	v_mov_b32_e32 v48, v44
	v_mov_b32_e32 v49, v45
	v_mov_b32_e32 v50, v40
	v_mov_b32_e32 v51, v39
	s_mov_b32 s11, 0
	s_branch .Lp2k
	.p2alignl 6, 3212836864
.Lp2k:
	s_andn2_b64 vcc, exec, s[8:9]
	s_cbranch_vccnz .Lp2k_inv
	s_cmp_lt_i32 s10, 1
	s_cbranch_scc1 .Lp2k_p0
	s_cmp_lg_u32 s10, 1
	s_cbranch_scc0 .Lp2k_p1
	ds_read_b128 v[56:59], v47
	ds_read_b128 v[64:67], v48
	ds_read_b128 v[60:63], v47 offset:2048
	ds_read_b128 v[68:71], v48 offset:2048
	ds_read_b32 v96, v193
	s_waitcnt lgkmcnt(1)
	v_mfma_f32_16x16x32_bf16 v[72:75], v[56:59], v[2:5], 0
	v_mfma_f32_16x16x32_bf16 v[76:79], v[60:63], v[2:5], 0
	v_mfma_f32_16x16x32_bf16 v[72:75], v[64:67], v[6:9], v[72:75]
	v_mfma_f32_16x16x32_bf16 v[76:79], v[68:71], v[6:9], v[76:79]
	v_mfma_f32_16x16x32_bf16 v[56:59], v[56:59], v[10:13], 0
	v_mfma_f32_16x16x32_bf16 v[60:63], v[60:63], v[10:13], 0
	v_mfma_f32_16x16x32_bf16 v[56:59], v[64:67], v[14:17], v[56:59]
	v_mfma_f32_16x16x32_bf16 v[60:63], v[68:71], v[14:17], v[60:63]
	s_waitcnt lgkmcnt(0)
	s_nop 7
	v_pk_fma_f32 v[80:81], v[72:73], s[36:37], v[96:97] op_sel_hi:[1,0,0]
	v_pk_fma_f32 v[82:83], v[74:75], s[36:37], v[96:97] op_sel_hi:[1,0,0]
	v_pk_fma_f32 v[84:85], v[76:77], s[36:37], v[96:97] op_sel_hi:[1,0,0]
	v_pk_fma_f32 v[86:87], v[78:79], s[36:37], v[96:97] op_sel_hi:[1,0,0]
	s_nop 0
	v_sub_f32_e32 v80, v80, v161
	v_sub_f32_e32 v81, v81, v161
	v_sub_f32_e32 v82, v82, v161
	v_sub_f32_e32 v83, v83, v161
	v_sub_f32_e32 v84, v84, v161
	v_sub_f32_e32 v85, v85, v161
	v_sub_f32_e32 v86, v86, v161
	v_sub_f32_e32 v87, v87, v161
	v_exp_f32_e32 v80, v80
	v_exp_f32_e32 v81, v81
	v_exp_f32_e32 v82, v82
	v_exp_f32_e32 v83, v83
	v_exp_f32_e32 v84, v84
	v_exp_f32_e32 v85, v85
	v_exp_f32_e32 v86, v86
	v_exp_f32_e32 v87, v87
	s_nop 0
	v_pk_fma_f32 v[88:89], v[56:57], s[36:37], v[96:97] op_sel_hi:[1,0,0]
	v_pk_fma_f32 v[90:91], v[58:59], s[36:37], v[96:97] op_sel_hi:[1,0,0]
	v_pk_fma_f32 v[92:93], v[60:61], s[36:37], v[96:97] op_sel_hi:[1,0,0]
	v_pk_fma_f32 v[94:95], v[62:63], s[36:37], v[96:97] op_sel_hi:[1,0,0]
	s_nop 0
	v_sub_f32_e32 v88, v88, v241
	v_sub_f32_e32 v89, v89, v241
	v_sub_f32_e32 v90, v90, v241
	v_sub_f32_e32 v91, v91, v241
	v_sub_f32_e32 v92, v92, v241
	v_sub_f32_e32 v93, v93, v241
	v_sub_f32_e32 v94, v94, v241
	v_sub_f32_e32 v95, v95, v241
	v_exp_f32_e32 v88, v88
	v_exp_f32_e32 v89, v89
	v_exp_f32_e32 v90, v90
	v_exp_f32_e32 v91, v91
	v_exp_f32_e32 v92, v92
	v_exp_f32_e32 v93, v93
	v_exp_f32_e32 v94, v94
	v_exp_f32_e32 v95, v95
	s_nop 0
	v_mov_b32_e32 v54, v81
	v_mov_b32_e32 v55, v83
	v_mov_b32_e32 v81, v82
	v_pk_mul_f32 v[54:55], v[34:35], v[54:55]
	s_nop 0
	v_pk_fma_f32 v[80:81], v[34:35], v[80:81], v[54:55]
	v_mov_b32_e32 v83, v55
	v_add_f32_e32 v72, v80, v81
	v_mov_b32_e32 v54, v85
	v_mov_b32_e32 v55, v87
	v_mov_b32_e32 v85, v86
	v_pk_mul_f32 v[54:55], v[34:35], v[54:55]
	s_nop 0
	v_pk_fma_f32 v[84:85], v[34:35], v[84:85], v[54:55]
	v_mov_b32_e32 v87, v55
	v_add_f32_e32 v73, v84, v85
	v_mov_b32_e32 v54, v89
	v_mov_b32_e32 v55, v91
	v_mov_b32_e32 v89, v90
	v_pk_mul_f32 v[54:55], v[36:37], v[54:55]
	s_nop 0
	v_pk_fma_f32 v[88:89], v[36:37], v[88:89], v[54:55]
	v_mov_b32_e32 v91, v55
	v_add_f32_e32 v74, v88, v89
	v_mov_b32_e32 v54, v93
	v_mov_b32_e32 v55, v95
	v_mov_b32_e32 v93, v94
	v_pk_mul_f32 v[54:55], v[36:37], v[54:55]
	s_nop 0
	v_pk_fma_f32 v[92:93], v[36:37], v[92:93], v[54:55]
	v_mov_b32_e32 v95, v55
	v_add_f32_e32 v75, v92, v93
	v_cndmask_b32_e64 v76, v83, v31, s[38:39]
	v_cndmask_b32_e64 v77, v87, v83, s[38:39]
	v_cndmask_b32_e64 v78, v91, v23, s[38:39]
	v_cndmask_b32_e64 v79, v95, v91, s[38:39]
	ds_bpermute_b32 v76, v0, v76
	ds_bpermute_b32 v77, v0, v77
	ds_bpermute_b32 v78, v0, v78
	ds_bpermute_b32 v79, v0, v79
	v_mov_b32_e32 v31, v87
	v_mov_b32_e32 v23, v95
	v_mov_b32_e32 v54, v49
	v_add_u32_e32 v55, 16, v49
	s_waitcnt lgkmcnt(0)
	v_add_f32_e32 v76, v72, v76
	v_add_f32_e32 v77, v73, v77
	v_add_f32_e32 v78, v74, v78
	v_add_f32_e32 v79, v75, v79
	v_xor_b32_e32 v54, v141, v54
	ds_write2st64_b32 v54, v76, v78 offset1:4
	v_xor_b32_e32 v55, v141, v55
	ds_write2st64_b32 v55, v77, v79 offset1:4
	ds_read_b128 v[56:59], v47 offset:4096
	ds_read_b128 v[64:67], v48 offset:4096
	ds_read_b128 v[60:63], v47 offset:6144
	ds_read_b128 v[68:71], v48 offset:6144
	ds_read_b32 v96, v193
	s_waitcnt lgkmcnt(1)
	v_mfma_f32_16x16x32_bf16 v[72:75], v[56:59], v[2:5], 0
	v_mfma_f32_16x16x32_bf16 v[76:79], v[60:63], v[2:5], 0
	v_mfma_f32_16x16x32_bf16 v[72:75], v[64:67], v[6:9], v[72:75]
	v_mfma_f32_16x16x32_bf16 v[76:79], v[68:71], v[6:9], v[76:79]
	v_mfma_f32_16x16x32_bf16 v[56:59], v[56:59], v[10:13], 0
	v_mfma_f32_16x16x32_bf16 v[60:63], v[60:63], v[10:13], 0
	v_mfma_f32_16x16x32_bf16 v[56:59], v[64:67], v[14:17], v[56:59]
	v_mfma_f32_16x16x32_bf16 v[60:63], v[68:71], v[14:17], v[60:63]
	s_waitcnt lgkmcnt(0)
	s_nop 7
	v_pk_fma_f32 v[80:81], v[72:73], s[36:37], v[96:97] op_sel_hi:[1,0,0]
	v_pk_fma_f32 v[82:83], v[74:75], s[36:37], v[96:97] op_sel_hi:[1,0,0]
	v_pk_fma_f32 v[84:85], v[76:77], s[36:37], v[96:97] op_sel_hi:[1,0,0]
	v_pk_fma_f32 v[86:87], v[78:79], s[36:37], v[96:97] op_sel_hi:[1,0,0]
	s_nop 0
	v_sub_f32_e32 v80, v80, v161
	v_sub_f32_e32 v81, v81, v161
	v_sub_f32_e32 v82, v82, v161
	v_sub_f32_e32 v83, v83, v161
	v_sub_f32_e32 v84, v84, v161
	v_sub_f32_e32 v85, v85, v161
	v_sub_f32_e32 v86, v86, v161
	v_sub_f32_e32 v87, v87, v161
	v_exp_f32_e32 v80, v80
	v_exp_f32_e32 v81, v81
	v_exp_f32_e32 v82, v82
	v_exp_f32_e32 v83, v83
	v_exp_f32_e32 v84, v84
	v_exp_f32_e32 v85, v85
	v_exp_f32_e32 v86, v86
	v_exp_f32_e32 v87, v87
	s_nop 0
	v_pk_fma_f32 v[88:89], v[56:57], s[36:37], v[96:97] op_sel_hi:[1,0,0]
	v_pk_fma_f32 v[90:91], v[58:59], s[36:37], v[96:97] op_sel_hi:[1,0,0]
	v_pk_fma_f32 v[92:93], v[60:61], s[36:37], v[96:97] op_sel_hi:[1,0,0]
	v_pk_fma_f32 v[94:95], v[62:63], s[36:37], v[96:97] op_sel_hi:[1,0,0]
	s_nop 0
	v_sub_f32_e32 v88, v88, v241
	v_sub_f32_e32 v89, v89, v241
	v_sub_f32_e32 v90, v90, v241
	v_sub_f32_e32 v91, v91, v241
	v_sub_f32_e32 v92, v92, v241
	v_sub_f32_e32 v93, v93, v241
	v_sub_f32_e32 v94, v94, v241
	v_sub_f32_e32 v95, v95, v241
	v_exp_f32_e32 v88, v88
	v_exp_f32_e32 v89, v89
	v_exp_f32_e32 v90, v90
	v_exp_f32_e32 v91, v91
	v_exp_f32_e32 v92, v92
	v_exp_f32_e32 v93, v93
	v_exp_f32_e32 v94, v94
	v_exp_f32_e32 v95, v95
	s_nop 0
	v_mov_b32_e32 v54, v81
	v_mov_b32_e32 v55, v83
	v_mov_b32_e32 v81, v82
	v_pk_mul_f32 v[54:55], v[34:35], v[54:55]
	s_nop 0
	v_pk_fma_f32 v[80:81], v[34:35], v[80:81], v[54:55]
	v_mov_b32_e32 v83, v55
	v_add_f32_e32 v72, v80, v81
	v_mov_b32_e32 v54, v85
	v_mov_b32_e32 v55, v87
	v_mov_b32_e32 v85, v86
	v_pk_mul_f32 v[54:55], v[34:35], v[54:55]
	s_nop 0
	v_pk_fma_f32 v[84:85], v[34:35], v[84:85], v[54:55]
	v_mov_b32_e32 v87, v55
	v_add_f32_e32 v73, v84, v85
	v_mov_b32_e32 v54, v89
	v_mov_b32_e32 v55, v91
	v_mov_b32_e32 v89, v90
	v_pk_mul_f32 v[54:55], v[36:37], v[54:55]
	s_nop 0
	v_pk_fma_f32 v[88:89], v[36:37], v[88:89], v[54:55]
	v_mov_b32_e32 v91, v55
	v_add_f32_e32 v74, v88, v89
	v_mov_b32_e32 v54, v93
	v_mov_b32_e32 v55, v95
	v_mov_b32_e32 v93, v94
	v_pk_mul_f32 v[54:55], v[36:37], v[54:55]
	s_nop 0
	v_pk_fma_f32 v[92:93], v[36:37], v[92:93], v[54:55]
	v_mov_b32_e32 v95, v55
	v_add_f32_e32 v75, v92, v93
	v_cndmask_b32_e64 v76, v83, v31, s[38:39]
	v_cndmask_b32_e64 v77, v87, v83, s[38:39]
	v_cndmask_b32_e64 v78, v91, v23, s[38:39]
	v_cndmask_b32_e64 v79, v95, v91, s[38:39]
	ds_bpermute_b32 v76, v0, v76
	ds_bpermute_b32 v77, v0, v77
	ds_bpermute_b32 v78, v0, v78
	ds_bpermute_b32 v79, v0, v79
	v_mov_b32_e32 v31, v87
	v_mov_b32_e32 v23, v95
	v_add_u32_e32 v54, 32, v49
	v_add_u32_e32 v55, 48, v49
	s_waitcnt lgkmcnt(0)
	v_add_f32_e32 v76, v72, v76
	v_add_f32_e32 v77, v73, v77
	v_add_f32_e32 v78, v74, v78
	v_add_f32_e32 v79, v75, v79
	v_xor_b32_e32 v54, v141, v54
	ds_write2st64_b32 v54, v76, v78 offset1:4
	v_xor_b32_e32 v55, v141, v55
	ds_write2st64_b32 v55, v77, v79 offset1:4
	s_branch .LBB0_365
	.p2alignl 6, 3212836864
.Lp2k_p1:
	ds_read_b128 v[56:59], v47
	ds_read_b128 v[64:67], v48
	ds_read_b128 v[60:63], v47 offset:2048
	ds_read_b128 v[68:71], v48 offset:2048
	ds_read2_b32 v[80:81], v50 offset1:16
	ds_read2_b32 v[82:83], v50 offset0:32 offset1:48
	v_add_u32_e32 v54, 0x400, v50
	ds_read2_b32 v[84:85], v54 offset1:16
	ds_read2_b32 v[86:87], v54 offset0:32 offset1:48
	ds_read2_b32 v[88:89], v51 offset1:16
	ds_read2_b32 v[90:91], v51 offset0:32 offset1:48
	v_add_u32_e32 v54, 0x400, v51
	ds_read2_b32 v[92:93], v54 offset1:16
	ds_read2_b32 v[94:95], v54 offset0:32 offset1:48
	s_waitcnt lgkmcnt(8)
	v_mfma_f32_16x16x32_bf16 v[72:75], v[56:59], v[2:5], 0
	v_mfma_f32_16x16x32_bf16 v[76:79], v[60:63], v[2:5], 0
	v_mfma_f32_16x16x32_bf16 v[72:75], v[64:67], v[6:9], v[72:75]
	v_mfma_f32_16x16x32_bf16 v[76:79], v[68:71], v[6:9], v[76:79]
	v_mfma_f32_16x16x32_bf16 v[56:59], v[56:59], v[10:13], 0
	v_mfma_f32_16x16x32_bf16 v[60:63], v[60:63], v[10:13], 0
	v_mfma_f32_16x16x32_bf16 v[56:59], v[64:67], v[14:17], v[56:59]
	v_mfma_f32_16x16x32_bf16 v[60:63], v[68:71], v[14:17], v[60:63]
	s_waitcnt lgkmcnt(0)
	s_nop 7
	v_pk_fma_f32 v[80:81], v[72:73], s[36:37], v[80:81] op_sel_hi:[1,0,1]
	v_pk_fma_f32 v[82:83], v[74:75], s[36:37], v[82:83] op_sel_hi:[1,0,1]
	v_pk_fma_f32 v[84:85], v[76:77], s[36:37], v[84:85] op_sel_hi:[1,0,1]
	v_pk_fma_f32 v[86:87], v[78:79], s[36:37], v[86:87] op_sel_hi:[1,0,1]
	s_nop 0
	v_sub_f32_e32 v80, v80, v161
	v_sub_f32_e32 v81, v81, v161
	v_sub_f32_e32 v82, v82, v161
	v_sub_f32_e32 v83, v83, v161
	v_sub_f32_e32 v84, v84, v161
	v_sub_f32_e32 v85, v85, v161
	v_sub_f32_e32 v86, v86, v161
	v_sub_f32_e32 v87, v87, v161
	v_exp_f32_e32 v80, v80
	v_exp_f32_e32 v81, v81
	v_exp_f32_e32 v82, v82
	v_exp_f32_e32 v83, v83
	v_exp_f32_e32 v84, v84
	v_exp_f32_e32 v85, v85
	v_exp_f32_e32 v86, v86
	v_exp_f32_e32 v87, v87
	s_nop 0
	v_pk_fma_f32 v[88:89], v[56:57], s[36:37], v[88:89] op_sel_hi:[1,0,1]
	v_pk_fma_f32 v[90:91], v[58:59], s[36:37], v[90:91] op_sel_hi:[1,0,1]
	v_pk_fma_f32 v[92:93], v[60:61], s[36:37], v[92:93] op_sel_hi:[1,0,1]
	v_pk_fma_f32 v[94:95], v[62:63], s[36:37], v[94:95] op_sel_hi:[1,0,1]
	s_nop 0
	v_sub_f32_e32 v88, v88, v241
	v_sub_f32_e32 v89, v89, v241
	v_sub_f32_e32 v90, v90, v241
	v_sub_f32_e32 v91, v91, v241
	v_sub_f32_e32 v92, v92, v241
	v_sub_f32_e32 v93, v93, v241
	v_sub_f32_e32 v94, v94, v241
	v_sub_f32_e32 v95, v95, v241
	v_exp_f32_e32 v88, v88
	v_exp_f32_e32 v89, v89
	v_exp_f32_e32 v90, v90
	v_exp_f32_e32 v91, v91
	v_exp_f32_e32 v92, v92
	v_exp_f32_e32 v93, v93
	v_exp_f32_e32 v94, v94
	v_exp_f32_e32 v95, v95
	s_nop 0
	v_mov_b32_e32 v54, v81
	v_mov_b32_e32 v55, v83
	v_mov_b32_e32 v81, v82
	v_pk_mul_f32 v[54:55], v[34:35], v[54:55]
	s_nop 0
	v_pk_fma_f32 v[80:81], v[34:35], v[80:81], v[54:55]
	v_mov_b32_e32 v83, v55
	v_add_f32_e32 v72, v80, v81
	v_mov_b32_e32 v54, v85
	v_mov_b32_e32 v55, v87
	v_mov_b32_e32 v85, v86
	v_pk_mul_f32 v[54:55], v[34:35], v[54:55]
	s_nop 0
	v_pk_fma_f32 v[84:85], v[34:35], v[84:85], v[54:55]
	v_mov_b32_e32 v87, v55
	v_add_f32_e32 v73, v84, v85
	v_mov_b32_e32 v54, v89
	v_mov_b32_e32 v55, v91
	v_mov_b32_e32 v89, v90
	v_pk_mul_f32 v[54:55], v[36:37], v[54:55]
	s_nop 0
	v_pk_fma_f32 v[88:89], v[36:37], v[88:89], v[54:55]
	v_mov_b32_e32 v91, v55
	v_add_f32_e32 v74, v88, v89
	v_mov_b32_e32 v54, v93
	v_mov_b32_e32 v55, v95
	v_mov_b32_e32 v93, v94
	v_pk_mul_f32 v[54:55], v[36:37], v[54:55]
	s_nop 0
	v_pk_fma_f32 v[92:93], v[36:37], v[92:93], v[54:55]
	v_mov_b32_e32 v95, v55
	v_add_f32_e32 v75, v92, v93
	v_cndmask_b32_e64 v76, v83, v31, s[38:39]
	v_cndmask_b32_e64 v77, v87, v83, s[38:39]
	v_cndmask_b32_e64 v78, v91, v23, s[38:39]
	v_cndmask_b32_e64 v79, v95, v91, s[38:39]
	ds_bpermute_b32 v76, v0, v76
	ds_bpermute_b32 v77, v0, v77
	ds_bpermute_b32 v78, v0, v78
	ds_bpermute_b32 v79, v0, v79
	v_mov_b32_e32 v31, v87
	v_mov_b32_e32 v23, v95
	v_mov_b32_e32 v54, v49
	v_add_u32_e32 v55, 16, v49
	s_waitcnt lgkmcnt(0)
	v_add_f32_e32 v76, v72, v76
	v_add_f32_e32 v77, v73, v77
	v_add_f32_e32 v78, v74, v78
	v_add_f32_e32 v79, v75, v79
	v_xor_b32_e32 v54, v141, v54
	ds_write2st64_b32 v54, v76, v78 offset1:4
	v_xor_b32_e32 v55, v141, v55
	ds_write2st64_b32 v55, v77, v79 offset1:4
	ds_read_b128 v[56:59], v47 offset:4096
	ds_read_b128 v[64:67], v48 offset:4096
	ds_read_b128 v[60:63], v47 offset:6144
	ds_read_b128 v[68:71], v48 offset:6144
	v_add_u32_e32 v54, 0x800, v50
	ds_read2_b32 v[80:81], v54 offset1:16
	ds_read2_b32 v[82:83], v54 offset0:32 offset1:48
	v_add_u32_e32 v54, 0xc00, v50
	ds_read2_b32 v[84:85], v54 offset1:16
	ds_read2_b32 v[86:87], v54 offset0:32 offset1:48
	v_add_u32_e32 v54, 0x800, v51
	ds_read2_b32 v[88:89], v54 offset1:16
	ds_read2_b32 v[90:91], v54 offset0:32 offset1:48
	v_add_u32_e32 v54, 0xc00, v51
	ds_read2_b32 v[92:93], v54 offset1:16
	ds_read2_b32 v[94:95], v54 offset0:32 offset1:48
	s_waitcnt lgkmcnt(8)
	v_mfma_f32_16x16x32_bf16 v[72:75], v[56:59], v[2:5], 0
	v_mfma_f32_16x16x32_bf16 v[76:79], v[60:63], v[2:5], 0
	v_mfma_f32_16x16x32_bf16 v[72:75], v[64:67], v[6:9], v[72:75]
	v_mfma_f32_16x16x32_bf16 v[76:79], v[68:71], v[6:9], v[76:79]
	v_mfma_f32_16x16x32_bf16 v[56:59], v[56:59], v[10:13], 0
	v_mfma_f32_16x16x32_bf16 v[60:63], v[60:63], v[10:13], 0
	v_mfma_f32_16x16x32_bf16 v[56:59], v[64:67], v[14:17], v[56:59]
	v_mfma_f32_16x16x32_bf16 v[60:63], v[68:71], v[14:17], v[60:63]
	s_waitcnt lgkmcnt(0)
	s_nop 7
	v_pk_fma_f32 v[80:81], v[72:73], s[36:37], v[80:81] op_sel_hi:[1,0,1]
	v_pk_fma_f32 v[82:83], v[74:75], s[36:37], v[82:83] op_sel_hi:[1,0,1]
	v_pk_fma_f32 v[84:85], v[76:77], s[36:37], v[84:85] op_sel_hi:[1,0,1]
	v_pk_fma_f32 v[86:87], v[78:79], s[36:37], v[86:87] op_sel_hi:[1,0,1]
	s_nop 0
	v_sub_f32_e32 v80, v80, v161
	v_sub_f32_e32 v81, v81, v161
	v_sub_f32_e32 v82, v82, v161
	v_sub_f32_e32 v83, v83, v161
	v_sub_f32_e32 v84, v84, v161
	v_sub_f32_e32 v85, v85, v161
	v_sub_f32_e32 v86, v86, v161
	v_sub_f32_e32 v87, v87, v161
	v_exp_f32_e32 v80, v80
	v_exp_f32_e32 v81, v81
	v_exp_f32_e32 v82, v82
	v_exp_f32_e32 v83, v83
	v_exp_f32_e32 v84, v84
	v_exp_f32_e32 v85, v85
	v_exp_f32_e32 v86, v86
	v_exp_f32_e32 v87, v87
	s_nop 0
	v_pk_fma_f32 v[88:89], v[56:57], s[36:37], v[88:89] op_sel_hi:[1,0,1]
	v_pk_fma_f32 v[90:91], v[58:59], s[36:37], v[90:91] op_sel_hi:[1,0,1]
	v_pk_fma_f32 v[92:93], v[60:61], s[36:37], v[92:93] op_sel_hi:[1,0,1]
	v_pk_fma_f32 v[94:95], v[62:63], s[36:37], v[94:95] op_sel_hi:[1,0,1]
	s_nop 0
	v_sub_f32_e32 v88, v88, v241
	v_sub_f32_e32 v89, v89, v241
	v_sub_f32_e32 v90, v90, v241
	v_sub_f32_e32 v91, v91, v241
	v_sub_f32_e32 v92, v92, v241
	v_sub_f32_e32 v93, v93, v241
	v_sub_f32_e32 v94, v94, v241
	v_sub_f32_e32 v95, v95, v241
	v_exp_f32_e32 v88, v88
	v_exp_f32_e32 v89, v89
	v_exp_f32_e32 v90, v90
	v_exp_f32_e32 v91, v91
	v_exp_f32_e32 v92, v92
	v_exp_f32_e32 v93, v93
	v_exp_f32_e32 v94, v94
	v_exp_f32_e32 v95, v95
	s_nop 0
	v_mov_b32_e32 v54, v81
	v_mov_b32_e32 v55, v83
	v_mov_b32_e32 v81, v82
	v_pk_mul_f32 v[54:55], v[34:35], v[54:55]
	s_nop 0
	v_pk_fma_f32 v[80:81], v[34:35], v[80:81], v[54:55]
	v_mov_b32_e32 v83, v55
	v_add_f32_e32 v72, v80, v81
	v_mov_b32_e32 v54, v85
	v_mov_b32_e32 v55, v87
	v_mov_b32_e32 v85, v86
	v_pk_mul_f32 v[54:55], v[34:35], v[54:55]
	s_nop 0
	v_pk_fma_f32 v[84:85], v[34:35], v[84:85], v[54:55]
	v_mov_b32_e32 v87, v55
	v_add_f32_e32 v73, v84, v85
	v_mov_b32_e32 v54, v89
	v_mov_b32_e32 v55, v91
	v_mov_b32_e32 v89, v90
	v_pk_mul_f32 v[54:55], v[36:37], v[54:55]
	s_nop 0
	v_pk_fma_f32 v[88:89], v[36:37], v[88:89], v[54:55]
	v_mov_b32_e32 v91, v55
	v_add_f32_e32 v74, v88, v89
	v_mov_b32_e32 v54, v93
	v_mov_b32_e32 v55, v95
	v_mov_b32_e32 v93, v94
	v_pk_mul_f32 v[54:55], v[36:37], v[54:55]
	s_nop 0
	v_pk_fma_f32 v[92:93], v[36:37], v[92:93], v[54:55]
	v_mov_b32_e32 v95, v55
	v_add_f32_e32 v75, v92, v93
	v_cndmask_b32_e64 v76, v83, v31, s[38:39]
	v_cndmask_b32_e64 v77, v87, v83, s[38:39]
	v_cndmask_b32_e64 v78, v91, v23, s[38:39]
	v_cndmask_b32_e64 v79, v95, v91, s[38:39]
	ds_bpermute_b32 v76, v0, v76
	ds_bpermute_b32 v77, v0, v77
	ds_bpermute_b32 v78, v0, v78
	ds_bpermute_b32 v79, v0, v79
	v_mov_b32_e32 v31, v87
	v_mov_b32_e32 v23, v95
	v_add_u32_e32 v54, 32, v49
	v_add_u32_e32 v55, 48, v49
	s_waitcnt lgkmcnt(0)
	v_add_f32_e32 v76, v72, v76
	v_add_f32_e32 v77, v73, v77
	v_add_f32_e32 v78, v74, v78
	v_add_f32_e32 v79, v75, v79
	v_xor_b32_e32 v54, v141, v54
	ds_write2st64_b32 v54, v76, v78 offset1:4
	v_xor_b32_e32 v55, v141, v55
	ds_write2st64_b32 v55, v77, v79 offset1:4
	s_branch .LBB0_365
	.p2alignl 6, 3212836864
.Lp2k_p0:
	ds_read_b128 v[56:59], v47
	ds_read_b128 v[64:67], v48
	ds_read_b128 v[60:63], v47 offset:2048
	ds_read_b128 v[68:71], v48 offset:2048
	v_subrev_u32_e32 v80, 31, v41
	v_subrev_u32_e32 v81, 47, v41
	v_subrev_u32_e32 v82, 63, v41
	v_subrev_u32_e32 v83, 79, v41
	v_min_u32_e32 v80, s31, v80
	v_min_u32_e32 v81, s31, v81
	v_min_u32_e32 v82, s31, v82
	v_min_u32_e32 v83, s31, v83
	v_xor_b32_e32 v80, s31, v80
	v_xor_b32_e32 v81, s31, v81
	v_xor_b32_e32 v82, s31, v82
	v_xor_b32_e32 v83, s31, v83
	v_lshl_add_u32 v80, v80, 2, v193
	v_lshl_add_u32 v81, v81, 2, v193
	v_lshl_add_u32 v82, v82, 2, v193
	v_lshl_add_u32 v83, v83, 2, v193
	v_subrev_u32_e32 v84, 287, v41
	v_subrev_u32_e32 v85, 303, v41
	v_subrev_u32_e32 v86, 319, v41
	v_subrev_u32_e32 v87, 335, v41
	v_min_u32_e32 v84, s31, v84
	v_min_u32_e32 v85, s31, v85
	v_min_u32_e32 v86, s31, v86
	v_min_u32_e32 v87, s31, v87
	v_xor_b32_e32 v84, s31, v84
	v_xor_b32_e32 v85, s31, v85
	v_xor_b32_e32 v86, s31, v86
	v_xor_b32_e32 v87, s31, v87
	v_lshl_add_u32 v84, v84, 2, v193
	v_lshl_add_u32 v85, v85, 2, v193
	v_lshl_add_u32 v86, v86, 2, v193
	v_lshl_add_u32 v87, v87, 2, v193
	v_subrev_u32_e32 v88, 27, v41
	v_subrev_u32_e32 v89, 43, v41
	v_subrev_u32_e32 v90, 59, v41
	v_subrev_u32_e32 v91, 75, v41
	v_min_u32_e32 v88, s31, v88
	v_min_u32_e32 v89, s31, v89
	v_min_u32_e32 v90, s31, v90
	v_min_u32_e32 v91, s31, v91
	v_xor_b32_e32 v88, s31, v88
	v_xor_b32_e32 v89, s31, v89
	v_xor_b32_e32 v90, s31, v90
	v_xor_b32_e32 v91, s31, v91
	v_lshl_add_u32 v88, v88, 2, v193
	v_lshl_add_u32 v89, v89, 2, v193
	v_lshl_add_u32 v90, v90, 2, v193
	v_lshl_add_u32 v91, v91, 2, v193
	v_subrev_u32_e32 v92, 283, v41
	v_subrev_u32_e32 v93, 299, v41
	v_subrev_u32_e32 v94, 315, v41
	v_subrev_u32_e32 v95, 331, v41
	v_min_u32_e32 v92, s31, v92
	v_min_u32_e32 v93, s31, v93
	v_min_u32_e32 v94, s31, v94
	v_min_u32_e32 v95, s31, v95
	v_xor_b32_e32 v92, s31, v92
	v_xor_b32_e32 v93, s31, v93
	v_xor_b32_e32 v94, s31, v94
	v_xor_b32_e32 v95, s31, v95
	v_lshl_add_u32 v92, v92, 2, v193
	v_lshl_add_u32 v93, v93, 2, v193
	v_lshl_add_u32 v94, v94, 2, v193
	v_lshl_add_u32 v95, v95, 2, v193
	ds_read_b32 v80, v80
	ds_read_b32 v81, v81
	ds_read_b32 v82, v82
	ds_read_b32 v83, v83
	ds_read_b32 v84, v84
	ds_read_b32 v85, v85
	ds_read_b32 v86, v86
	ds_read_b32 v87, v87
	s_waitcnt lgkmcnt(7)
	ds_read_b32 v88, v88
	ds_read_b32 v89, v89
	ds_read_b32 v90, v90
	ds_read_b32 v91, v91
	ds_read_b32 v92, v92
	ds_read_b32 v93, v93
	ds_read_b32 v94, v94
	ds_read_b32 v95, v95
	v_cmp_gt_u32_e64 s[12:13], s27, v46
	s_sub_i32 s98, s27, 16
	v_cmp_gt_u32_e64 s[6:7], s98, v46
	v_mfma_f32_16x16x32_bf16 v[72:75], v[56:59], v[2:5], 0
	v_mfma_f32_16x16x32_bf16 v[76:79], v[60:63], v[2:5], 0
	v_mfma_f32_16x16x32_bf16 v[72:75], v[64:67], v[6:9], v[72:75]
	v_mfma_f32_16x16x32_bf16 v[76:79], v[68:71], v[6:9], v[76:79]
	v_mfma_f32_16x16x32_bf16 v[56:59], v[56:59], v[10:13], 0
	v_mfma_f32_16x16x32_bf16 v[60:63], v[60:63], v[10:13], 0
	v_mfma_f32_16x16x32_bf16 v[56:59], v[64:67], v[14:17], v[56:59]
	v_mfma_f32_16x16x32_bf16 v[60:63], v[68:71], v[14:17], v[60:63]
	v_subrev_u32_e32 v96, 27, v41
	v_subrev_u32_e32 v97, 43, v41
	v_subrev_u32_e32 v98, 59, v41
	v_subrev_u32_e32 v99, 75, v41
	v_subrev_u32_e32 v100, 283, v41
	v_subrev_u32_e32 v101, 299, v41
	v_subrev_u32_e32 v54, 315, v41
	v_subrev_u32_e32 v55, 331, v41
	v_subrev_u32_e32 v64, 31, v41
	v_subrev_u32_e32 v65, 47, v41
	v_subrev_u32_e32 v66, 63, v41
	v_subrev_u32_e32 v67, 79, v41
	v_subrev_u32_e32 v68, 287, v41
	v_subrev_u32_e32 v69, 303, v41
	v_subrev_u32_e32 v70, 319, v41
	v_subrev_u32_e32 v71, 335, v41
	v_ashrrev_i32_e32 v96, 31, v96
	v_ashrrev_i32_e32 v97, 31, v97
	v_ashrrev_i32_e32 v98, 31, v98
	v_ashrrev_i32_e32 v99, 31, v99
	v_ashrrev_i32_e32 v100, 31, v100
	v_ashrrev_i32_e32 v101, 31, v101
	v_ashrrev_i32_e32 v54, 31, v54
	v_ashrrev_i32_e32 v55, 31, v55
	v_ashrrev_i32_e32 v64, 31, v64
	v_ashrrev_i32_e32 v65, 31, v65
	v_ashrrev_i32_e32 v66, 31, v66
	v_ashrrev_i32_e32 v67, 31, v67
	v_ashrrev_i32_e32 v68, 31, v68
	v_ashrrev_i32_e32 v69, 31, v69
	v_ashrrev_i32_e32 v70, 31, v70
	v_ashrrev_i32_e32 v71, 31, v71
	s_waitcnt lgkmcnt(0)
	v_fmac_f32_e32 v80, 0x3e38aa3b, v72
	v_fmac_f32_e32 v81, 0x3e38aa3b, v73
	v_fmac_f32_e32 v82, 0x3e38aa3b, v74
	v_fmac_f32_e32 v83, 0x3e38aa3b, v75
	v_fmac_f32_e32 v84, 0x3e38aa3b, v76
	v_fmac_f32_e32 v85, 0x3e38aa3b, v77
	v_fmac_f32_e32 v86, 0x3e38aa3b, v78
	v_fmac_f32_e32 v87, 0x3e38aa3b, v79
	v_sub_f32_e32 v80, v80, v161
	v_sub_f32_e32 v81, v81, v161
	v_sub_f32_e32 v82, v82, v161
	v_sub_f32_e32 v83, v83, v161
	v_sub_f32_e32 v84, v84, v161
	v_sub_f32_e32 v85, v85, v161
	v_sub_f32_e32 v86, v86, v161
	v_sub_f32_e32 v87, v87, v161
	v_exp_f32_e32 v80, v80
	v_exp_f32_e32 v81, v81
	v_exp_f32_e32 v82, v82
	v_exp_f32_e32 v83, v83
	v_exp_f32_e32 v84, v84
	v_exp_f32_e32 v85, v85
	v_exp_f32_e32 v86, v86
	v_exp_f32_e32 v87, v87
	s_nop 0
	v_fmac_f32_e32 v88, 0x3e38aa3b, v56
	v_fmac_f32_e32 v89, 0x3e38aa3b, v57
	v_fmac_f32_e32 v90, 0x3e38aa3b, v58
	v_fmac_f32_e32 v91, 0x3e38aa3b, v59
	v_fmac_f32_e32 v92, 0x3e38aa3b, v60
	v_fmac_f32_e32 v93, 0x3e38aa3b, v61
	v_fmac_f32_e32 v94, 0x3e38aa3b, v62
	v_fmac_f32_e32 v95, 0x3e38aa3b, v63
	v_sub_f32_e32 v88, v88, v241
	v_sub_f32_e32 v89, v89, v241
	v_sub_f32_e32 v90, v90, v241
	v_sub_f32_e32 v91, v91, v241
	v_sub_f32_e32 v92, v92, v241
	v_sub_f32_e32 v93, v93, v241
	v_sub_f32_e32 v94, v94, v241
	v_sub_f32_e32 v95, v95, v241
	v_exp_f32_e32 v88, v88
	v_exp_f32_e32 v89, v89
	v_exp_f32_e32 v90, v90
	v_exp_f32_e32 v91, v91
	v_exp_f32_e32 v92, v92
	v_exp_f32_e32 v93, v93
	v_exp_f32_e32 v94, v94
	v_exp_f32_e32 v95, v95
	s_nop 0
	v_mul_f32_e32 v80, v34, v80
	v_mul_f32_e32 v81, v34, v81
	v_mul_f32_e32 v82, v34, v82
	v_mul_f32_e32 v83, v34, v83
	v_bfi_b32 v80, v64, 0, v80
	v_bfi_b32 v81, v65, 0, v81
	v_bfi_b32 v82, v66, 0, v82
	v_bfi_b32 v83, v67, 0, v83
	v_cndmask_b32_e64 v83, 0, v83, s[12:13]
	v_add_f32_e32 v72, v80, v81
	v_add_f32_e32 v72, v72, v82
	v_add_f32_e32 v72, v72, v83
	v_mul_f32_e32 v84, v34, v84
	v_mul_f32_e32 v85, v34, v85
	v_mul_f32_e32 v86, v34, v86
	v_mul_f32_e32 v87, v34, v87
	v_bfi_b32 v84, v68, 0, v84
	v_bfi_b32 v85, v69, 0, v85
	v_bfi_b32 v86, v70, 0, v86
	v_bfi_b32 v87, v71, 0, v87
	v_cndmask_b32_e64 v87, 0, v87, s[6:7]
	v_add_f32_e32 v73, v84, v85
	v_add_f32_e32 v73, v73, v86
	v_add_f32_e32 v73, v73, v87
	v_mul_f32_e32 v88, v36, v88
	v_mul_f32_e32 v89, v36, v89
	v_mul_f32_e32 v90, v36, v90
	v_mul_f32_e32 v91, v36, v91
	v_bfi_b32 v88, v96, 0, v88
	v_bfi_b32 v89, v97, 0, v89
	v_bfi_b32 v90, v98, 0, v90
	v_bfi_b32 v91, v99, 0, v91
	v_cndmask_b32_e64 v91, 0, v91, s[12:13]
	v_add_f32_e32 v74, v88, v89
	v_add_f32_e32 v74, v74, v90
	v_add_f32_e32 v74, v74, v91
	v_mul_f32_e32 v92, v36, v92
	v_mul_f32_e32 v93, v36, v93
	v_mul_f32_e32 v94, v36, v94
	v_mul_f32_e32 v95, v36, v95
	v_bfi_b32 v92, v100, 0, v92
	v_bfi_b32 v93, v101, 0, v93
	v_bfi_b32 v94, v54, 0, v94
	v_bfi_b32 v95, v55, 0, v95
	v_cndmask_b32_e64 v95, 0, v95, s[6:7]
	v_add_f32_e32 v75, v92, v93
	v_add_f32_e32 v75, v75, v94
	v_add_f32_e32 v75, v75, v95
	v_cndmask_b32_e64 v76, v83, v31, s[38:39]
	v_cndmask_b32_e64 v77, v87, v83, s[38:39]
	v_cndmask_b32_e64 v78, v91, v23, s[38:39]
	v_cndmask_b32_e64 v79, v95, v91, s[38:39]
	ds_bpermute_b32 v76, v0, v76
	ds_bpermute_b32 v77, v0, v77
	ds_bpermute_b32 v78, v0, v78
	ds_bpermute_b32 v79, v0, v79
	v_mov_b32_e32 v31, v87
	v_mov_b32_e32 v23, v95
	v_mov_b32_e32 v54, v49
	v_add_u32_e32 v55, 16, v49
	s_waitcnt lgkmcnt(0)
	v_add_f32_e32 v76, v72, v76
	v_add_f32_e32 v77, v73, v77
	v_add_f32_e32 v78, v74, v78
	v_add_f32_e32 v79, v75, v79
	v_xor_b32_e32 v54, v141, v54
	ds_write2st64_b32 v54, v76, v78 offset1:4
	v_xor_b32_e32 v55, v141, v55
	ds_write2st64_b32 v55, v77, v79 offset1:4
	ds_read_b128 v[56:59], v47 offset:4096
	ds_read_b128 v[64:67], v48 offset:4096
	ds_read_b128 v[60:63], v47 offset:6144
	ds_read_b128 v[68:71], v48 offset:6144
	v_subrev_u32_e32 v80, 543, v41
	v_subrev_u32_e32 v81, 559, v41
	v_subrev_u32_e32 v82, 575, v41
	v_subrev_u32_e32 v83, 591, v41
	v_min_u32_e32 v80, s31, v80
	v_min_u32_e32 v81, s31, v81
	v_min_u32_e32 v82, s31, v82
	v_min_u32_e32 v83, s31, v83
	v_xor_b32_e32 v80, s31, v80
	v_xor_b32_e32 v81, s31, v81
	v_xor_b32_e32 v82, s31, v82
	v_xor_b32_e32 v83, s31, v83
	v_lshl_add_u32 v80, v80, 2, v193
	v_lshl_add_u32 v81, v81, 2, v193
	v_lshl_add_u32 v82, v82, 2, v193
	v_lshl_add_u32 v83, v83, 2, v193
	v_subrev_u32_e32 v84, 799, v41
	v_subrev_u32_e32 v85, 815, v41
	v_subrev_u32_e32 v86, 831, v41
	v_subrev_u32_e32 v87, 847, v41
	v_min_u32_e32 v84, s31, v84
	v_min_u32_e32 v85, s31, v85
	v_min_u32_e32 v86, s31, v86
	v_min_u32_e32 v87, s31, v87
	v_xor_b32_e32 v84, s31, v84
	v_xor_b32_e32 v85, s31, v85
	v_xor_b32_e32 v86, s31, v86
	v_xor_b32_e32 v87, s31, v87
	v_lshl_add_u32 v84, v84, 2, v193
	v_lshl_add_u32 v85, v85, 2, v193
	v_lshl_add_u32 v86, v86, 2, v193
	v_lshl_add_u32 v87, v87, 2, v193
	v_subrev_u32_e32 v88, 539, v41
	v_subrev_u32_e32 v89, 555, v41
	v_subrev_u32_e32 v90, 571, v41
	v_subrev_u32_e32 v91, 587, v41
	v_min_u32_e32 v88, s31, v88
	v_min_u32_e32 v89, s31, v89
	v_min_u32_e32 v90, s31, v90
	v_min_u32_e32 v91, s31, v91
	v_xor_b32_e32 v88, s31, v88
	v_xor_b32_e32 v89, s31, v89
	v_xor_b32_e32 v90, s31, v90
	v_xor_b32_e32 v91, s31, v91
	v_lshl_add_u32 v88, v88, 2, v193
	v_lshl_add_u32 v89, v89, 2, v193
	v_lshl_add_u32 v90, v90, 2, v193
	v_lshl_add_u32 v91, v91, 2, v193
	v_subrev_u32_e32 v92, 795, v41
	v_subrev_u32_e32 v93, 811, v41
	v_subrev_u32_e32 v94, 827, v41
	v_subrev_u32_e32 v95, 843, v41
	v_min_u32_e32 v92, s31, v92
	v_min_u32_e32 v93, s31, v93
	v_min_u32_e32 v94, s31, v94
	v_min_u32_e32 v95, s31, v95
	v_xor_b32_e32 v92, s31, v92
	v_xor_b32_e32 v93, s31, v93
	v_xor_b32_e32 v94, s31, v94
	v_xor_b32_e32 v95, s31, v95
	v_lshl_add_u32 v92, v92, 2, v193
	v_lshl_add_u32 v93, v93, 2, v193
	v_lshl_add_u32 v94, v94, 2, v193
	v_lshl_add_u32 v95, v95, 2, v193
	ds_read_b32 v80, v80
	ds_read_b32 v81, v81
	ds_read_b32 v82, v82
	ds_read_b32 v83, v83
	ds_read_b32 v84, v84
	ds_read_b32 v85, v85
	ds_read_b32 v86, v86
	ds_read_b32 v87, v87
	s_waitcnt lgkmcnt(7)
	ds_read_b32 v88, v88
	ds_read_b32 v89, v89
	ds_read_b32 v90, v90
	ds_read_b32 v91, v91
	ds_read_b32 v92, v92
	ds_read_b32 v93, v93
	ds_read_b32 v94, v94
	ds_read_b32 v95, v95
	s_sub_i32 s98, s27, 32
	v_cmp_gt_u32_e64 s[12:13], s98, v46
	s_sub_i32 s98, s27, 48
	v_cmp_gt_u32_e64 s[6:7], s98, v46
	v_mfma_f32_16x16x32_bf16 v[72:75], v[56:59], v[2:5], 0
	v_mfma_f32_16x16x32_bf16 v[76:79], v[60:63], v[2:5], 0
	v_mfma_f32_16x16x32_bf16 v[72:75], v[64:67], v[6:9], v[72:75]
	v_mfma_f32_16x16x32_bf16 v[76:79], v[68:71], v[6:9], v[76:79]
	v_mfma_f32_16x16x32_bf16 v[56:59], v[56:59], v[10:13], 0
	v_mfma_f32_16x16x32_bf16 v[60:63], v[60:63], v[10:13], 0
	v_mfma_f32_16x16x32_bf16 v[56:59], v[64:67], v[14:17], v[56:59]
	v_mfma_f32_16x16x32_bf16 v[60:63], v[68:71], v[14:17], v[60:63]
	v_subrev_u32_e32 v96, 539, v41
	v_subrev_u32_e32 v97, 555, v41
	v_subrev_u32_e32 v98, 571, v41
	v_subrev_u32_e32 v99, 587, v41
	v_subrev_u32_e32 v100, 795, v41
	v_subrev_u32_e32 v101, 811, v41
	v_subrev_u32_e32 v54, 827, v41
	v_subrev_u32_e32 v55, 843, v41
	v_subrev_u32_e32 v64, 543, v41
	v_subrev_u32_e32 v65, 559, v41
	v_subrev_u32_e32 v66, 575, v41
	v_subrev_u32_e32 v67, 591, v41
	v_subrev_u32_e32 v68, 799, v41
	v_subrev_u32_e32 v69, 815, v41
	v_subrev_u32_e32 v70, 831, v41
	v_subrev_u32_e32 v71, 847, v41
	v_ashrrev_i32_e32 v96, 31, v96
	v_ashrrev_i32_e32 v97, 31, v97
	v_ashrrev_i32_e32 v98, 31, v98
	v_ashrrev_i32_e32 v99, 31, v99
	v_ashrrev_i32_e32 v100, 31, v100
	v_ashrrev_i32_e32 v101, 31, v101
	v_ashrrev_i32_e32 v54, 31, v54
	v_ashrrev_i32_e32 v55, 31, v55
	v_ashrrev_i32_e32 v64, 31, v64
	v_ashrrev_i32_e32 v65, 31, v65
	v_ashrrev_i32_e32 v66, 31, v66
	v_ashrrev_i32_e32 v67, 31, v67
	v_ashrrev_i32_e32 v68, 31, v68
	v_ashrrev_i32_e32 v69, 31, v69
	v_ashrrev_i32_e32 v70, 31, v70
	v_ashrrev_i32_e32 v71, 31, v71
	s_waitcnt lgkmcnt(0)
	v_fmac_f32_e32 v80, 0x3e38aa3b, v72
	v_fmac_f32_e32 v81, 0x3e38aa3b, v73
	v_fmac_f32_e32 v82, 0x3e38aa3b, v74
	v_fmac_f32_e32 v83, 0x3e38aa3b, v75
	v_fmac_f32_e32 v84, 0x3e38aa3b, v76
	v_fmac_f32_e32 v85, 0x3e38aa3b, v77
	v_fmac_f32_e32 v86, 0x3e38aa3b, v78
	v_fmac_f32_e32 v87, 0x3e38aa3b, v79
	v_sub_f32_e32 v80, v80, v161
	v_sub_f32_e32 v81, v81, v161
	v_sub_f32_e32 v82, v82, v161
	v_sub_f32_e32 v83, v83, v161
	v_sub_f32_e32 v84, v84, v161
	v_sub_f32_e32 v85, v85, v161
	v_sub_f32_e32 v86, v86, v161
	v_sub_f32_e32 v87, v87, v161
	v_exp_f32_e32 v80, v80
	v_exp_f32_e32 v81, v81
	v_exp_f32_e32 v82, v82
	v_exp_f32_e32 v83, v83
	v_exp_f32_e32 v84, v84
	v_exp_f32_e32 v85, v85
	v_exp_f32_e32 v86, v86
	v_exp_f32_e32 v87, v87
	s_nop 0
	v_fmac_f32_e32 v88, 0x3e38aa3b, v56
	v_fmac_f32_e32 v89, 0x3e38aa3b, v57
	v_fmac_f32_e32 v90, 0x3e38aa3b, v58
	v_fmac_f32_e32 v91, 0x3e38aa3b, v59
	v_fmac_f32_e32 v92, 0x3e38aa3b, v60
	v_fmac_f32_e32 v93, 0x3e38aa3b, v61
	v_fmac_f32_e32 v94, 0x3e38aa3b, v62
	v_fmac_f32_e32 v95, 0x3e38aa3b, v63
	v_sub_f32_e32 v88, v88, v241
	v_sub_f32_e32 v89, v89, v241
	v_sub_f32_e32 v90, v90, v241
	v_sub_f32_e32 v91, v91, v241
	v_sub_f32_e32 v92, v92, v241
	v_sub_f32_e32 v93, v93, v241
	v_sub_f32_e32 v94, v94, v241
	v_sub_f32_e32 v95, v95, v241
	v_exp_f32_e32 v88, v88
	v_exp_f32_e32 v89, v89
	v_exp_f32_e32 v90, v90
	v_exp_f32_e32 v91, v91
	v_exp_f32_e32 v92, v92
	v_exp_f32_e32 v93, v93
	v_exp_f32_e32 v94, v94
	v_exp_f32_e32 v95, v95
	s_nop 0
	v_mul_f32_e32 v80, v34, v80
	v_mul_f32_e32 v81, v34, v81
	v_mul_f32_e32 v82, v34, v82
	v_mul_f32_e32 v83, v34, v83
	v_bfi_b32 v80, v64, 0, v80
	v_bfi_b32 v81, v65, 0, v81
	v_bfi_b32 v82, v66, 0, v82
	v_bfi_b32 v83, v67, 0, v83
	v_cndmask_b32_e64 v83, 0, v83, s[12:13]
	v_add_f32_e32 v72, v80, v81
	v_add_f32_e32 v72, v72, v82
	v_add_f32_e32 v72, v72, v83
	v_mul_f32_e32 v84, v34, v84
	v_mul_f32_e32 v85, v34, v85
	v_mul_f32_e32 v86, v34, v86
	v_mul_f32_e32 v87, v34, v87
	v_bfi_b32 v84, v68, 0, v84
	v_bfi_b32 v85, v69, 0, v85
	v_bfi_b32 v86, v70, 0, v86
	v_bfi_b32 v87, v71, 0, v87
	v_cndmask_b32_e64 v87, 0, v87, s[6:7]
	v_add_f32_e32 v73, v84, v85
	v_add_f32_e32 v73, v73, v86
	v_add_f32_e32 v73, v73, v87
	v_mul_f32_e32 v88, v36, v88
	v_mul_f32_e32 v89, v36, v89
	v_mul_f32_e32 v90, v36, v90
	v_mul_f32_e32 v91, v36, v91
	v_bfi_b32 v88, v96, 0, v88
	v_bfi_b32 v89, v97, 0, v89
	v_bfi_b32 v90, v98, 0, v90
	v_bfi_b32 v91, v99, 0, v91
	v_cndmask_b32_e64 v91, 0, v91, s[12:13]
	v_add_f32_e32 v74, v88, v89
	v_add_f32_e32 v74, v74, v90
	v_add_f32_e32 v74, v74, v91
	v_mul_f32_e32 v92, v36, v92
	v_mul_f32_e32 v93, v36, v93
	v_mul_f32_e32 v94, v36, v94
	v_mul_f32_e32 v95, v36, v95
	v_bfi_b32 v92, v100, 0, v92
	v_bfi_b32 v93, v101, 0, v93
	v_bfi_b32 v94, v54, 0, v94
	v_bfi_b32 v95, v55, 0, v95
	v_cndmask_b32_e64 v95, 0, v95, s[6:7]
	v_add_f32_e32 v75, v92, v93
	v_add_f32_e32 v75, v75, v94
	v_add_f32_e32 v75, v75, v95
	v_cndmask_b32_e64 v76, v83, v31, s[38:39]
	v_cndmask_b32_e64 v77, v87, v83, s[38:39]
	v_cndmask_b32_e64 v78, v91, v23, s[38:39]
	v_cndmask_b32_e64 v79, v95, v91, s[38:39]
	ds_bpermute_b32 v76, v0, v76
	ds_bpermute_b32 v77, v0, v77
	ds_bpermute_b32 v78, v0, v78
	ds_bpermute_b32 v79, v0, v79
	v_mov_b32_e32 v31, v87
	v_mov_b32_e32 v23, v95
	v_add_u32_e32 v54, 32, v49
	v_add_u32_e32 v55, 48, v49
	s_waitcnt lgkmcnt(0)
	v_add_f32_e32 v76, v72, v76
	v_add_f32_e32 v77, v73, v77
	v_add_f32_e32 v78, v74, v78
	v_add_f32_e32 v79, v75, v79
	v_xor_b32_e32 v54, v141, v54
	ds_write2st64_b32 v54, v76, v78 offset1:4
	v_xor_b32_e32 v55, v141, v55
	ds_write2st64_b32 v55, v77, v79 offset1:4
	s_branch .LBB0_365
	.p2alignl 6, 3212836864
.Lp2k_inv:
	v_cndmask_b32_e64 v72, 0, v31, s[38:39]
	v_cndmask_b32_e64 v73, 0, v23, s[38:39]
	ds_bpermute_b32 v72, v0, v72
	ds_bpermute_b32 v73, v0, v73
	v_mov_b32_e32 v74, 0
	v_mov_b32_e32 v31, 0
	v_mov_b32_e32 v23, 0
	v_add_u32_e32 v54, 16, v49
	v_add_u32_e32 v55, 32, v49
	v_add_u32_e32 v56, 48, v49
	s_waitcnt lgkmcnt(0)
	v_add_f32_e32 v72, 0, v72
	v_add_f32_e32 v73, 0, v73
	v_xor_b32_e32 v57, v141, v49
	ds_write2st64_b32 v57, v72, v73 offset1:4
	v_xor_b32_e32 v54, v141, v54
	ds_write2st64_b32 v54, v74, v74 offset1:4
	v_xor_b32_e32 v55, v141, v55
	ds_write2st64_b32 v55, v74, v74 offset1:4
	v_xor_b32_e32 v56, v141, v56
	ds_write2st64_b32 v56, v74, v74 offset1:4
	s_branch .LBB0_365
	.p2alignl 6, 3212836864
.LBB0_402:
	v_cmp_eq_u32_e32 vcc, s0, v190
	s_add_i32 s6, s0, -1
	s_or_b64 s[4:5], s[40:41], vcc
	v_cmp_eq_u32_e32 vcc, s6, v190
	s_or_b64 vcc, s[4:5], vcc
	v_cmp_lt_u32_e64 s[42:43], s0, v190
	v_cmp_ge_u32_e64 s[8:9], s0, v190
	s_mov_b32 s0, 0
	v_mov_b32_e32 v0, v229
	s_waitcnt lgkmcnt(0)
	s_barrier
	s_branch .LBB0_404
	.p2alignl 6, 3212836864

.LBB0_406:
	s_or_b64 exec, exec, s[10:11]
	v_cndmask_b32_e64 v18, 0, 1, s[22:23]
	v_cmp_ne_u32_e64 s[10:11], 0, v18
	s_and_saveexec_b64 s[6:7], s[40:41]
	s_cbranch_execz .LBB0_403
	s_add_i32 s4, s37, s0
	v_mov_b32_e32 v18, s4
	v_mov_b64_e32 v[20:21], s[10:11]
	ds_write_b64 v18, v[20:21]
	s_branch .LBB0_403
	.p2alignl 6, 3212836864

.LBB0_417:
	s_mov_b32 s13, 0
	s_mov_b64 s[20:21], -1
	s_branch .LBB0_419
	.p2alignl 6, 3212836864

.Lp0_cb1:
	v_add_u32_e32 v88, 0xfec, v0
	ds_read_b128 v[64:67], v62 offset:16384
	ds_read_b128 v[68:71], v62 offset:18432
	ds_read_b128 v[72:75], v89 offset:16384
	ds_read_b128 v[76:79], v89 offset:18432
	ds_read2_b32 v[90:91], v88 offset1:1
	ds_read2_b32 v[92:93], v88 offset0:2 offset1:3
	ds_read2_b32 v[94:95], v88 offset0:16 offset1:17
	ds_read2_b32 v[96:97], v88 offset0:18 offset1:19
	ds_read2_b32 v[98:99], v88 offset0:32 offset1:33
	ds_read2_b32 v[100:101], v88 offset0:34 offset1:35
	ds_read2_b32 v[154:155], v88 offset0:48 offset1:49
	ds_read2_b32 v[156:157], v88 offset0:50 offset1:51
	s_waitcnt lgkmcnt(8)
	s_setprio 1
	v_mfma_f32_16x16x32_bf16 v[64:67], v[64:67], v[10:13], 0
	v_mfma_f32_16x16x32_bf16 v[68:71], v[68:71], v[10:13], 0
	v_mfma_f32_16x16x32_bf16 v[64:67], v[72:75], v[14:17], v[64:67]
	ds_read_b128 v[72:75], v62 offset:20480
	v_mfma_f32_16x16x32_bf16 v[68:71], v[76:79], v[14:17], v[68:71]
	ds_read_b128 v[76:79], v89 offset:20480
	ds_read_b128 v[80:83], v62 offset:22528
	ds_read_b128 v[84:87], v89 offset:22528
	s_waitcnt lgkmcnt(0)
	v_mfma_f32_16x16x32_bf16 v[72:75], v[72:75], v[10:13], 0
	v_mfma_f32_16x16x32_bf16 v[80:83], v[80:83], v[10:13], 0
	v_mfma_f32_16x16x32_bf16 v[72:75], v[76:79], v[14:17], v[72:75]
	v_mfma_f32_16x16x32_bf16 v[80:83], v[84:87], v[14:17], v[80:83]
	s_setprio 0
	v_pk_fma_f32 v[64:65], v[64:65], s[36:37], v[90:91] op_sel_hi:[1,0,1]
	v_pk_fma_f32 v[66:67], v[66:67], s[36:37], v[92:93] op_sel_hi:[1,0,1]
	v_pk_fma_f32 v[68:69], v[68:69], s[36:37], v[94:95] op_sel_hi:[1,0,1]
	v_pk_fma_f32 v[70:71], v[70:71], s[36:37], v[96:97] op_sel_hi:[1,0,1]
	s_nop 3
	v_pk_fma_f32 v[72:73], v[72:73], s[36:37], v[98:99] op_sel_hi:[1,0,1]
	v_pk_fma_f32 v[74:75], v[74:75], s[36:37], v[100:101] op_sel_hi:[1,0,1]
	v_pk_fma_f32 v[80:81], v[80:81], s[36:37], v[154:155] op_sel_hi:[1,0,1]
	v_pk_fma_f32 v[82:83], v[82:83], s[36:37], v[156:157] op_sel_hi:[1,0,1]
	v_or_b32_e32 v79, s14, v197
	v_sub_u32_e32 v88, v142, v79
	v_cmp_le_i32_e64 s[6:7], 0, v88
	v_cmp_le_i32_e64 s[18:19], 1, v88
	v_cmp_le_i32_e64 s[98:99], 2, v88
	v_cmp_le_i32_e64 s[100:101], 3, v88
	v_cndmask_b32_e64 v64, v148, v64, s[6:7]
	v_cndmask_b32_e64 v65, v148, v65, s[18:19]
	v_cndmask_b32_e64 v66, v148, v66, s[98:99]
	v_cndmask_b32_e64 v67, v148, v67, s[100:101]
	v_cmp_le_i32_e64 s[6:7], 16, v88
	v_cmp_le_i32_e64 s[18:19], 17, v88
	v_cmp_le_i32_e64 s[98:99], 18, v88
	v_cmp_le_i32_e64 s[100:101], 19, v88
	v_cndmask_b32_e64 v68, v148, v68, s[6:7]
	v_cndmask_b32_e64 v69, v148, v69, s[18:19]
	v_cndmask_b32_e64 v70, v148, v70, s[98:99]
	v_cndmask_b32_e64 v71, v148, v71, s[100:101]
	v_cmp_le_i32_e64 s[6:7], 32, v88
	v_cmp_le_i32_e64 s[18:19], 33, v88
	v_cmp_le_i32_e64 s[98:99], 34, v88
	v_cmp_le_i32_e64 s[100:101], 35, v88
	v_cndmask_b32_e64 v72, v148, v72, s[6:7]
	v_cndmask_b32_e64 v73, v148, v73, s[18:19]
	v_cndmask_b32_e64 v74, v148, v74, s[98:99]
	v_cndmask_b32_e64 v75, v148, v75, s[100:101]
	v_cmp_le_i32_e64 s[6:7], 48, v88
	v_cmp_le_i32_e64 s[18:19], 49, v88
	v_cmp_le_i32_e64 s[98:99], 50, v88
	v_cmp_le_i32_e64 s[100:101], 51, v88
	v_cndmask_b32_e64 v80, v148, v80, s[6:7]
	v_cndmask_b32_e64 v81, v148, v81, s[18:19]
	v_cndmask_b32_e64 v82, v148, v82, s[98:99]
	v_cndmask_b32_e64 v83, v148, v83, s[100:101]
	v_max3_f32 v76, v64, v65, v66
	v_max3_f32 v76, v76, v67, v68
	v_max3_f32 v76, v76, v69, v70
	v_max3_f32 v76, v76, v71, v72
	v_max3_f32 v76, v76, v73, v74
	v_max3_f32 v76, v76, v75, v80
	v_max3_f32 v76, v76, v81, v82
	v_max3_f32 v76, v76, v83, s29
	v_mov_b32_e32 v77, v76
	s_nop 1
	v_permlane16_swap_b32_e32 v76, v77
	v_max_f32_e32 v76, v76, v77
	v_mov_b32_e32 v77, v76
	s_nop 1
	v_permlane32_swap_b32_e32 v76, v77
	v_max_f32_e32 v76, v76, v77
	v_cndmask_b32_e64 v76, v148, v76, s[42:43]
	v_max_f32_e32 v77, v161, v76
	v_sub_f32_e32 v0, v161, v77
	v_exp_f32_e32 v0, v0
	v_cndmask_b32_e64 v78, v209, v77, s[42:43]
	v_mov_b32_e32 v161, v77
	v_pk_mul_f32 v[32:33], v[32:33], v[0:1] op_sel_hi:[1,0]
	v_pk_mul_f32 v[30:31], v[30:31], v[0:1] op_sel_hi:[1,0]
	v_pk_mul_f32 v[28:29], v[28:29], v[0:1] op_sel_hi:[1,0]
	v_pk_mul_f32 v[26:27], v[26:27], v[0:1] op_sel_hi:[1,0]
	v_pk_mul_f32 v[24:25], v[24:25], v[0:1] op_sel_hi:[1,0]
	v_pk_mul_f32 v[22:23], v[22:23], v[0:1] op_sel_hi:[1,0]
	v_pk_mul_f32 v[20:21], v[20:21], v[0:1] op_sel_hi:[1,0]
	v_pk_mul_f32 v[18:19], v[18:19], v[0:1] op_sel_hi:[1,0]
	v_pk_add_f32 v[64:65], v[64:65], v[78:79] op_sel_hi:[1,0] neg_lo:[0,1] neg_hi:[0,1]
	v_pk_add_f32 v[66:67], v[66:67], v[78:79] op_sel_hi:[1,0] neg_lo:[0,1] neg_hi:[0,1]
	v_pk_add_f32 v[68:69], v[68:69], v[78:79] op_sel_hi:[1,0] neg_lo:[0,1] neg_hi:[0,1]
	v_pk_add_f32 v[70:71], v[70:71], v[78:79] op_sel_hi:[1,0] neg_lo:[0,1] neg_hi:[0,1]
	v_pk_add_f32 v[72:73], v[72:73], v[78:79] op_sel_hi:[1,0] neg_lo:[0,1] neg_hi:[0,1]
	v_pk_add_f32 v[74:75], v[74:75], v[78:79] op_sel_hi:[1,0] neg_lo:[0,1] neg_hi:[0,1]
	v_pk_add_f32 v[80:81], v[80:81], v[78:79] op_sel_hi:[1,0] neg_lo:[0,1] neg_hi:[0,1]
	v_pk_add_f32 v[82:83], v[82:83], v[78:79] op_sel_hi:[1,0] neg_lo:[0,1] neg_hi:[0,1]
	v_exp_f32_e32 v64, v64
	v_exp_f32_e32 v65, v65
	v_exp_f32_e32 v66, v66
	v_exp_f32_e32 v67, v67
	v_exp_f32_e32 v68, v68
	v_exp_f32_e32 v69, v69
	v_exp_f32_e32 v70, v70
	v_exp_f32_e32 v71, v71
	v_exp_f32_e32 v72, v72
	v_exp_f32_e32 v73, v73
	v_exp_f32_e32 v74, v74
	v_exp_f32_e32 v75, v75
	v_exp_f32_e32 v80, v80
	v_exp_f32_e32 v81, v81
	v_exp_f32_e32 v82, v82
	v_exp_f32_e32 v83, v83
	s_nop 0
	v_pk_add_f32 v[84:85], v[64:65], v[66:67]
	v_pk_add_f32 v[86:87], v[68:69], v[70:71]
	v_pk_add_f32 v[76:77], v[72:73], v[74:75]
	v_pk_add_f32 v[78:79], v[80:81], v[82:83]
	v_pk_add_f32 v[84:85], v[84:85], v[86:87]
	v_pk_add_f32 v[76:77], v[76:77], v[78:79]
	s_nop 0
	v_pk_add_f32 v[84:85], v[84:85], v[76:77]
	s_nop 0
	v_add_f32_e32 v84, v84, v85
	v_fma_f32 v145, v145, v0, v84
	v_cvt_pk_bf16_f32 v67, v66, v67
	v_cvt_pk_bf16_f32 v66, v64, v65
	v_cvt_pk_bf16_f32 v68, v68, v69
	v_cvt_pk_bf16_f32 v69, v70, v71
	v_cvt_pk_bf16_f32 v62, v72, v73
	v_cvt_pk_bf16_f32 v63, v74, v75
	v_cvt_pk_bf16_f32 v64, v80, v81
	v_cvt_pk_bf16_f32 v65, v82, v83
	s_branch .LBB0_446
	.p2alignl 6, 3212836864
.Lp0_skip0:
	v_mov_b32_e32 v54, 0
	v_mov_b32_e32 v55, v54
	v_mov_b32_e32 v56, v54
	v_mov_b32_e32 v57, v54
	v_mov_b32_e32 v58, v54
	v_mov_b32_e32 v59, v54
	v_mov_b32_e32 v60, v54
	v_mov_b32_e32 v61, v54
	v_cndmask_b32_e64 v63, 0, 1, s[42:43]
	v_cmp_ne_u32_e32 vcc, 0, v63
	s_cbranch_vccnz .Lp0_cb1
	s_branch .LBB0_445
	.p2alignl 6, 3212836864
.LBB0_430:
	s_andn2_b64 vcc, exec, s[6:7]
	s_cbranch_vccnz .LBB0_438
	v_cmp_ne_u32_e32 vcc, 0, v139
	s_cbranch_vccz .Lsel_fast
	v_add_u32_e32 v54, s13, v196
	v_sub_u32_e32 v0, s14, v140
	v_add_u32_e32 v62, v54, v194
	v_add_u32_e32 v89, v54, v195
	v_lshl_add_u32 v0, v0, 2, v216
	s_cmp_lg_u64 s[44:45], 0
	s_movk_i32 s98, 0xfec
	s_cselect_b32 s98, 0xffc, s98
	v_add_u32_e32 v230, s98, v0
	v_add_u32_e32 v231, 0xfec, v0
	ds_read_b128 v[64:67], v62 offset:16384
	ds_read_b128 v[54:57], v89 offset:16384
	ds_read_b128 v[68:71], v62 offset:18432
	ds_read_b128 v[58:61], v89 offset:18432
	ds_read_b128 v[72:75], v62 offset:20480
	ds_read_b128 v[76:79], v89 offset:20480
	ds_read_b128 v[80:83], v62 offset:22528
	ds_read_b128 v[84:87], v89 offset:22528
	ds_read2_b32 v[90:91], v230 offset1:1
	ds_read2_b32 v[92:93], v230 offset0:2 offset1:3
	ds_read2_b32 v[94:95], v230 offset0:16 offset1:17
	ds_read2_b32 v[96:97], v230 offset0:18 offset1:19
	s_waitcnt lgkmcnt(4)
	ds_read2_b32 v[98:99], v230 offset0:32 offset1:33
	ds_read2_b32 v[100:101], v230 offset0:34 offset1:35
	ds_read2_b32 v[154:155], v230 offset0:48 offset1:49
	ds_read2_b32 v[156:157], v230 offset0:50 offset1:51
	s_cbranch_scc0 .Lp1v_m1
	s_cmp_lg_u64 s[42:43], 0
	s_cbranch_scc0 .Lp1v_only0
	s_setprio 1
	v_mfma_f32_16x16x32_bf16 v[170:173], v[64:67], v[2:5], 0
	v_mfma_f32_16x16x32_bf16 v[174:177], v[68:71], v[2:5], 0
	v_mfma_f32_16x16x32_bf16 v[170:173], v[54:57], v[6:9], v[170:173]
	v_mfma_f32_16x16x32_bf16 v[178:181], v[72:75], v[2:5], 0
	v_mfma_f32_16x16x32_bf16 v[174:177], v[58:61], v[6:9], v[174:177]
	v_mfma_f32_16x16x32_bf16 v[182:185], v[80:83], v[2:5], 0
	v_mfma_f32_16x16x32_bf16 v[178:181], v[76:79], v[6:9], v[178:181]
	v_mfma_f32_16x16x32_bf16 v[182:185], v[84:87], v[6:9], v[182:185]
	v_mfma_f32_16x16x32_bf16 v[64:67], v[64:67], v[10:13], 0
	v_mfma_f32_16x16x32_bf16 v[68:71], v[68:71], v[10:13], 0
	v_mfma_f32_16x16x32_bf16 v[64:67], v[54:57], v[14:17], v[64:67]
	v_mfma_f32_16x16x32_bf16 v[72:75], v[72:75], v[10:13], 0
	v_mfma_f32_16x16x32_bf16 v[68:71], v[58:61], v[14:17], v[68:71]
	v_mfma_f32_16x16x32_bf16 v[80:83], v[80:83], v[10:13], 0
	v_mfma_f32_16x16x32_bf16 v[72:75], v[76:79], v[14:17], v[72:75]
	v_mfma_f32_16x16x32_bf16 v[80:83], v[84:87], v[14:17], v[80:83]
	s_setprio 0
	s_waitcnt lgkmcnt(0)
	v_pk_fma_f32 v[170:171], v[170:171], s[36:37], v[90:91] op_sel_hi:[1,0,1]
	v_pk_fma_f32 v[172:173], v[172:173], s[36:37], v[92:93] op_sel_hi:[1,0,1]
	v_pk_fma_f32 v[174:175], v[174:175], s[36:37], v[94:95] op_sel_hi:[1,0,1]
	v_pk_fma_f32 v[176:177], v[176:177], s[36:37], v[96:97] op_sel_hi:[1,0,1]
	v_pk_fma_f32 v[178:179], v[178:179], s[36:37], v[98:99] op_sel_hi:[1,0,1]
	v_pk_fma_f32 v[180:181], v[180:181], s[36:37], v[100:101] op_sel_hi:[1,0,1]
	v_pk_fma_f32 v[182:183], v[182:183], s[36:37], v[154:155] op_sel_hi:[1,0,1]
	v_pk_fma_f32 v[184:185], v[184:185], s[36:37], v[156:157] op_sel_hi:[1,0,1]
	ds_read2_b32 v[90:91], v231 offset1:1
	ds_read2_b32 v[92:93], v231 offset0:2 offset1:3
	ds_read2_b32 v[94:95], v231 offset0:16 offset1:17
	ds_read2_b32 v[96:97], v231 offset0:18 offset1:19
	ds_read2_b32 v[98:99], v231 offset0:32 offset1:33
	ds_read2_b32 v[100:101], v231 offset0:34 offset1:35
	ds_read2_b32 v[154:155], v231 offset0:48 offset1:49
	ds_read2_b32 v[156:157], v231 offset0:50 offset1:51
	v_max3_f32 v186, v170, v171, v172
	v_max3_f32 v186, v186, v173, v174
	v_max3_f32 v186, v186, v175, v176
	v_max3_f32 v186, v186, v177, v178
	v_max3_f32 v186, v186, v179, v180
	v_max3_f32 v186, v186, v181, v182
	v_max3_f32 v186, v186, v183, v184
	v_max3_f32 v186, v186, v185, s29
	v_mov_b32_e32 v187, v186
	s_nop 1
	v_permlane16_swap_b32_e32 v186, v187
	v_max_f32_e32 v186, v186, v187
	v_mov_b32_e32 v187, v186
	s_nop 1
	v_permlane32_swap_b32_e32 v186, v187
	v_max_f32_e32 v186, v186, v187
	v_cndmask_b32_e64 v186, v148, v186, s[44:45]
	v_max_f32_e32 v187, v160, v186
	s_waitcnt lgkmcnt(0)
	v_pk_fma_f32 v[64:65], v[64:65], s[36:37], v[90:91] op_sel_hi:[1,0,1]
	v_pk_fma_f32 v[66:67], v[66:67], s[36:37], v[92:93] op_sel_hi:[1,0,1]
	v_pk_fma_f32 v[68:69], v[68:69], s[36:37], v[94:95] op_sel_hi:[1,0,1]
	v_pk_fma_f32 v[70:71], v[70:71], s[36:37], v[96:97] op_sel_hi:[1,0,1]
	v_pk_fma_f32 v[72:73], v[72:73], s[36:37], v[98:99] op_sel_hi:[1,0,1]
	v_pk_fma_f32 v[74:75], v[74:75], s[36:37], v[100:101] op_sel_hi:[1,0,1]
	v_pk_fma_f32 v[80:81], v[80:81], s[36:37], v[154:155] op_sel_hi:[1,0,1]
	v_pk_fma_f32 v[82:83], v[82:83], s[36:37], v[156:157] op_sel_hi:[1,0,1]
	v_max3_f32 v76, v64, v65, v66
	v_max3_f32 v76, v76, v67, v68
	v_max3_f32 v76, v76, v69, v70
	v_max3_f32 v76, v76, v71, v72
	v_max3_f32 v76, v76, v73, v74
	v_max3_f32 v76, v76, v75, v80
	v_max3_f32 v76, v76, v81, v82
	v_max3_f32 v76, v76, v83, s29
	v_mov_b32_e32 v77, v76
	s_nop 1
	v_permlane16_swap_b32_e32 v76, v77
	v_max_f32_e32 v76, v76, v77
	v_mov_b32_e32 v77, v76
	s_nop 1
	v_permlane32_swap_b32_e32 v76, v77
	v_max_f32_e32 v76, v76, v77
	v_cndmask_b32_e64 v76, v148, v76, s[42:43]
	v_max_f32_e32 v77, v161, v76
	v_sub_f32_e32 v248, v160, v187
	v_sub_f32_e32 v0, v161, v77
	v_exp_f32_e32 v236, v248
	v_exp_f32_e32 v0, v0
	v_cndmask_b32_e64 v246, v209, v187, s[44:45]
	v_cndmask_b32_e64 v78, v209, v77, s[42:43]
	v_mov_b32_e32 v160, v187
	v_mov_b32_e32 v161, v77
	v_pk_mul_f32 v[36:37], v[36:37], v[236:237] op_sel_hi:[1,0]
	v_pk_mul_f32 v[32:33], v[32:33], v[0:1] op_sel_hi:[1,0]
	v_pk_mul_f32 v[34:35], v[34:35], v[236:237] op_sel_hi:[1,0]
	v_pk_mul_f32 v[30:31], v[30:31], v[0:1] op_sel_hi:[1,0]
	v_pk_mul_f32 v[48:49], v[48:49], v[236:237] op_sel_hi:[1,0]
	v_pk_mul_f32 v[28:29], v[28:29], v[0:1] op_sel_hi:[1,0]
	v_pk_mul_f32 v[46:47], v[46:47], v[236:237] op_sel_hi:[1,0]
	v_pk_mul_f32 v[26:27], v[26:27], v[0:1] op_sel_hi:[1,0]
	v_pk_mul_f32 v[44:45], v[44:45], v[236:237] op_sel_hi:[1,0]
	v_pk_mul_f32 v[24:25], v[24:25], v[0:1] op_sel_hi:[1,0]
	v_pk_mul_f32 v[42:43], v[42:43], v[236:237] op_sel_hi:[1,0]
	v_pk_mul_f32 v[22:23], v[22:23], v[0:1] op_sel_hi:[1,0]
	v_pk_mul_f32 v[52:53], v[52:53], v[236:237] op_sel_hi:[1,0]
	v_pk_mul_f32 v[20:21], v[20:21], v[0:1] op_sel_hi:[1,0]
	v_pk_mul_f32 v[50:51], v[50:51], v[236:237] op_sel_hi:[1,0]
	v_pk_mul_f32 v[18:19], v[18:19], v[0:1] op_sel_hi:[1,0]
	v_pk_add_f32 v[170:171], v[170:171], v[246:247] op_sel_hi:[1,0] neg_lo:[0,1] neg_hi:[0,1]
	v_pk_add_f32 v[64:65], v[64:65], v[78:79] op_sel_hi:[1,0] neg_lo:[0,1] neg_hi:[0,1]
	v_pk_add_f32 v[172:173], v[172:173], v[246:247] op_sel_hi:[1,0] neg_lo:[0,1] neg_hi:[0,1]
	v_pk_add_f32 v[66:67], v[66:67], v[78:79] op_sel_hi:[1,0] neg_lo:[0,1] neg_hi:[0,1]
	v_pk_add_f32 v[174:175], v[174:175], v[246:247] op_sel_hi:[1,0] neg_lo:[0,1] neg_hi:[0,1]
	v_pk_add_f32 v[68:69], v[68:69], v[78:79] op_sel_hi:[1,0] neg_lo:[0,1] neg_hi:[0,1]
	v_pk_add_f32 v[176:177], v[176:177], v[246:247] op_sel_hi:[1,0] neg_lo:[0,1] neg_hi:[0,1]
	v_pk_add_f32 v[70:71], v[70:71], v[78:79] op_sel_hi:[1,0] neg_lo:[0,1] neg_hi:[0,1]
	v_pk_add_f32 v[178:179], v[178:179], v[246:247] op_sel_hi:[1,0] neg_lo:[0,1] neg_hi:[0,1]
	v_pk_add_f32 v[72:73], v[72:73], v[78:79] op_sel_hi:[1,0] neg_lo:[0,1] neg_hi:[0,1]
	v_pk_add_f32 v[180:181], v[180:181], v[246:247] op_sel_hi:[1,0] neg_lo:[0,1] neg_hi:[0,1]
	v_pk_add_f32 v[74:75], v[74:75], v[78:79] op_sel_hi:[1,0] neg_lo:[0,1] neg_hi:[0,1]
	v_pk_add_f32 v[182:183], v[182:183], v[246:247] op_sel_hi:[1,0] neg_lo:[0,1] neg_hi:[0,1]
	v_pk_add_f32 v[80:81], v[80:81], v[78:79] op_sel_hi:[1,0] neg_lo:[0,1] neg_hi:[0,1]
	v_pk_add_f32 v[184:185], v[184:185], v[246:247] op_sel_hi:[1,0] neg_lo:[0,1] neg_hi:[0,1]
	v_pk_add_f32 v[82:83], v[82:83], v[78:79] op_sel_hi:[1,0] neg_lo:[0,1] neg_hi:[0,1]
	v_exp_f32_e32 v170, v170
	v_exp_f32_e32 v64, v64
	v_exp_f32_e32 v171, v171
	v_exp_f32_e32 v65, v65
	v_exp_f32_e32 v172, v172
	v_exp_f32_e32 v66, v66
	v_exp_f32_e32 v173, v173
	v_exp_f32_e32 v67, v67
	v_exp_f32_e32 v174, v174
	v_exp_f32_e32 v68, v68
	v_exp_f32_e32 v175, v175
	v_exp_f32_e32 v69, v69
	v_exp_f32_e32 v176, v176
	v_exp_f32_e32 v70, v70
	v_exp_f32_e32 v177, v177
	v_exp_f32_e32 v71, v71
	v_exp_f32_e32 v178, v178
	v_exp_f32_e32 v72, v72
	v_exp_f32_e32 v179, v179
	v_exp_f32_e32 v73, v73
	v_exp_f32_e32 v180, v180
	v_exp_f32_e32 v74, v74
	v_exp_f32_e32 v181, v181
	v_exp_f32_e32 v75, v75
	v_exp_f32_e32 v182, v182
	v_exp_f32_e32 v80, v80
	v_exp_f32_e32 v183, v183
	v_exp_f32_e32 v81, v81
	v_exp_f32_e32 v184, v184
	v_exp_f32_e32 v82, v82
	v_exp_f32_e32 v185, v185
	v_exp_f32_e32 v83, v83
	v_pk_add_f32 v[238:239], v[170:171], v[172:173]
	v_pk_add_f32 v[84:85], v[64:65], v[66:67]
	v_pk_add_f32 v[240:241], v[174:175], v[176:177]
	v_pk_add_f32 v[86:87], v[68:69], v[70:71]
	v_pk_add_f32 v[242:243], v[178:179], v[180:181]
	v_pk_add_f32 v[76:77], v[72:73], v[74:75]
	v_pk_add_f32 v[244:245], v[182:183], v[184:185]
	v_pk_add_f32 v[78:79], v[80:81], v[82:83]
	v_pk_add_f32 v[238:239], v[238:239], v[240:241]
	v_pk_add_f32 v[84:85], v[84:85], v[86:87]
	v_pk_add_f32 v[242:243], v[242:243], v[244:245]
	v_pk_add_f32 v[76:77], v[76:77], v[78:79]
	v_pk_add_f32 v[238:239], v[238:239], v[242:243]
	v_pk_add_f32 v[84:85], v[84:85], v[76:77]
	v_add_f32_e32 v238, v238, v239
	v_add_f32_e32 v84, v84, v85
	v_fma_f32 v144, v144, v236, v238
	v_fma_f32 v145, v145, v0, v84
	v_cvt_pk_bf16_f32 v58, v170, v171
	v_cvt_pk_bf16_f32 v67, v66, v67
	v_cvt_pk_bf16_f32 v59, v172, v173
	v_cvt_pk_bf16_f32 v66, v64, v65
	v_cvt_pk_bf16_f32 v60, v174, v175
	v_cvt_pk_bf16_f32 v68, v68, v69
	v_cvt_pk_bf16_f32 v61, v176, v177
	v_cvt_pk_bf16_f32 v69, v70, v71
	v_cvt_pk_bf16_f32 v54, v178, v179
	v_cvt_pk_bf16_f32 v62, v72, v73
	v_cvt_pk_bf16_f32 v55, v180, v181
	v_cvt_pk_bf16_f32 v63, v74, v75
	v_cvt_pk_bf16_f32 v56, v182, v183
	v_cvt_pk_bf16_f32 v64, v80, v81
	v_cvt_pk_bf16_f32 v57, v184, v185
	v_cvt_pk_bf16_f32 v65, v82, v83
	s_branch .LBB0_446
	.p2alignl 6, 3212836864
.Lp1v_only0:
	s_setprio 1
	v_mfma_f32_16x16x32_bf16 v[170:173], v[64:67], v[2:5], 0
	v_mfma_f32_16x16x32_bf16 v[174:177], v[68:71], v[2:5], 0
	v_mfma_f32_16x16x32_bf16 v[170:173], v[54:57], v[6:9], v[170:173]
	v_mfma_f32_16x16x32_bf16 v[178:181], v[72:75], v[2:5], 0
	v_mfma_f32_16x16x32_bf16 v[174:177], v[58:61], v[6:9], v[174:177]
	v_mfma_f32_16x16x32_bf16 v[182:185], v[80:83], v[2:5], 0
	v_mfma_f32_16x16x32_bf16 v[178:181], v[76:79], v[6:9], v[178:181]
	v_mfma_f32_16x16x32_bf16 v[182:185], v[84:87], v[6:9], v[182:185]
	s_setprio 0
	s_nop 7
	s_nop 7
	s_waitcnt lgkmcnt(0)
	v_pk_fma_f32 v[170:171], v[170:171], s[36:37], v[90:91] op_sel_hi:[1,0,1]
	v_pk_fma_f32 v[172:173], v[172:173], s[36:37], v[92:93] op_sel_hi:[1,0,1]
	v_pk_fma_f32 v[174:175], v[174:175], s[36:37], v[94:95] op_sel_hi:[1,0,1]
	v_pk_fma_f32 v[176:177], v[176:177], s[36:37], v[96:97] op_sel_hi:[1,0,1]
	v_pk_fma_f32 v[178:179], v[178:179], s[36:37], v[98:99] op_sel_hi:[1,0,1]
	v_pk_fma_f32 v[180:181], v[180:181], s[36:37], v[100:101] op_sel_hi:[1,0,1]
	v_pk_fma_f32 v[182:183], v[182:183], s[36:37], v[154:155] op_sel_hi:[1,0,1]
	v_pk_fma_f32 v[184:185], v[184:185], s[36:37], v[156:157] op_sel_hi:[1,0,1]
	v_max3_f32 v186, v170, v171, v172
	v_max3_f32 v186, v186, v173, v174
	v_max3_f32 v186, v186, v175, v176
	v_max3_f32 v186, v186, v177, v178
	v_max3_f32 v186, v186, v179, v180
	v_max3_f32 v186, v186, v181, v182
	v_max3_f32 v186, v186, v183, v184
	v_max3_f32 v186, v186, v185, s29
	v_mov_b32_e32 v187, v186
	s_nop 1
	v_permlane16_swap_b32_e32 v186, v187
	v_max_f32_e32 v186, v186, v187
	v_mov_b32_e32 v187, v186
	s_nop 1
	v_permlane32_swap_b32_e32 v186, v187
	v_max_f32_e32 v186, v186, v187
	v_cndmask_b32_e64 v186, v148, v186, s[44:45]
	v_max_f32_e32 v187, v160, v186
	v_sub_f32_e32 v248, v160, v187
	v_exp_f32_e32 v236, v248
	v_cndmask_b32_e64 v246, v209, v187, s[44:45]
	v_mov_b32_e32 v160, v187
	v_pk_mul_f32 v[36:37], v[36:37], v[236:237] op_sel_hi:[1,0]
	v_pk_mul_f32 v[34:35], v[34:35], v[236:237] op_sel_hi:[1,0]
	v_pk_mul_f32 v[48:49], v[48:49], v[236:237] op_sel_hi:[1,0]
	v_pk_mul_f32 v[46:47], v[46:47], v[236:237] op_sel_hi:[1,0]
	v_pk_mul_f32 v[44:45], v[44:45], v[236:237] op_sel_hi:[1,0]
	v_pk_mul_f32 v[42:43], v[42:43], v[236:237] op_sel_hi:[1,0]
	v_pk_mul_f32 v[52:53], v[52:53], v[236:237] op_sel_hi:[1,0]
	v_pk_mul_f32 v[50:51], v[50:51], v[236:237] op_sel_hi:[1,0]
	v_pk_add_f32 v[170:171], v[170:171], v[246:247] op_sel_hi:[1,0] neg_lo:[0,1] neg_hi:[0,1]
	v_pk_add_f32 v[172:173], v[172:173], v[246:247] op_sel_hi:[1,0] neg_lo:[0,1] neg_hi:[0,1]
	v_pk_add_f32 v[174:175], v[174:175], v[246:247] op_sel_hi:[1,0] neg_lo:[0,1] neg_hi:[0,1]
	v_pk_add_f32 v[176:177], v[176:177], v[246:247] op_sel_hi:[1,0] neg_lo:[0,1] neg_hi:[0,1]
	v_pk_add_f32 v[178:179], v[178:179], v[246:247] op_sel_hi:[1,0] neg_lo:[0,1] neg_hi:[0,1]
	v_pk_add_f32 v[180:181], v[180:181], v[246:247] op_sel_hi:[1,0] neg_lo:[0,1] neg_hi:[0,1]
	v_pk_add_f32 v[182:183], v[182:183], v[246:247] op_sel_hi:[1,0] neg_lo:[0,1] neg_hi:[0,1]
	v_pk_add_f32 v[184:185], v[184:185], v[246:247] op_sel_hi:[1,0] neg_lo:[0,1] neg_hi:[0,1]
	v_exp_f32_e32 v170, v170
	v_exp_f32_e32 v171, v171
	v_exp_f32_e32 v172, v172
	v_exp_f32_e32 v173, v173
	v_exp_f32_e32 v174, v174
	v_exp_f32_e32 v175, v175
	v_exp_f32_e32 v176, v176
	v_exp_f32_e32 v177, v177
	v_exp_f32_e32 v178, v178
	v_exp_f32_e32 v179, v179
	v_exp_f32_e32 v180, v180
	v_exp_f32_e32 v181, v181
	v_exp_f32_e32 v182, v182
	v_exp_f32_e32 v183, v183
	v_exp_f32_e32 v184, v184
	v_exp_f32_e32 v185, v185
	s_nop 0
	v_pk_add_f32 v[238:239], v[170:171], v[172:173]
	v_pk_add_f32 v[240:241], v[174:175], v[176:177]
	v_pk_add_f32 v[242:243], v[178:179], v[180:181]
	v_pk_add_f32 v[244:245], v[182:183], v[184:185]
	v_pk_add_f32 v[238:239], v[238:239], v[240:241]
	v_pk_add_f32 v[242:243], v[242:243], v[244:245]
	s_nop 0
	v_pk_add_f32 v[238:239], v[238:239], v[242:243]
	s_nop 0
	v_add_f32_e32 v238, v238, v239
	v_fma_f32 v144, v144, v236, v238
	v_cvt_pk_bf16_f32 v58, v170, v171
	v_cvt_pk_bf16_f32 v59, v172, v173
	v_cvt_pk_bf16_f32 v60, v174, v175
	v_cvt_pk_bf16_f32 v61, v176, v177
	v_cvt_pk_bf16_f32 v54, v178, v179
	v_cvt_pk_bf16_f32 v55, v180, v181
	v_cvt_pk_bf16_f32 v56, v182, v183
	v_cvt_pk_bf16_f32 v57, v184, v185
	s_branch .LBB0_445
	.p2alignl 6, 3212836864
.Lp1v_m1:
	s_setprio 1
	v_mfma_f32_16x16x32_bf16 v[64:67], v[64:67], v[10:13], 0
	v_mfma_f32_16x16x32_bf16 v[68:71], v[68:71], v[10:13], 0
	v_mfma_f32_16x16x32_bf16 v[64:67], v[54:57], v[14:17], v[64:67]
	v_mfma_f32_16x16x32_bf16 v[72:75], v[72:75], v[10:13], 0
	v_mfma_f32_16x16x32_bf16 v[68:71], v[58:61], v[14:17], v[68:71]
	v_mfma_f32_16x16x32_bf16 v[80:83], v[80:83], v[10:13], 0
	v_mfma_f32_16x16x32_bf16 v[72:75], v[76:79], v[14:17], v[72:75]
	v_mfma_f32_16x16x32_bf16 v[80:83], v[84:87], v[14:17], v[80:83]
	s_setprio 0
	s_nop 7
	s_nop 7
	v_mov_b32_e32 v54, 0
	v_mov_b32_e32 v55, v54
	v_mov_b32_e32 v56, v54
	v_mov_b32_e32 v57, v54
	v_mov_b32_e32 v58, v54
	v_mov_b32_e32 v59, v54
	v_mov_b32_e32 v60, v54
	v_mov_b32_e32 v61, v54
	s_waitcnt lgkmcnt(0)
	v_pk_fma_f32 v[64:65], v[64:65], s[36:37], v[90:91] op_sel_hi:[1,0,1]
	v_pk_fma_f32 v[66:67], v[66:67], s[36:37], v[92:93] op_sel_hi:[1,0,1]
	v_pk_fma_f32 v[68:69], v[68:69], s[36:37], v[94:95] op_sel_hi:[1,0,1]
	v_pk_fma_f32 v[70:71], v[70:71], s[36:37], v[96:97] op_sel_hi:[1,0,1]
	v_pk_fma_f32 v[72:73], v[72:73], s[36:37], v[98:99] op_sel_hi:[1,0,1]
	v_pk_fma_f32 v[74:75], v[74:75], s[36:37], v[100:101] op_sel_hi:[1,0,1]
	v_pk_fma_f32 v[80:81], v[80:81], s[36:37], v[154:155] op_sel_hi:[1,0,1]
	v_pk_fma_f32 v[82:83], v[82:83], s[36:37], v[156:157] op_sel_hi:[1,0,1]
	v_max3_f32 v76, v64, v65, v66
	v_max3_f32 v76, v76, v67, v68
	v_max3_f32 v76, v76, v69, v70
	v_max3_f32 v76, v76, v71, v72
	v_max3_f32 v76, v76, v73, v74
	v_max3_f32 v76, v76, v75, v80
	v_max3_f32 v76, v76, v81, v82
	v_max3_f32 v76, v76, v83, s29
	v_mov_b32_e32 v77, v76
	s_nop 1
	v_permlane16_swap_b32_e32 v76, v77
	v_max_f32_e32 v76, v76, v77
	v_mov_b32_e32 v77, v76
	s_nop 1
	v_permlane32_swap_b32_e32 v76, v77
	v_max_f32_e32 v76, v76, v77
	v_cndmask_b32_e64 v76, v148, v76, s[42:43]
	v_max_f32_e32 v77, v161, v76
	v_sub_f32_e32 v0, v161, v77
	v_exp_f32_e32 v0, v0
	v_cndmask_b32_e64 v78, v209, v77, s[42:43]
	v_mov_b32_e32 v161, v77
	v_pk_mul_f32 v[32:33], v[32:33], v[0:1] op_sel_hi:[1,0]
	v_pk_mul_f32 v[30:31], v[30:31], v[0:1] op_sel_hi:[1,0]
	v_pk_mul_f32 v[28:29], v[28:29], v[0:1] op_sel_hi:[1,0]
	v_pk_mul_f32 v[26:27], v[26:27], v[0:1] op_sel_hi:[1,0]
	v_pk_mul_f32 v[24:25], v[24:25], v[0:1] op_sel_hi:[1,0]
	v_pk_mul_f32 v[22:23], v[22:23], v[0:1] op_sel_hi:[1,0]
	v_pk_mul_f32 v[20:21], v[20:21], v[0:1] op_sel_hi:[1,0]
	v_pk_mul_f32 v[18:19], v[18:19], v[0:1] op_sel_hi:[1,0]
	v_pk_add_f32 v[64:65], v[64:65], v[78:79] op_sel_hi:[1,0] neg_lo:[0,1] neg_hi:[0,1]
	v_pk_add_f32 v[66:67], v[66:67], v[78:79] op_sel_hi:[1,0] neg_lo:[0,1] neg_hi:[0,1]
	v_pk_add_f32 v[68:69], v[68:69], v[78:79] op_sel_hi:[1,0] neg_lo:[0,1] neg_hi:[0,1]
	v_pk_add_f32 v[70:71], v[70:71], v[78:79] op_sel_hi:[1,0] neg_lo:[0,1] neg_hi:[0,1]
	v_pk_add_f32 v[72:73], v[72:73], v[78:79] op_sel_hi:[1,0] neg_lo:[0,1] neg_hi:[0,1]
	v_pk_add_f32 v[74:75], v[74:75], v[78:79] op_sel_hi:[1,0] neg_lo:[0,1] neg_hi:[0,1]
	v_pk_add_f32 v[80:81], v[80:81], v[78:79] op_sel_hi:[1,0] neg_lo:[0,1] neg_hi:[0,1]
	v_pk_add_f32 v[82:83], v[82:83], v[78:79] op_sel_hi:[1,0] neg_lo:[0,1] neg_hi:[0,1]
	v_exp_f32_e32 v64, v64
	v_exp_f32_e32 v65, v65
	v_exp_f32_e32 v66, v66
	v_exp_f32_e32 v67, v67
	v_exp_f32_e32 v68, v68
	v_exp_f32_e32 v69, v69
	v_exp_f32_e32 v70, v70
	v_exp_f32_e32 v71, v71
	v_exp_f32_e32 v72, v72
	v_exp_f32_e32 v73, v73
	v_exp_f32_e32 v74, v74
	v_exp_f32_e32 v75, v75
	v_exp_f32_e32 v80, v80
	v_exp_f32_e32 v81, v81
	v_exp_f32_e32 v82, v82
	v_exp_f32_e32 v83, v83
	s_nop 0
	v_pk_add_f32 v[84:85], v[64:65], v[66:67]
	v_pk_add_f32 v[86:87], v[68:69], v[70:71]
	v_pk_add_f32 v[76:77], v[72:73], v[74:75]
	v_pk_add_f32 v[78:79], v[80:81], v[82:83]
	v_pk_add_f32 v[84:85], v[84:85], v[86:87]
	v_pk_add_f32 v[76:77], v[76:77], v[78:79]
	s_nop 0
	v_pk_add_f32 v[84:85], v[84:85], v[76:77]
	s_nop 0
	v_add_f32_e32 v84, v84, v85
	v_fma_f32 v145, v145, v0, v84
	v_cvt_pk_bf16_f32 v67, v66, v67
	v_cvt_pk_bf16_f32 v66, v64, v65
	v_cvt_pk_bf16_f32 v68, v68, v69
	v_cvt_pk_bf16_f32 v69, v70, v71
	v_cvt_pk_bf16_f32 v62, v72, v73
	v_cvt_pk_bf16_f32 v63, v74, v75
	v_cvt_pk_bf16_f32 v64, v80, v81
	v_cvt_pk_bf16_f32 v65, v82, v83
	s_branch .LBB0_446
	.p2alignl 6, 3212836864

.LBB0_439:
	s_andn2_b64 vcc, exec, s[6:7]
	s_cbranch_vccnz .LBB0_448
	v_and_b32_e32 v0, 1, v164
	v_cmp_eq_u32_e64 s[42:43], 1, v0
	v_and_b32_e32 v0, 1, v162
	v_cmp_eq_u32_e64 s[44:45], 1, v0
	s_or_b64 s[6:7], s[44:45], s[42:43]
	v_cndmask_b32_e64 v54, 0, 1, s[6:7]
	v_cmp_ne_u32_e32 vcc, 0, v54
	s_cbranch_vccz .Lsel_fast
	v_add_u32_e32 v54, s13, v196
	v_add_u32_e32 v62, v54, v194
	v_add_u32_e32 v0, v54, v195
	s_cmp_lg_u64 s[44:45], 0
	ds_read_b128 v[64:67], v62 offset:16384
	ds_read_b128 v[54:57], v0 offset:16384
	ds_read_b128 v[68:71], v62 offset:18432
	ds_read_b128 v[58:61], v0 offset:18432
	ds_read_b128 v[72:75], v62 offset:20480
	ds_read_b128 v[76:79], v0 offset:20480
	ds_read_b128 v[80:83], v62 offset:22528
	ds_read_b128 v[84:87], v0 offset:22528
	ds_read_b32 v188, v193
	s_waitcnt lgkmcnt(0)
	s_cbranch_scc0 .Lp2v_m1
	s_cmp_lg_u64 s[42:43], 0
	s_cbranch_scc0 .Lp2v_only0
	s_setprio 1
	v_mfma_f32_16x16x32_bf16 v[170:173], v[64:67], v[2:5], 0
	v_mfma_f32_16x16x32_bf16 v[174:177], v[68:71], v[2:5], 0
	v_mfma_f32_16x16x32_bf16 v[170:173], v[54:57], v[6:9], v[170:173]
	v_mfma_f32_16x16x32_bf16 v[178:181], v[72:75], v[2:5], 0
	v_mfma_f32_16x16x32_bf16 v[174:177], v[58:61], v[6:9], v[174:177]
	v_mfma_f32_16x16x32_bf16 v[182:185], v[80:83], v[2:5], 0
	v_mfma_f32_16x16x32_bf16 v[178:181], v[76:79], v[6:9], v[178:181]
	v_mfma_f32_16x16x32_bf16 v[182:185], v[84:87], v[6:9], v[182:185]
	v_mfma_f32_16x16x32_bf16 v[64:67], v[64:67], v[10:13], 0
	v_mfma_f32_16x16x32_bf16 v[68:71], v[68:71], v[10:13], 0
	v_mfma_f32_16x16x32_bf16 v[64:67], v[54:57], v[14:17], v[64:67]
	v_mfma_f32_16x16x32_bf16 v[72:75], v[72:75], v[10:13], 0
	v_mfma_f32_16x16x32_bf16 v[68:71], v[58:61], v[14:17], v[68:71]
	v_mfma_f32_16x16x32_bf16 v[80:83], v[80:83], v[10:13], 0
	v_mfma_f32_16x16x32_bf16 v[72:75], v[76:79], v[14:17], v[72:75]
	v_mfma_f32_16x16x32_bf16 v[80:83], v[84:87], v[14:17], v[80:83]
	s_setprio 0
	s_nop 7
	v_max3_f32 v186, v170, v171, v172
	v_max3_f32 v76, v64, v65, v66
	v_max3_f32 v186, v186, v173, v174
	v_max3_f32 v76, v76, v67, v68
	v_max3_f32 v186, v186, v175, v176
	v_max3_f32 v76, v76, v69, v70
	v_max3_f32 v186, v186, v177, v178
	v_max3_f32 v76, v76, v71, v72
	v_max3_f32 v186, v186, v179, v180
	v_max3_f32 v76, v76, v73, v74
	v_max3_f32 v186, v186, v181, v182
	v_max3_f32 v76, v76, v75, v80
	v_max3_f32 v186, v186, v183, v184
	v_max3_f32 v76, v76, v81, v82
	v_max_f32_e32 v186, v186, v185
	v_max_f32_e32 v76, v76, v83
	v_mov_b32_e32 v187, v186
	v_mov_b32_e32 v77, v76
	s_nop 0
	v_permlane16_swap_b32_e32 v186, v187
	v_permlane16_swap_b32_e32 v76, v77
	v_max_f32_e32 v186, v186, v187
	v_max_f32_e32 v76, v76, v77
	v_mov_b32_e32 v187, v186
	v_mov_b32_e32 v77, v76
	s_nop 0
	v_permlane32_swap_b32_e32 v186, v187
	v_permlane32_swap_b32_e32 v76, v77
	v_max_f32_e32 v186, v186, v187
	v_max_f32_e32 v76, v76, v77
	v_fma_f32 v186, v186, s36, v188
	v_fma_f32 v76, v76, s36, v188
	v_max_f32_e32 v186, s29, v186
	v_max_f32_e32 v76, s29, v76
	v_cndmask_b32_e64 v186, v148, v186, s[44:45]
	v_cndmask_b32_e64 v76, v148, v76, s[42:43]
	v_max_f32_e32 v187, v160, v186
	v_max_f32_e32 v77, v161, v76
	v_sub_f32_e32 v248, v160, v187
	v_sub_f32_e32 v0, v161, v77
	v_exp_f32_e32 v236, v248
	v_exp_f32_e32 v0, v0
	v_cndmask_b32_e64 v186, v209, v187, s[44:45]
	v_cndmask_b32_e64 v76, v209, v77, s[42:43]
	v_mov_b32_e32 v160, v187
	v_mov_b32_e32 v161, v77
	v_sub_f32_e32 v246, v188, v186
	v_sub_f32_e32 v78, v188, v76
	v_pk_mul_f32 v[36:37], v[36:37], v[236:237] op_sel_hi:[1,0]
	v_pk_mul_f32 v[32:33], v[32:33], v[0:1] op_sel_hi:[1,0]
	v_pk_mul_f32 v[34:35], v[34:35], v[236:237] op_sel_hi:[1,0]
	v_pk_mul_f32 v[30:31], v[30:31], v[0:1] op_sel_hi:[1,0]
	v_pk_mul_f32 v[48:49], v[48:49], v[236:237] op_sel_hi:[1,0]
	v_pk_mul_f32 v[28:29], v[28:29], v[0:1] op_sel_hi:[1,0]
	v_pk_mul_f32 v[46:47], v[46:47], v[236:237] op_sel_hi:[1,0]
	v_pk_mul_f32 v[26:27], v[26:27], v[0:1] op_sel_hi:[1,0]
	v_pk_mul_f32 v[44:45], v[44:45], v[236:237] op_sel_hi:[1,0]
	v_pk_mul_f32 v[24:25], v[24:25], v[0:1] op_sel_hi:[1,0]
	v_pk_mul_f32 v[42:43], v[42:43], v[236:237] op_sel_hi:[1,0]
	v_pk_mul_f32 v[22:23], v[22:23], v[0:1] op_sel_hi:[1,0]
	v_pk_mul_f32 v[52:53], v[52:53], v[236:237] op_sel_hi:[1,0]
	v_pk_mul_f32 v[20:21], v[20:21], v[0:1] op_sel_hi:[1,0]
	v_pk_mul_f32 v[50:51], v[50:51], v[236:237] op_sel_hi:[1,0]
	v_pk_mul_f32 v[18:19], v[18:19], v[0:1] op_sel_hi:[1,0]
	v_pk_fma_f32 v[170:171], v[170:171], s[36:37], v[246:247] op_sel_hi:[1,0,0]
	v_pk_fma_f32 v[64:65], v[64:65], s[36:37], v[78:79] op_sel_hi:[1,0,0]
	v_pk_fma_f32 v[172:173], v[172:173], s[36:37], v[246:247] op_sel_hi:[1,0,0]
	v_pk_fma_f32 v[66:67], v[66:67], s[36:37], v[78:79] op_sel_hi:[1,0,0]
	v_pk_fma_f32 v[174:175], v[174:175], s[36:37], v[246:247] op_sel_hi:[1,0,0]
	v_pk_fma_f32 v[68:69], v[68:69], s[36:37], v[78:79] op_sel_hi:[1,0,0]
	v_pk_fma_f32 v[176:177], v[176:177], s[36:37], v[246:247] op_sel_hi:[1,0,0]
	v_pk_fma_f32 v[70:71], v[70:71], s[36:37], v[78:79] op_sel_hi:[1,0,0]
	v_pk_fma_f32 v[178:179], v[178:179], s[36:37], v[246:247] op_sel_hi:[1,0,0]
	v_pk_fma_f32 v[72:73], v[72:73], s[36:37], v[78:79] op_sel_hi:[1,0,0]
	v_pk_fma_f32 v[180:181], v[180:181], s[36:37], v[246:247] op_sel_hi:[1,0,0]
	v_pk_fma_f32 v[74:75], v[74:75], s[36:37], v[78:79] op_sel_hi:[1,0,0]
	v_pk_fma_f32 v[182:183], v[182:183], s[36:37], v[246:247] op_sel_hi:[1,0,0]
	v_pk_fma_f32 v[80:81], v[80:81], s[36:37], v[78:79] op_sel_hi:[1,0,0]
	v_pk_fma_f32 v[184:185], v[184:185], s[36:37], v[246:247] op_sel_hi:[1,0,0]
	v_pk_fma_f32 v[82:83], v[82:83], s[36:37], v[78:79] op_sel_hi:[1,0,0]
	v_exp_f32_e32 v170, v170
	v_exp_f32_e32 v64, v64
	v_exp_f32_e32 v171, v171
	v_exp_f32_e32 v65, v65
	v_exp_f32_e32 v172, v172
	v_exp_f32_e32 v66, v66
	v_exp_f32_e32 v173, v173
	v_exp_f32_e32 v67, v67
	v_exp_f32_e32 v174, v174
	v_exp_f32_e32 v68, v68
	v_exp_f32_e32 v175, v175
	v_exp_f32_e32 v69, v69
	v_exp_f32_e32 v176, v176
	v_exp_f32_e32 v70, v70
	v_exp_f32_e32 v177, v177
	v_exp_f32_e32 v71, v71
	v_exp_f32_e32 v178, v178
	v_exp_f32_e32 v72, v72
	v_exp_f32_e32 v179, v179
	v_exp_f32_e32 v73, v73
	v_exp_f32_e32 v180, v180
	v_exp_f32_e32 v74, v74
	v_exp_f32_e32 v181, v181
	v_exp_f32_e32 v75, v75
	v_exp_f32_e32 v182, v182
	v_exp_f32_e32 v80, v80
	v_exp_f32_e32 v183, v183
	v_exp_f32_e32 v81, v81
	v_exp_f32_e32 v184, v184
	v_exp_f32_e32 v82, v82
	v_exp_f32_e32 v185, v185
	v_exp_f32_e32 v83, v83
	v_pk_add_f32 v[238:239], v[170:171], v[172:173]
	v_pk_add_f32 v[84:85], v[64:65], v[66:67]
	v_pk_add_f32 v[240:241], v[174:175], v[176:177]
	v_pk_add_f32 v[86:87], v[68:69], v[70:71]
	v_pk_add_f32 v[242:243], v[178:179], v[180:181]
	v_pk_add_f32 v[76:77], v[72:73], v[74:75]
	v_pk_add_f32 v[244:245], v[182:183], v[184:185]
	v_pk_add_f32 v[78:79], v[80:81], v[82:83]
	v_pk_add_f32 v[238:239], v[238:239], v[240:241]
	v_pk_add_f32 v[84:85], v[84:85], v[86:87]
	v_pk_add_f32 v[242:243], v[242:243], v[244:245]
	v_pk_add_f32 v[76:77], v[76:77], v[78:79]
	v_pk_add_f32 v[238:239], v[238:239], v[242:243]
	v_pk_add_f32 v[84:85], v[84:85], v[76:77]
	v_add_f32_e32 v238, v238, v239
	v_add_f32_e32 v84, v84, v85
	v_fma_f32 v144, v144, v236, v238
	v_fma_f32 v145, v145, v0, v84
	v_cvt_pk_bf16_f32 v58, v170, v171
	v_cvt_pk_bf16_f32 v67, v66, v67
	v_cvt_pk_bf16_f32 v59, v172, v173
	v_cvt_pk_bf16_f32 v66, v64, v65
	v_cvt_pk_bf16_f32 v60, v174, v175
	v_cvt_pk_bf16_f32 v68, v68, v69
	v_cvt_pk_bf16_f32 v61, v176, v177
	v_cvt_pk_bf16_f32 v69, v70, v71
	v_cvt_pk_bf16_f32 v54, v178, v179
	v_cvt_pk_bf16_f32 v62, v72, v73
	v_cvt_pk_bf16_f32 v55, v180, v181
	v_cvt_pk_bf16_f32 v63, v74, v75
	v_cvt_pk_bf16_f32 v56, v182, v183
	v_cvt_pk_bf16_f32 v64, v80, v81
	v_cvt_pk_bf16_f32 v57, v184, v185
	v_cvt_pk_bf16_f32 v65, v82, v83
	s_branch .LBB0_446
	.p2alignl 6, 3212836864
.Lp2v_only0:
	s_setprio 1
	v_mfma_f32_16x16x32_bf16 v[170:173], v[64:67], v[2:5], 0
	v_mfma_f32_16x16x32_bf16 v[174:177], v[68:71], v[2:5], 0
	v_mfma_f32_16x16x32_bf16 v[170:173], v[54:57], v[6:9], v[170:173]
	v_mfma_f32_16x16x32_bf16 v[178:181], v[72:75], v[2:5], 0
	v_mfma_f32_16x16x32_bf16 v[174:177], v[58:61], v[6:9], v[174:177]
	v_mfma_f32_16x16x32_bf16 v[182:185], v[80:83], v[2:5], 0
	v_mfma_f32_16x16x32_bf16 v[178:181], v[76:79], v[6:9], v[178:181]
	v_mfma_f32_16x16x32_bf16 v[182:185], v[84:87], v[6:9], v[182:185]
	s_setprio 0
	s_nop 7
	s_nop 7
	v_max3_f32 v186, v170, v171, v172
	v_max3_f32 v186, v186, v173, v174
	v_max3_f32 v186, v186, v175, v176
	v_max3_f32 v186, v186, v177, v178
	v_max3_f32 v186, v186, v179, v180
	v_max3_f32 v186, v186, v181, v182
	v_max3_f32 v186, v186, v183, v184
	v_max_f32_e32 v186, v186, v185
	v_mov_b32_e32 v187, v186
	s_nop 1
	v_permlane16_swap_b32_e32 v186, v187
	v_max_f32_e32 v186, v186, v187
	v_mov_b32_e32 v187, v186
	s_nop 1
	v_permlane32_swap_b32_e32 v186, v187
	v_max_f32_e32 v186, v186, v187
	v_fma_f32 v186, v186, s36, v188
	v_max_f32_e32 v186, s29, v186
	v_cndmask_b32_e64 v186, v148, v186, s[44:45]
	v_max_f32_e32 v187, v160, v186
	v_sub_f32_e32 v248, v160, v187
	v_exp_f32_e32 v236, v248
	v_cndmask_b32_e64 v186, v209, v187, s[44:45]
	v_mov_b32_e32 v160, v187
	v_sub_f32_e32 v246, v188, v186
	v_pk_mul_f32 v[36:37], v[36:37], v[236:237] op_sel_hi:[1,0]
	v_pk_mul_f32 v[34:35], v[34:35], v[236:237] op_sel_hi:[1,0]
	v_pk_mul_f32 v[48:49], v[48:49], v[236:237] op_sel_hi:[1,0]
	v_pk_mul_f32 v[46:47], v[46:47], v[236:237] op_sel_hi:[1,0]
	v_pk_mul_f32 v[44:45], v[44:45], v[236:237] op_sel_hi:[1,0]
	v_pk_mul_f32 v[42:43], v[42:43], v[236:237] op_sel_hi:[1,0]
	v_pk_mul_f32 v[52:53], v[52:53], v[236:237] op_sel_hi:[1,0]
	v_pk_mul_f32 v[50:51], v[50:51], v[236:237] op_sel_hi:[1,0]
	v_pk_fma_f32 v[170:171], v[170:171], s[36:37], v[246:247] op_sel_hi:[1,0,0]
	v_pk_fma_f32 v[172:173], v[172:173], s[36:37], v[246:247] op_sel_hi:[1,0,0]
	v_pk_fma_f32 v[174:175], v[174:175], s[36:37], v[246:247] op_sel_hi:[1,0,0]
	v_pk_fma_f32 v[176:177], v[176:177], s[36:37], v[246:247] op_sel_hi:[1,0,0]
	v_pk_fma_f32 v[178:179], v[178:179], s[36:37], v[246:247] op_sel_hi:[1,0,0]
	v_pk_fma_f32 v[180:181], v[180:181], s[36:37], v[246:247] op_sel_hi:[1,0,0]
	v_pk_fma_f32 v[182:183], v[182:183], s[36:37], v[246:247] op_sel_hi:[1,0,0]
	v_pk_fma_f32 v[184:185], v[184:185], s[36:37], v[246:247] op_sel_hi:[1,0,0]
	v_exp_f32_e32 v170, v170
	v_exp_f32_e32 v171, v171
	v_exp_f32_e32 v172, v172
	v_exp_f32_e32 v173, v173
	v_exp_f32_e32 v174, v174
	v_exp_f32_e32 v175, v175
	v_exp_f32_e32 v176, v176
	v_exp_f32_e32 v177, v177
	v_exp_f32_e32 v178, v178
	v_exp_f32_e32 v179, v179
	v_exp_f32_e32 v180, v180
	v_exp_f32_e32 v181, v181
	v_exp_f32_e32 v182, v182
	v_exp_f32_e32 v183, v183
	v_exp_f32_e32 v184, v184
	v_exp_f32_e32 v185, v185
	s_nop 0
	v_pk_add_f32 v[238:239], v[170:171], v[172:173]
	v_pk_add_f32 v[240:241], v[174:175], v[176:177]
	v_pk_add_f32 v[242:243], v[178:179], v[180:181]
	v_pk_add_f32 v[244:245], v[182:183], v[184:185]
	v_pk_add_f32 v[238:239], v[238:239], v[240:241]
	v_pk_add_f32 v[242:243], v[242:243], v[244:245]
	s_nop 0
	v_pk_add_f32 v[238:239], v[238:239], v[242:243]
	s_nop 0
	v_add_f32_e32 v238, v238, v239
	v_fma_f32 v144, v144, v236, v238
	v_cvt_pk_bf16_f32 v58, v170, v171
	v_cvt_pk_bf16_f32 v59, v172, v173
	v_cvt_pk_bf16_f32 v60, v174, v175
	v_cvt_pk_bf16_f32 v61, v176, v177
	v_cvt_pk_bf16_f32 v54, v178, v179
	v_cvt_pk_bf16_f32 v55, v180, v181
	v_cvt_pk_bf16_f32 v56, v182, v183
	v_cvt_pk_bf16_f32 v57, v184, v185
	s_branch .LBB0_445
	.p2alignl 6, 3212836864
.Lp2v_m1:
	s_setprio 1
	v_mfma_f32_16x16x32_bf16 v[64:67], v[64:67], v[10:13], 0
	v_mfma_f32_16x16x32_bf16 v[68:71], v[68:71], v[10:13], 0
	v_mfma_f32_16x16x32_bf16 v[64:67], v[54:57], v[14:17], v[64:67]
	v_mfma_f32_16x16x32_bf16 v[72:75], v[72:75], v[10:13], 0
	v_mfma_f32_16x16x32_bf16 v[68:71], v[58:61], v[14:17], v[68:71]
	v_mfma_f32_16x16x32_bf16 v[80:83], v[80:83], v[10:13], 0
	v_mfma_f32_16x16x32_bf16 v[72:75], v[76:79], v[14:17], v[72:75]
	v_mfma_f32_16x16x32_bf16 v[80:83], v[84:87], v[14:17], v[80:83]
	s_setprio 0
	s_nop 7
	s_nop 7
	v_mov_b32_e32 v54, 0
	v_mov_b32_e32 v55, v54
	v_mov_b32_e32 v56, v54
	v_mov_b32_e32 v57, v54
	v_mov_b32_e32 v58, v54
	v_mov_b32_e32 v59, v54
	v_mov_b32_e32 v60, v54
	v_mov_b32_e32 v61, v54
	v_max3_f32 v76, v64, v65, v66
	v_max3_f32 v76, v76, v67, v68
	v_max3_f32 v76, v76, v69, v70
	v_max3_f32 v76, v76, v71, v72
	v_max3_f32 v76, v76, v73, v74
	v_max3_f32 v76, v76, v75, v80
	v_max3_f32 v76, v76, v81, v82
	v_max_f32_e32 v76, v76, v83
	v_mov_b32_e32 v77, v76
	s_nop 1
	v_permlane16_swap_b32_e32 v76, v77
	v_max_f32_e32 v76, v76, v77
	v_mov_b32_e32 v77, v76
	s_nop 1
	v_permlane32_swap_b32_e32 v76, v77
	v_max_f32_e32 v76, v76, v77
	v_fma_f32 v76, v76, s36, v188
	v_max_f32_e32 v76, s29, v76
	v_cndmask_b32_e64 v76, v148, v76, s[42:43]
	v_max_f32_e32 v77, v161, v76
	v_sub_f32_e32 v0, v161, v77
	v_exp_f32_e32 v0, v0
	v_cndmask_b32_e64 v76, v209, v77, s[42:43]
	v_mov_b32_e32 v161, v77
	v_sub_f32_e32 v78, v188, v76
	v_pk_mul_f32 v[32:33], v[32:33], v[0:1] op_sel_hi:[1,0]
	v_pk_mul_f32 v[30:31], v[30:31], v[0:1] op_sel_hi:[1,0]
	v_pk_mul_f32 v[28:29], v[28:29], v[0:1] op_sel_hi:[1,0]
	v_pk_mul_f32 v[26:27], v[26:27], v[0:1] op_sel_hi:[1,0]
	v_pk_mul_f32 v[24:25], v[24:25], v[0:1] op_sel_hi:[1,0]
	v_pk_mul_f32 v[22:23], v[22:23], v[0:1] op_sel_hi:[1,0]
	v_pk_mul_f32 v[20:21], v[20:21], v[0:1] op_sel_hi:[1,0]
	v_pk_mul_f32 v[18:19], v[18:19], v[0:1] op_sel_hi:[1,0]
	v_pk_fma_f32 v[64:65], v[64:65], s[36:37], v[78:79] op_sel_hi:[1,0,0]
	v_pk_fma_f32 v[66:67], v[66:67], s[36:37], v[78:79] op_sel_hi:[1,0,0]
	v_pk_fma_f32 v[68:69], v[68:69], s[36:37], v[78:79] op_sel_hi:[1,0,0]
	v_pk_fma_f32 v[70:71], v[70:71], s[36:37], v[78:79] op_sel_hi:[1,0,0]
	v_pk_fma_f32 v[72:73], v[72:73], s[36:37], v[78:79] op_sel_hi:[1,0,0]
	v_pk_fma_f32 v[74:75], v[74:75], s[36:37], v[78:79] op_sel_hi:[1,0,0]
	v_pk_fma_f32 v[80:81], v[80:81], s[36:37], v[78:79] op_sel_hi:[1,0,0]
	v_pk_fma_f32 v[82:83], v[82:83], s[36:37], v[78:79] op_sel_hi:[1,0,0]
	v_exp_f32_e32 v64, v64
	v_exp_f32_e32 v65, v65
	v_exp_f32_e32 v66, v66
	v_exp_f32_e32 v67, v67
	v_exp_f32_e32 v68, v68
	v_exp_f32_e32 v69, v69
	v_exp_f32_e32 v70, v70
	v_exp_f32_e32 v71, v71
	v_exp_f32_e32 v72, v72
	v_exp_f32_e32 v73, v73
	v_exp_f32_e32 v74, v74
	v_exp_f32_e32 v75, v75
	v_exp_f32_e32 v80, v80
	v_exp_f32_e32 v81, v81
	v_exp_f32_e32 v82, v82
	v_exp_f32_e32 v83, v83
	s_nop 0
	v_pk_add_f32 v[84:85], v[64:65], v[66:67]
	v_pk_add_f32 v[86:87], v[68:69], v[70:71]
	v_pk_add_f32 v[76:77], v[72:73], v[74:75]
	v_pk_add_f32 v[78:79], v[80:81], v[82:83]
	v_pk_add_f32 v[84:85], v[84:85], v[86:87]
	v_pk_add_f32 v[76:77], v[76:77], v[78:79]
	s_nop 0
	v_pk_add_f32 v[84:85], v[84:85], v[76:77]
	s_nop 0
	v_add_f32_e32 v84, v84, v85
	v_fma_f32 v145, v145, v0, v84
	v_cvt_pk_bf16_f32 v67, v66, v67
	v_cvt_pk_bf16_f32 v66, v64, v65
	v_cvt_pk_bf16_f32 v68, v68, v69
	v_cvt_pk_bf16_f32 v69, v70, v71
	v_cvt_pk_bf16_f32 v62, v72, v73
	v_cvt_pk_bf16_f32 v63, v74, v75
	v_cvt_pk_bf16_f32 v64, v80, v81
	v_cvt_pk_bf16_f32 v65, v82, v83
	s_branch .LBB0_446
	.p2alignl 6, 3212836864

.LBB0_446:
	v_add3_u32 v0, s13, v198, v199
	v_add_u32_e32 v78, v0, v200
	v_add_u32_e32 v79, v0, v201
	s_waitcnt vmcnt(0)
	ds_read_b64_tr_b16 v[70:71], v78 offset:24576
	ds_read_b64_tr_b16 v[72:73], v78 offset:26624
	ds_read_b64_tr_b16 v[74:75], v79 offset:24576
	ds_read_b64_tr_b16 v[76:77], v79 offset:26624
	v_add_u32_e32 v80, v0, v202
	v_add_u32_e32 v0, v0, v203
	s_waitcnt lgkmcnt(0)
	s_setprio 1
	v_mfma_f32_16x16x32_bf16 v[34:37], v[70:73], v[58:61], v[34:37]
	v_mfma_f32_16x16x32_bf16 v[30:33], v[70:73], v[66:69], v[30:33]
	ds_read_b64_tr_b16 v[70:71], v80 offset:24576
	ds_read_b64_tr_b16 v[72:73], v80 offset:26624
	v_mfma_f32_16x16x32_bf16 v[46:49], v[74:77], v[58:61], v[46:49]
	v_mfma_f32_16x16x32_bf16 v[26:29], v[74:77], v[66:69], v[26:29]
	ds_read_b64_tr_b16 v[74:75], v0 offset:24576
	ds_read_b64_tr_b16 v[76:77], v0 offset:26624
	s_waitcnt lgkmcnt(2)
	v_mfma_f32_16x16x32_bf16 v[42:45], v[70:73], v[58:61], v[42:45]
	v_mfma_f32_16x16x32_bf16 v[22:25], v[70:73], v[66:69], v[22:25]
	s_waitcnt lgkmcnt(0)
	v_mfma_f32_16x16x32_bf16 v[50:53], v[74:77], v[58:61], v[50:53]
	ds_read_b64_tr_b16 v[58:59], v78 offset:28672
	ds_read_b64_tr_b16 v[60:61], v78 offset:30720
	v_mfma_f32_16x16x32_bf16 v[18:21], v[74:77], v[66:69], v[18:21]
	ds_read_b64_tr_b16 v[66:67], v79 offset:28672
	ds_read_b64_tr_b16 v[68:69], v79 offset:30720
	s_waitcnt lgkmcnt(2)
	v_mfma_f32_16x16x32_bf16 v[34:37], v[58:61], v[54:57], v[34:37]
	v_mfma_f32_16x16x32_bf16 v[30:33], v[58:61], v[62:65], v[30:33]
	ds_read_b64_tr_b16 v[58:59], v80 offset:28672
	ds_read_b64_tr_b16 v[60:61], v80 offset:30720
	s_waitcnt lgkmcnt(2)
	v_mfma_f32_16x16x32_bf16 v[46:49], v[66:69], v[54:57], v[46:49]
	v_mfma_f32_16x16x32_bf16 v[26:29], v[66:69], v[62:65], v[26:29]
	ds_read_b64_tr_b16 v[66:67], v0 offset:28672
	ds_read_b64_tr_b16 v[68:69], v0 offset:30720
	s_waitcnt lgkmcnt(2)
	v_mfma_f32_16x16x32_bf16 v[42:45], v[58:61], v[54:57], v[42:45]
	v_mfma_f32_16x16x32_bf16 v[22:25], v[58:61], v[62:65], v[22:25]
	s_waitcnt lgkmcnt(0)
	v_mfma_f32_16x16x32_bf16 v[50:53], v[66:69], v[54:57], v[50:53]
	v_mfma_f32_16x16x32_bf16 v[18:21], v[66:69], v[62:65], v[18:21]
	s_setprio 0
	s_branch .Lsel_fast
	.p2alignl 6, 3212836864
.LBB0_448:
	s_xor_b64 s[6:7], s[20:21], -1
	s_add_u32 s18, s8, -1
	s_addc_u32 s19, s9, -1
	v_mov_b64_e32 v[34:35], v[58:59]
	v_mov_b64_e32 v[46:47], v[66:67]
	v_mov_b64_e32 v[42:43], v[78:79]
	v_mov_b64_e32 v[50:51], v[54:55]
	v_mov_b64_e32 v[30:31], v[62:63]
	v_mov_b64_e32 v[26:27], v[74:75]
	v_mov_b64_e32 v[22:23], v[86:87]
	v_mov_b64_e32 v[18:19], v[70:71]
	s_and_b64 s[8:9], s[18:19], s[8:9]
	v_mov_b64_e32 v[160:161], v[166:167]
	v_mov_b64_e32 v[144:145], v[168:169]
	v_mov_b64_e32 v[36:37], v[60:61]
	v_mov_b64_e32 v[48:49], v[68:69]
	v_mov_b64_e32 v[44:45], v[80:81]
	v_mov_b64_e32 v[52:53], v[56:57]
	v_mov_b64_e32 v[32:33], v[64:65]
	v_mov_b64_e32 v[28:29], v[76:77]
	v_mov_b64_e32 v[24:25], v[88:89]
	v_mov_b64_e32 v[20:21], v[72:73]
	s_mov_b32 s13, 1
	s_mov_b64 s[20:21], 0
	s_and_b64 vcc, exec, s[6:7]
	s_cbranch_vccz .LBB0_419
	s_branch .LBB0_449
	.p2alignl 6, 3212836864

.LBB0_449:
	s_add_i32 s5, s5, 2
	s_add_i32 s12, s12, -2
	s_cmp_lt_u32 s5, s0
	s_cbranch_scc0 .LBB0_350
	s_mov_b64 s[6:7], s[10:11]
	s_branch .LBB0_413
	.p2alignl 6, 3212836864
